# v17: v12 + nt (streaming) hint on the 72 GEMM-epilogue result stores (cache policy only)
# baseline (speedup 1.0000x reference)
; __device__ __forceinline__ unsigned cvt_pk_bf16(float lo, float hi) { unsigned r; asm volatile("v_cvt_pk_bf16_f32 %0, %1, %2" : "=v"(r) : "v"(lo), "v"(hi)); return r; }
;     __device__ __forceinline__ void operator()(const f32x4 (&acc)[2][2][4][2], const Unit& u, int wr, int wc, int fr, int fq) const {
;     ...
;         for (int ai = 0; ai < 2; ++ai)
; #pragma unroll
;             for (int m = 0; m < 4; ++m) {
;                 const int row = row0 + ai * HALF + m * 16;
;                 bf16_t* rowp = O + (size_t)row * 14336 + col0;
;                 f32x4 a0 = acc[ai][0][m][0], a1 = acc[ai][0][m][1], b0 = acc[ai][1][m][0], b1 = acc[ai][1][m][1];
;                 if (rot) {
;                     const int pos = row < 16384 ? (row & 2047) : (row - 16384);
;                     const f32x4* rp = (const f32x4*)(rope + ((size_t)pos * 128 + wc * 32 + 8 * fq) * 2);
;                     const f32x4 r0 = rp[0], r1 = rp[1], r2 = rp[2], r3 = rp[3];
;                     const f32x4 c0 = {r0.x, r0.z, r1.x, r1.z}, s0 = {r0.y, r0.w, r1.y, r1.w}, c1 = {r2.x, r2.z, r3.x, r3.z}, s1 = {r2.y, r2.w, r3.y, r3.w};
;                     const f32x4 na0 = a0 * c0 - b0 * s0, nb0 = a0 * s0 + b0 * c0, na1 = a1 * c1 - b1 * s1, nb1 = a1 * s1 + b1 * c1;
;                     a0 = na0 * ksc; b0 = nb0 * ksc; a1 = na1 * ksc; b1 = nb1 * ksc;
;                 }
;                 u32x4 w0, w1;
;                 w0.x = cvt_pk_bf16(a0[0], a0[1]); w0.y = cvt_pk_bf16(a0[2], a0[3]); w0.z = cvt_pk_bf16(a1[0], a1[1]); w0.w = cvt_pk_bf16(a1[2], a1[3]);
;                 w1.x = cvt_pk_bf16(b0[0], b0[1]); w1.y = cvt_pk_bf16(b0[2], b0[3]); w1.z = cvt_pk_bf16(b1[0], b1[1]); w1.w = cvt_pk_bf16(b1[2], b1[3]);
;                 *(u32x4*)(rowp) = w0; *(u32x4*)(rowp + HALF) = w1;
.LBB0_305:
	v_lshl_add_u32 v144, s68, 8, v153
	v_mov_b64_e32 v[146:147], s[8:9]
	v_ashrrev_i32_e32 v145, 31, v144
	v_mad_i64_i32 v[146:147], s[6:7], v155, s33, v[146:147]
	v_cvt_pk_bf16_f32 v126, v126, v127
	v_cvt_pk_bf16_f32 v127, v128, v129
	v_cvt_pk_bf16_f32 v128, v122, v123
	v_cvt_pk_bf16_f32 v129, v124, v125
	v_cvt_pk_bf16_f32 v118, v118, v119
	v_cvt_pk_bf16_f32 v119, v120, v121
	v_cvt_pk_bf16_f32 v120, v114, v115
	v_cndmask_b32_e64 v114, 0, 1, s[52:53]
	v_lshl_add_u64 v[146:147], v[144:145], 1, v[146:147]
	v_cmp_ne_u32_e64 s[6:7], 1, v114
	s_andn2_b64 vcc, exec, s[52:53]
	v_or_b32_e32 v122, 16, v155
	v_cvt_pk_bf16_f32 v121, v116, v117
	global_store_dwordx4 v[146:147], v[126:129], off nt
	global_store_dwordx4 v[146:147], v[118:121], off offset:256 nt
	s_cbranch_vccnz .LBB0_307
	v_cmp_gt_i32_e32 vcc, s49, v122
	v_and_b32_e32 v114, 0x7df, v122
	v_add_u32_e32 v115, 0xffffc010, v155
	v_cndmask_b32_e32 v114, v115, v114, vcc
	v_ashrrev_i32_e32 v115, 31, v114
	v_lshlrev_b64 v[114:115], 10, v[114:115]
	v_lshl_add_u64 v[114:115], v[136:137], 0, v[114:115]
	global_load_dwordx4 v[124:127], v[114:115], off offset:48
	global_load_dwordx4 v[146:149], v[114:115], off offset:32
	global_load_dwordx4 v[118:121], v[114:115], off offset:16
	global_load_dwordx4 v[156:159], v[114:115], off
	s_waitcnt vmcnt(0)
	v_mov_b32_e32 v128, v119
	v_mov_b32_e32 v129, v121
	v_mov_b32_e32 v150, v157
	v_mov_b32_e32 v151, v159
	v_mov_b32_e32 v157, v158
	v_mov_b32_e32 v119, v120
	v_pk_mul_f32 v[116:117], v[104:105], v[128:129]
	v_pk_mul_f32 v[114:115], v[102:103], v[150:151]
	v_pk_mul_f32 v[104:105], v[104:105], v[118:119]
	v_pk_mul_f32 v[102:103], v[102:103], v[156:157]
	v_pk_fma_f32 v[114:115], v[110:111], v[156:157], v[114:115] neg_lo:[0,0,1] neg_hi:[0,0,1]
	v_pk_fma_f32 v[102:103], v[110:111], v[150:151], v[102:103]
	v_pk_fma_f32 v[104:105], v[112:113], v[128:129], v[104:105]
	v_mov_b32_e32 v110, v125
	v_mov_b32_e32 v111, v127
	v_mov_b32_e32 v128, v147
	v_mov_b32_e32 v129, v149
	v_mov_b32_e32 v147, v148
	v_mov_b32_e32 v125, v126
	v_pk_fma_f32 v[116:117], v[112:113], v[118:119], v[116:117] neg_lo:[0,0,1] neg_hi:[0,0,1]
	v_pk_mul_f32 v[112:113], v[100:101], v[110:111]
	v_pk_mul_f32 v[118:119], v[98:99], v[128:129]
	v_pk_mul_f32 v[100:101], v[100:101], v[124:125]
	v_pk_mul_f32 v[98:99], v[98:99], v[146:147]
	v_pk_fma_f32 v[118:119], v[106:107], v[146:147], v[118:119] neg_lo:[0,0,1] neg_hi:[0,0,1]
	v_pk_fma_f32 v[120:121], v[108:109], v[124:125], v[112:113] neg_lo:[0,0,1] neg_hi:[0,0,1]
	v_pk_fma_f32 v[98:99], v[106:107], v[128:129], v[98:99]
	v_pk_fma_f32 v[100:101], v[108:109], v[110:111], v[100:101]
	v_mov_b32_e32 v124, v142
	v_mov_b32_e32 v125, v142
	v_pk_mul_f32 v[112:113], v[124:125], v[116:117]
	v_pk_mul_f32 v[110:111], v[142:143], v[114:115]
	v_pk_mul_f32 v[104:105], v[124:125], v[104:105]
	v_pk_mul_f32 v[102:103], v[142:143], v[102:103]
	v_pk_mul_f32 v[108:109], v[124:125], v[120:121]
	v_pk_mul_f32 v[106:107], v[142:143], v[118:119]
	v_pk_mul_f32 v[100:101], v[124:125], v[100:101]
	v_pk_mul_f32 v[98:99], v[142:143], v[98:99]
.LBB0_307:
	v_mov_b64_e32 v[114:115], s[8:9]
	v_mad_i64_i32 v[114:115], s[30:31], v122, s33, v[114:115]
	v_lshl_add_u64 v[114:115], v[144:145], 1, v[114:115]
	v_cvt_pk_bf16_f32 v110, v110, v111
	v_cvt_pk_bf16_f32 v111, v112, v113
	v_cvt_pk_bf16_f32 v112, v106, v107
	v_cvt_pk_bf16_f32 v113, v108, v109
	s_and_b64 vcc, exec, s[6:7]
	v_or_b32_e32 v106, 32, v155
	v_cvt_pk_bf16_f32 v102, v102, v103
	v_cvt_pk_bf16_f32 v103, v104, v105
	v_cvt_pk_bf16_f32 v104, v98, v99
	v_cvt_pk_bf16_f32 v105, v100, v101
	global_store_dwordx4 v[114:115], v[110:113], off nt
	global_store_dwordx4 v[114:115], v[102:105], off offset:256 nt
	s_cbranch_vccnz .LBB0_309
	v_cmp_gt_i32_e32 vcc, s49, v106
	v_and_b32_e32 v98, 0x7ef, v106
	v_add_u32_e32 v99, 0xffffc020, v155
	v_cndmask_b32_e32 v98, v99, v98, vcc
	v_ashrrev_i32_e32 v99, 31, v98
	v_lshlrev_b64 v[98:99], 10, v[98:99]
	v_lshl_add_u64 v[98:99], v[136:137], 0, v[98:99]
	global_load_dwordx4 v[108:111], v[98:99], off offset:48
	global_load_dwordx4 v[112:115], v[98:99], off offset:32
	global_load_dwordx4 v[102:105], v[98:99], off offset:16
	global_load_dwordx4 v[116:119], v[98:99], off
	s_waitcnt vmcnt(0)
	v_mov_b32_e32 v120, v103
	v_mov_b32_e32 v122, v117
	v_mov_b32_e32 v123, v119
	v_mov_b32_e32 v117, v118
	v_mov_b32_e32 v121, v105
	v_pk_mul_f32 v[98:99], v[86:87], v[122:123]
	v_mov_b32_e32 v103, v104
	v_pk_mul_f32 v[86:87], v[86:87], v[116:117]
	v_pk_mul_f32 v[100:101], v[88:89], v[120:121]
	v_pk_fma_f32 v[98:99], v[94:95], v[116:117], v[98:99] neg_lo:[0,0,1] neg_hi:[0,0,1]
	v_pk_mul_f32 v[88:89], v[88:89], v[102:103]
	v_pk_fma_f32 v[86:87], v[94:95], v[122:123], v[86:87]
	v_mov_b32_e32 v94, v109
	v_mov_b32_e32 v95, v111
	v_mov_b32_e32 v116, v113
	v_mov_b32_e32 v117, v115
	v_mov_b32_e32 v113, v114
	v_mov_b32_e32 v109, v110
	v_pk_fma_f32 v[100:101], v[96:97], v[102:103], v[100:101] neg_lo:[0,0,1] neg_hi:[0,0,1]
	v_pk_fma_f32 v[88:89], v[96:97], v[120:121], v[88:89]
	v_pk_mul_f32 v[96:97], v[84:85], v[94:95]
	v_pk_mul_f32 v[102:103], v[82:83], v[116:117]
	v_pk_mul_f32 v[84:85], v[84:85], v[108:109]
	v_pk_mul_f32 v[82:83], v[82:83], v[112:113]
	v_pk_fma_f32 v[102:103], v[90:91], v[112:113], v[102:103] neg_lo:[0,0,1] neg_hi:[0,0,1]
	v_pk_fma_f32 v[104:105], v[92:93], v[108:109], v[96:97] neg_lo:[0,0,1] neg_hi:[0,0,1]
	v_pk_fma_f32 v[82:83], v[90:91], v[116:117], v[82:83]
	v_pk_fma_f32 v[84:85], v[92:93], v[94:95], v[84:85]
	v_mov_b32_e32 v108, v142
	v_mov_b32_e32 v109, v142
	v_pk_mul_f32 v[96:97], v[108:109], v[100:101]
	v_pk_mul_f32 v[94:95], v[142:143], v[98:99]
	v_pk_mul_f32 v[88:89], v[108:109], v[88:89]
	v_pk_mul_f32 v[86:87], v[142:143], v[86:87]
	v_pk_mul_f32 v[92:93], v[108:109], v[104:105]
	v_pk_mul_f32 v[90:91], v[142:143], v[102:103]
	v_pk_mul_f32 v[84:85], v[108:109], v[84:85]
	v_pk_mul_f32 v[82:83], v[142:143], v[82:83]
; __device__ __forceinline__ unsigned cvt_pk_bf16(float lo, float hi) { unsigned r; asm volatile("v_cvt_pk_bf16_f32 %0, %1, %2" : "=v"(r) : "v"(lo), "v"(hi)); return r; }
;     __device__ __forceinline__ void operator()(const f32x4 (&acc)[2][2][4][2], const Unit& u, int wr, int wc, int fr, int fq) const {
;     ...
;         for (int ai = 0; ai < 2; ++ai)
; #pragma unroll
;             for (int m = 0; m < 4; ++m) {
;                 const int row = row0 + ai * HALF + m * 16;
;                 bf16_t* rowp = O + (size_t)row * 14336 + col0;
;                 f32x4 a0 = acc[ai][0][m][0], a1 = acc[ai][0][m][1], b0 = acc[ai][1][m][0], b1 = acc[ai][1][m][1];
;                 if (rot) {
;                     const int pos = row < 16384 ? (row & 2047) : (row - 16384);
;                     const f32x4* rp = (const f32x4*)(rope + ((size_t)pos * 128 + wc * 32 + 8 * fq) * 2);
;                     const f32x4 r0 = rp[0], r1 = rp[1], r2 = rp[2], r3 = rp[3];
;                     const f32x4 c0 = {r0.x, r0.z, r1.x, r1.z}, s0 = {r0.y, r0.w, r1.y, r1.w}, c1 = {r2.x, r2.z, r3.x, r3.z}, s1 = {r2.y, r2.w, r3.y, r3.w};
;                     const f32x4 na0 = a0 * c0 - b0 * s0, nb0 = a0 * s0 + b0 * c0, na1 = a1 * c1 - b1 * s1, nb1 = a1 * s1 + b1 * c1;
;                     a0 = na0 * ksc; b0 = nb0 * ksc; a1 = na1 * ksc; b1 = nb1 * ksc;
;                 }
;                 u32x4 w0, w1;
;                 w0.x = cvt_pk_bf16(a0[0], a0[1]); w0.y = cvt_pk_bf16(a0[2], a0[3]); w0.z = cvt_pk_bf16(a1[0], a1[1]); w0.w = cvt_pk_bf16(a1[2], a1[3]);
;                 w1.x = cvt_pk_bf16(b0[0], b0[1]); w1.y = cvt_pk_bf16(b0[2], b0[3]); w1.z = cvt_pk_bf16(b1[0], b1[1]); w1.w = cvt_pk_bf16(b1[2], b1[3]);
;                 *(u32x4*)(rowp) = w0; *(u32x4*)(rowp + HALF) = w1;
.LBB0_309:
	v_mov_b64_e32 v[98:99], s[8:9]
	v_mad_i64_i32 v[98:99], s[30:31], v106, s33, v[98:99]
	v_lshl_add_u64 v[98:99], v[144:145], 1, v[98:99]
	v_cvt_pk_bf16_f32 v94, v94, v95
	v_cvt_pk_bf16_f32 v95, v96, v97
	v_cvt_pk_bf16_f32 v96, v90, v91
	v_cvt_pk_bf16_f32 v97, v92, v93
	s_and_b64 vcc, exec, s[6:7]
	v_or_b32_e32 v90, 48, v155
	v_cvt_pk_bf16_f32 v86, v86, v87
	v_cvt_pk_bf16_f32 v87, v88, v89
	v_cvt_pk_bf16_f32 v88, v82, v83
	v_cvt_pk_bf16_f32 v89, v84, v85
	global_store_dwordx4 v[98:99], v[94:97], off nt
	global_store_dwordx4 v[98:99], v[86:89], off offset:256 nt
	s_cbranch_vccnz .LBB0_311
	v_cmp_gt_i32_e32 vcc, s49, v90
	v_and_b32_e32 v82, 0x7ff, v90
	v_add_u32_e32 v83, 0xffffc030, v155
	v_cndmask_b32_e32 v82, v83, v82, vcc
	v_ashrrev_i32_e32 v83, 31, v82
	v_lshlrev_b64 v[82:83], 10, v[82:83]
	v_lshl_add_u64 v[82:83], v[136:137], 0, v[82:83]
	global_load_dwordx4 v[92:95], v[82:83], off offset:48
	global_load_dwordx4 v[96:99], v[82:83], off offset:32
	global_load_dwordx4 v[86:89], v[82:83], off offset:16
	global_load_dwordx4 v[100:103], v[82:83], off
	s_waitcnt vmcnt(0)
	v_mov_b32_e32 v104, v87
	v_mov_b32_e32 v106, v101
	v_mov_b32_e32 v107, v103
	v_mov_b32_e32 v101, v102
	v_mov_b32_e32 v105, v89
	v_pk_mul_f32 v[82:83], v[70:71], v[106:107]
	v_mov_b32_e32 v87, v88
	v_pk_mul_f32 v[70:71], v[70:71], v[100:101]
	v_pk_mul_f32 v[84:85], v[72:73], v[104:105]
	v_pk_fma_f32 v[82:83], v[78:79], v[100:101], v[82:83] neg_lo:[0,0,1] neg_hi:[0,0,1]
	v_pk_mul_f32 v[72:73], v[72:73], v[86:87]
	v_pk_fma_f32 v[70:71], v[78:79], v[106:107], v[70:71]
	v_mov_b32_e32 v78, v93
	v_mov_b32_e32 v79, v95
	v_mov_b32_e32 v100, v97
	v_mov_b32_e32 v101, v99
	v_mov_b32_e32 v97, v98
	v_mov_b32_e32 v93, v94
	v_pk_fma_f32 v[84:85], v[80:81], v[86:87], v[84:85] neg_lo:[0,0,1] neg_hi:[0,0,1]
	v_pk_fma_f32 v[72:73], v[80:81], v[104:105], v[72:73]
	v_pk_mul_f32 v[80:81], v[68:69], v[78:79]
	v_pk_mul_f32 v[86:87], v[66:67], v[100:101]
	v_pk_mul_f32 v[68:69], v[68:69], v[92:93]
	v_pk_mul_f32 v[66:67], v[66:67], v[96:97]
	v_pk_fma_f32 v[86:87], v[74:75], v[96:97], v[86:87] neg_lo:[0,0,1] neg_hi:[0,0,1]
	v_pk_fma_f32 v[88:89], v[76:77], v[92:93], v[80:81] neg_lo:[0,0,1] neg_hi:[0,0,1]
	v_pk_fma_f32 v[66:67], v[74:75], v[100:101], v[66:67]
	v_pk_fma_f32 v[68:69], v[76:77], v[78:79], v[68:69]
	v_mov_b32_e32 v92, v142
	v_mov_b32_e32 v93, v142
	v_pk_mul_f32 v[80:81], v[92:93], v[84:85]
	v_pk_mul_f32 v[78:79], v[142:143], v[82:83]
	v_pk_mul_f32 v[72:73], v[92:93], v[72:73]
	v_pk_mul_f32 v[70:71], v[142:143], v[70:71]
	v_pk_mul_f32 v[76:77], v[92:93], v[88:89]
	v_pk_mul_f32 v[74:75], v[142:143], v[86:87]
	v_pk_mul_f32 v[68:69], v[92:93], v[68:69]
	v_pk_mul_f32 v[66:67], v[142:143], v[66:67]
.LBB0_311:
	v_mov_b64_e32 v[82:83], s[8:9]
	v_mad_i64_i32 v[82:83], s[30:31], v90, s33, v[82:83]
	v_lshl_add_u64 v[82:83], v[144:145], 1, v[82:83]
	v_cvt_pk_bf16_f32 v78, v78, v79
	v_cvt_pk_bf16_f32 v79, v80, v81
	v_cvt_pk_bf16_f32 v80, v74, v75
	v_cvt_pk_bf16_f32 v81, v76, v77
	s_and_b64 vcc, exec, s[6:7]
	v_add_u32_e32 v74, 0x80, v155
	v_cvt_pk_bf16_f32 v70, v70, v71
	v_cvt_pk_bf16_f32 v71, v72, v73
	v_cvt_pk_bf16_f32 v72, v66, v67
	v_cvt_pk_bf16_f32 v73, v68, v69
	global_store_dwordx4 v[82:83], v[78:81], off nt
	global_store_dwordx4 v[82:83], v[70:73], off offset:256 nt
	s_cbranch_vccnz .LBB0_313
	s_movk_i32 s30, 0x3f80
	v_cmp_gt_i32_e32 vcc, s30, v155
	v_and_b32_e32 v66, 0x7cf, v74
	v_add_u32_e32 v67, 0xffffc080, v155
	v_cndmask_b32_e32 v66, v67, v66, vcc
	v_ashrrev_i32_e32 v67, 31, v66
	v_lshlrev_b64 v[66:67], 10, v[66:67]
	v_lshl_add_u64 v[66:67], v[136:137], 0, v[66:67]
	global_load_dwordx4 v[76:79], v[66:67], off offset:48
	global_load_dwordx4 v[80:83], v[66:67], off offset:32
	global_load_dwordx4 v[70:73], v[66:67], off offset:16
	global_load_dwordx4 v[84:87], v[66:67], off
	s_waitcnt vmcnt(0)
	v_mov_b32_e32 v88, v71
	v_mov_b32_e32 v90, v85
	v_mov_b32_e32 v91, v87
	v_mov_b32_e32 v85, v86
	v_mov_b32_e32 v89, v73
	v_pk_mul_f32 v[66:67], v[54:55], v[90:91]
	v_mov_b32_e32 v71, v72
	v_pk_mul_f32 v[54:55], v[54:55], v[84:85]
	v_pk_mul_f32 v[68:69], v[56:57], v[88:89]
	v_pk_fma_f32 v[66:67], v[62:63], v[84:85], v[66:67] neg_lo:[0,0,1] neg_hi:[0,0,1]
	v_pk_mul_f32 v[56:57], v[56:57], v[70:71]
	v_pk_fma_f32 v[54:55], v[62:63], v[90:91], v[54:55]
	v_mov_b32_e32 v62, v77
	v_mov_b32_e32 v63, v79
	v_mov_b32_e32 v84, v81
	v_mov_b32_e32 v85, v83
	v_mov_b32_e32 v81, v82
	v_mov_b32_e32 v77, v78
	v_pk_fma_f32 v[68:69], v[64:65], v[70:71], v[68:69] neg_lo:[0,0,1] neg_hi:[0,0,1]
	v_pk_fma_f32 v[56:57], v[64:65], v[88:89], v[56:57]
	v_pk_mul_f32 v[64:65], v[52:53], v[62:63]
	v_pk_mul_f32 v[70:71], v[50:51], v[84:85]
	v_pk_mul_f32 v[52:53], v[52:53], v[76:77]
	v_pk_mul_f32 v[50:51], v[50:51], v[80:81]
	v_pk_fma_f32 v[70:71], v[58:59], v[80:81], v[70:71] neg_lo:[0,0,1] neg_hi:[0,0,1]
	v_pk_fma_f32 v[72:73], v[60:61], v[76:77], v[64:65] neg_lo:[0,0,1] neg_hi:[0,0,1]
	v_pk_fma_f32 v[50:51], v[58:59], v[84:85], v[50:51]
	v_pk_fma_f32 v[52:53], v[60:61], v[62:63], v[52:53]
	v_mov_b32_e32 v76, v142
	v_mov_b32_e32 v77, v142
	v_pk_mul_f32 v[64:65], v[76:77], v[68:69]
	v_pk_mul_f32 v[62:63], v[142:143], v[66:67]
	v_pk_mul_f32 v[56:57], v[76:77], v[56:57]
	v_pk_mul_f32 v[54:55], v[142:143], v[54:55]
	v_pk_mul_f32 v[60:61], v[76:77], v[72:73]
	v_pk_mul_f32 v[58:59], v[142:143], v[70:71]
	v_pk_mul_f32 v[52:53], v[76:77], v[52:53]
	v_pk_mul_f32 v[50:51], v[142:143], v[50:51]
; __device__ __forceinline__ unsigned cvt_pk_bf16(float lo, float hi) { unsigned r; asm volatile("v_cvt_pk_bf16_f32 %0, %1, %2" : "=v"(r) : "v"(lo), "v"(hi)); return r; }
;     __device__ __forceinline__ void operator()(const f32x4 (&acc)[2][2][4][2], const Unit& u, int wr, int wc, int fr, int fq) const {
;     ...
;         for (int ai = 0; ai < 2; ++ai)
; #pragma unroll
;             for (int m = 0; m < 4; ++m) {
;                 const int row = row0 + ai * HALF + m * 16;
;                 bf16_t* rowp = O + (size_t)row * 14336 + col0;
;                 f32x4 a0 = acc[ai][0][m][0], a1 = acc[ai][0][m][1], b0 = acc[ai][1][m][0], b1 = acc[ai][1][m][1];
;                 if (rot) {
;                     const int pos = row < 16384 ? (row & 2047) : (row - 16384);
;                     const f32x4* rp = (const f32x4*)(rope + ((size_t)pos * 128 + wc * 32 + 8 * fq) * 2);
;                     const f32x4 r0 = rp[0], r1 = rp[1], r2 = rp[2], r3 = rp[3];
;                     const f32x4 c0 = {r0.x, r0.z, r1.x, r1.z}, s0 = {r0.y, r0.w, r1.y, r1.w}, c1 = {r2.x, r2.z, r3.x, r3.z}, s1 = {r2.y, r2.w, r3.y, r3.w};
;                     const f32x4 na0 = a0 * c0 - b0 * s0, nb0 = a0 * s0 + b0 * c0, na1 = a1 * c1 - b1 * s1, nb1 = a1 * s1 + b1 * c1;
;                     a0 = na0 * ksc; b0 = nb0 * ksc; a1 = na1 * ksc; b1 = nb1 * ksc;
;                 }
;                 u32x4 w0, w1;
;                 w0.x = cvt_pk_bf16(a0[0], a0[1]); w0.y = cvt_pk_bf16(a0[2], a0[3]); w0.z = cvt_pk_bf16(a1[0], a1[1]); w0.w = cvt_pk_bf16(a1[2], a1[3]);
;                 w1.x = cvt_pk_bf16(b0[0], b0[1]); w1.y = cvt_pk_bf16(b0[2], b0[3]); w1.z = cvt_pk_bf16(b1[0], b1[1]); w1.w = cvt_pk_bf16(b1[2], b1[3]);
;                 *(u32x4*)(rowp) = w0; *(u32x4*)(rowp + HALF) = w1;
.LBB0_313:
	v_mov_b64_e32 v[66:67], s[8:9]
	v_mad_i64_i32 v[66:67], s[30:31], v74, s33, v[66:67]
	v_lshl_add_u64 v[66:67], v[144:145], 1, v[66:67]
	v_cvt_pk_bf16_f32 v62, v62, v63
	v_cvt_pk_bf16_f32 v63, v64, v65
	v_cvt_pk_bf16_f32 v64, v58, v59
	v_cvt_pk_bf16_f32 v65, v60, v61
	s_and_b64 vcc, exec, s[6:7]
	v_add_u32_e32 v58, 0x90, v155
	v_cvt_pk_bf16_f32 v54, v54, v55
	v_cvt_pk_bf16_f32 v55, v56, v57
	v_cvt_pk_bf16_f32 v56, v50, v51
	v_cvt_pk_bf16_f32 v57, v52, v53
	global_store_dwordx4 v[66:67], v[62:65], off nt
	global_store_dwordx4 v[66:67], v[54:57], off offset:256 nt
	s_cbranch_vccnz .LBB0_315
	s_movk_i32 s30, 0x3f70
	v_cmp_gt_i32_e32 vcc, s30, v155
	v_and_b32_e32 v50, 0x7df, v58
	v_add_u32_e32 v51, 0xffffc090, v155
	v_cndmask_b32_e32 v50, v51, v50, vcc
	v_ashrrev_i32_e32 v51, 31, v50
	v_lshlrev_b64 v[50:51], 10, v[50:51]
	v_lshl_add_u64 v[50:51], v[136:137], 0, v[50:51]
	global_load_dwordx4 v[60:63], v[50:51], off offset:48
	global_load_dwordx4 v[64:67], v[50:51], off offset:32
	global_load_dwordx4 v[54:57], v[50:51], off offset:16
	global_load_dwordx4 v[68:71], v[50:51], off
	s_waitcnt vmcnt(0)
	v_mov_b32_e32 v72, v55
	v_mov_b32_e32 v74, v69
	v_mov_b32_e32 v75, v71
	v_mov_b32_e32 v69, v70
	v_mov_b32_e32 v73, v57
	v_pk_mul_f32 v[50:51], v[38:39], v[74:75]
	v_mov_b32_e32 v55, v56
	v_pk_mul_f32 v[38:39], v[38:39], v[68:69]
	v_pk_mul_f32 v[52:53], v[40:41], v[72:73]
	v_pk_fma_f32 v[50:51], v[46:47], v[68:69], v[50:51] neg_lo:[0,0,1] neg_hi:[0,0,1]
	v_pk_mul_f32 v[40:41], v[40:41], v[54:55]
	v_pk_fma_f32 v[38:39], v[46:47], v[74:75], v[38:39]
	v_mov_b32_e32 v46, v61
	v_mov_b32_e32 v47, v63
	v_mov_b32_e32 v68, v65
	v_mov_b32_e32 v69, v67
	v_mov_b32_e32 v65, v66
	v_mov_b32_e32 v61, v62
	v_pk_fma_f32 v[52:53], v[48:49], v[54:55], v[52:53] neg_lo:[0,0,1] neg_hi:[0,0,1]
	v_pk_fma_f32 v[40:41], v[48:49], v[72:73], v[40:41]
	v_pk_mul_f32 v[48:49], v[36:37], v[46:47]
	v_pk_mul_f32 v[54:55], v[34:35], v[68:69]
	v_pk_mul_f32 v[36:37], v[36:37], v[60:61]
	v_pk_mul_f32 v[34:35], v[34:35], v[64:65]
	v_pk_fma_f32 v[54:55], v[42:43], v[64:65], v[54:55] neg_lo:[0,0,1] neg_hi:[0,0,1]
	v_pk_fma_f32 v[56:57], v[44:45], v[60:61], v[48:49] neg_lo:[0,0,1] neg_hi:[0,0,1]
	v_pk_fma_f32 v[34:35], v[42:43], v[68:69], v[34:35]
	v_pk_fma_f32 v[36:37], v[44:45], v[46:47], v[36:37]
	v_mov_b32_e32 v60, v142
	v_mov_b32_e32 v61, v142
	v_pk_mul_f32 v[48:49], v[60:61], v[52:53]
	v_pk_mul_f32 v[46:47], v[142:143], v[50:51]
	v_pk_mul_f32 v[40:41], v[60:61], v[40:41]
	v_pk_mul_f32 v[38:39], v[142:143], v[38:39]
	v_pk_mul_f32 v[44:45], v[60:61], v[56:57]
	v_pk_mul_f32 v[42:43], v[142:143], v[54:55]
	v_pk_mul_f32 v[36:37], v[60:61], v[36:37]
	v_pk_mul_f32 v[34:35], v[142:143], v[34:35]
.LBB0_315:
	v_mov_b64_e32 v[50:51], s[8:9]
	v_mad_i64_i32 v[50:51], s[30:31], v58, s33, v[50:51]
	v_lshl_add_u64 v[50:51], v[144:145], 1, v[50:51]
	v_cvt_pk_bf16_f32 v46, v46, v47
	v_cvt_pk_bf16_f32 v47, v48, v49
	v_cvt_pk_bf16_f32 v48, v42, v43
	v_cvt_pk_bf16_f32 v49, v44, v45
	s_and_b64 vcc, exec, s[6:7]
	v_add_u32_e32 v42, 0xa0, v155
	v_cvt_pk_bf16_f32 v38, v38, v39
	v_cvt_pk_bf16_f32 v39, v40, v41
	v_cvt_pk_bf16_f32 v40, v34, v35
	v_cvt_pk_bf16_f32 v41, v36, v37
	global_store_dwordx4 v[50:51], v[46:49], off nt
	global_store_dwordx4 v[50:51], v[38:41], off offset:256 nt
	s_cbranch_vccnz .LBB0_317
	s_movk_i32 s30, 0x3f60
	v_cmp_gt_i32_e32 vcc, s30, v155
	v_and_b32_e32 v34, 0x7ef, v42
	v_add_u32_e32 v35, 0xffffc0a0, v155
	v_cndmask_b32_e32 v34, v35, v34, vcc
	v_ashrrev_i32_e32 v35, 31, v34
	v_lshlrev_b64 v[34:35], 10, v[34:35]
	v_lshl_add_u64 v[34:35], v[136:137], 0, v[34:35]
	global_load_dwordx4 v[44:47], v[34:35], off offset:48
	global_load_dwordx4 v[48:51], v[34:35], off offset:32
	global_load_dwordx4 v[38:41], v[34:35], off offset:16
	global_load_dwordx4 v[52:55], v[34:35], off
	s_waitcnt vmcnt(0)
	v_mov_b32_e32 v56, v39
	v_mov_b32_e32 v58, v53
	v_mov_b32_e32 v59, v55
	v_mov_b32_e32 v53, v54
	v_mov_b32_e32 v57, v41
	v_pk_mul_f32 v[34:35], v[22:23], v[58:59]
	v_mov_b32_e32 v39, v40
	v_pk_mul_f32 v[22:23], v[22:23], v[52:53]
	v_pk_mul_f32 v[36:37], v[24:25], v[56:57]
	v_pk_fma_f32 v[34:35], v[30:31], v[52:53], v[34:35] neg_lo:[0,0,1] neg_hi:[0,0,1]
	v_pk_mul_f32 v[24:25], v[24:25], v[38:39]
	v_pk_fma_f32 v[22:23], v[30:31], v[58:59], v[22:23]
	v_mov_b32_e32 v30, v45
	v_mov_b32_e32 v31, v47
	v_mov_b32_e32 v52, v49
	v_mov_b32_e32 v53, v51
	v_mov_b32_e32 v49, v50
	v_mov_b32_e32 v45, v46
	v_pk_fma_f32 v[36:37], v[32:33], v[38:39], v[36:37] neg_lo:[0,0,1] neg_hi:[0,0,1]
	v_pk_fma_f32 v[24:25], v[32:33], v[56:57], v[24:25]
	v_pk_mul_f32 v[32:33], v[20:21], v[30:31]
	v_pk_mul_f32 v[38:39], v[18:19], v[52:53]
	v_pk_mul_f32 v[20:21], v[20:21], v[44:45]
	v_pk_mul_f32 v[18:19], v[18:19], v[48:49]
	v_pk_fma_f32 v[38:39], v[26:27], v[48:49], v[38:39] neg_lo:[0,0,1] neg_hi:[0,0,1]
	v_pk_fma_f32 v[40:41], v[28:29], v[44:45], v[32:33] neg_lo:[0,0,1] neg_hi:[0,0,1]
	v_pk_fma_f32 v[18:19], v[26:27], v[52:53], v[18:19]
	v_pk_fma_f32 v[20:21], v[28:29], v[30:31], v[20:21]
	v_mov_b32_e32 v44, v142
	v_mov_b32_e32 v45, v142
	v_pk_mul_f32 v[32:33], v[44:45], v[36:37]
	v_pk_mul_f32 v[30:31], v[142:143], v[34:35]
	v_pk_mul_f32 v[24:25], v[44:45], v[24:25]
	v_pk_mul_f32 v[22:23], v[142:143], v[22:23]
	v_pk_mul_f32 v[28:29], v[44:45], v[40:41]
	v_pk_mul_f32 v[26:27], v[142:143], v[38:39]
	v_pk_mul_f32 v[20:21], v[44:45], v[20:21]
	v_pk_mul_f32 v[18:19], v[142:143], v[18:19]
; __device__ __forceinline__ unsigned cvt_pk_bf16(float lo, float hi) { unsigned r; asm volatile("v_cvt_pk_bf16_f32 %0, %1, %2" : "=v"(r) : "v"(lo), "v"(hi)); return r; }
; #define PG8_BAR __builtin_amdgcn_s_barrier()
; template <class Epi, class Sched, bool ALIGN_EPI = false, bool SP2 = false, bool I8 = false, bool F16 = false>
; __device__ __forceinline__ void gemm_phase(PG8_LAS unsigned char* lds, const Gemm g, const Sched& S, const Epi& E) {
;     ...
;         cur = nxt; cA = nA; cB = nB; ++ui;
;         if constexpr (ALIGN_EPI) { if (wr == 1) PG8_BAR; }
;     __device__ __forceinline__ void operator()(const f32x4 (&acc)[2][2][4][2], const Unit& u, int wr, int wc, int fr, int fq) const {
;     ...
;         for (int ai = 0; ai < 2; ++ai)
; #pragma unroll
;             for (int m = 0; m < 4; ++m) {
;                 const int row = row0 + ai * HALF + m * 16;
;                 bf16_t* rowp = O + (size_t)row * 14336 + col0;
;                 f32x4 a0 = acc[ai][0][m][0], a1 = acc[ai][0][m][1], b0 = acc[ai][1][m][0], b1 = acc[ai][1][m][1];
;                 if (rot) {
;                     const int pos = row < 16384 ? (row & 2047) : (row - 16384);
;                     const f32x4* rp = (const f32x4*)(rope + ((size_t)pos * 128 + wc * 32 + 8 * fq) * 2);
;                     const f32x4 r0 = rp[0], r1 = rp[1], r2 = rp[2], r3 = rp[3];
;                     const f32x4 c0 = {r0.x, r0.z, r1.x, r1.z}, s0 = {r0.y, r0.w, r1.y, r1.w}, c1 = {r2.x, r2.z, r3.x, r3.z}, s1 = {r2.y, r2.w, r3.y, r3.w};
;                     const f32x4 na0 = a0 * c0 - b0 * s0, nb0 = a0 * s0 + b0 * c0, na1 = a1 * c1 - b1 * s1, nb1 = a1 * s1 + b1 * c1;
;                     a0 = na0 * ksc; b0 = nb0 * ksc; a1 = na1 * ksc; b1 = nb1 * ksc;
;                 }
;                 u32x4 w0, w1;
;                 w0.x = cvt_pk_bf16(a0[0], a0[1]); w0.y = cvt_pk_bf16(a0[2], a0[3]); w0.z = cvt_pk_bf16(a1[0], a1[1]); w0.w = cvt_pk_bf16(a1[2], a1[3]);
;                 w1.x = cvt_pk_bf16(b0[0], b0[1]); w1.y = cvt_pk_bf16(b0[2], b0[3]); w1.z = cvt_pk_bf16(b1[0], b1[1]); w1.w = cvt_pk_bf16(b1[2], b1[3]);
;                 *(u32x4*)(rowp) = w0; *(u32x4*)(rowp + HALF) = w1;
.LBB0_317:
	v_mov_b64_e32 v[34:35], s[8:9]
	v_mad_i64_i32 v[34:35], s[30:31], v42, s33, v[34:35]
	v_lshl_add_u64 v[34:35], v[144:145], 1, v[34:35]
	v_cvt_pk_bf16_f32 v30, v30, v31
	v_cvt_pk_bf16_f32 v31, v32, v33
	v_cvt_pk_bf16_f32 v32, v26, v27
	v_cvt_pk_bf16_f32 v33, v28, v29
	s_and_b64 vcc, exec, s[6:7]
	v_add_u32_e32 v26, 0xb0, v155
	v_cvt_pk_bf16_f32 v22, v22, v23
	v_cvt_pk_bf16_f32 v23, v24, v25
	v_cvt_pk_bf16_f32 v24, v18, v19
	v_cvt_pk_bf16_f32 v25, v20, v21
	global_store_dwordx4 v[34:35], v[30:33], off nt
	global_store_dwordx4 v[34:35], v[22:25], off offset:256 nt
	s_cbranch_vccnz .LBB0_319
	s_movk_i32 s6, 0x3f50
	v_cmp_gt_i32_e32 vcc, s6, v155
	v_and_b32_e32 v18, 0x7ff, v26
	v_add_u32_e32 v19, 0xffffc0b0, v155
	v_cndmask_b32_e32 v18, v19, v18, vcc
	v_ashrrev_i32_e32 v19, 31, v18
	v_lshlrev_b64 v[18:19], 10, v[18:19]
	v_lshl_add_u64 v[18:19], v[136:137], 0, v[18:19]
	global_load_dwordx4 v[28:31], v[18:19], off offset:48
	global_load_dwordx4 v[32:35], v[18:19], off offset:32
	global_load_dwordx4 v[22:25], v[18:19], off offset:16
	global_load_dwordx4 v[36:39], v[18:19], off
	s_waitcnt vmcnt(0)
	v_mov_b32_e32 v40, v23
	v_mov_b32_e32 v42, v37
	v_mov_b32_e32 v43, v39
	v_mov_b32_e32 v37, v38
	v_mov_b32_e32 v41, v25
	v_pk_mul_f32 v[18:19], v[6:7], v[42:43]
	v_mov_b32_e32 v23, v24
	v_pk_mul_f32 v[6:7], v[6:7], v[36:37]
	v_pk_mul_f32 v[20:21], v[8:9], v[40:41]
	v_pk_fma_f32 v[18:19], v[14:15], v[36:37], v[18:19] neg_lo:[0,0,1] neg_hi:[0,0,1]
	v_pk_mul_f32 v[8:9], v[8:9], v[22:23]
	v_pk_fma_f32 v[6:7], v[14:15], v[42:43], v[6:7]
	v_mov_b32_e32 v14, v29
	v_mov_b32_e32 v15, v31
	v_mov_b32_e32 v36, v33
	v_mov_b32_e32 v37, v35
	v_mov_b32_e32 v33, v34
	v_mov_b32_e32 v29, v30
	v_pk_fma_f32 v[20:21], v[16:17], v[22:23], v[20:21] neg_lo:[0,0,1] neg_hi:[0,0,1]
	v_pk_fma_f32 v[8:9], v[16:17], v[40:41], v[8:9]
	v_pk_mul_f32 v[16:17], v[4:5], v[14:15]
	v_pk_mul_f32 v[22:23], v[2:3], v[36:37]
	v_pk_mul_f32 v[4:5], v[4:5], v[28:29]
	v_pk_mul_f32 v[2:3], v[2:3], v[32:33]
	v_pk_fma_f32 v[22:23], v[10:11], v[32:33], v[22:23] neg_lo:[0,0,1] neg_hi:[0,0,1]
	v_pk_fma_f32 v[24:25], v[12:13], v[28:29], v[16:17] neg_lo:[0,0,1] neg_hi:[0,0,1]
	v_pk_fma_f32 v[2:3], v[10:11], v[36:37], v[2:3]
	v_pk_fma_f32 v[4:5], v[12:13], v[14:15], v[4:5]
	v_mov_b32_e32 v28, v142
	v_mov_b32_e32 v29, v142
	v_pk_mul_f32 v[16:17], v[28:29], v[20:21]
	v_pk_mul_f32 v[14:15], v[142:143], v[18:19]
	v_pk_mul_f32 v[8:9], v[28:29], v[8:9]
	v_pk_mul_f32 v[6:7], v[142:143], v[6:7]
	v_pk_mul_f32 v[12:13], v[28:29], v[24:25]
	v_pk_mul_f32 v[10:11], v[142:143], v[22:23]
	v_pk_mul_f32 v[4:5], v[28:29], v[4:5]
	v_pk_mul_f32 v[2:3], v[142:143], v[2:3]
.LBB0_319:
	v_mov_b64_e32 v[18:19], s[8:9]
	v_mad_i64_i32 v[18:19], s[6:7], v26, s33, v[18:19]
	v_lshl_add_u64 v[18:19], v[144:145], 1, v[18:19]
	v_cvt_pk_bf16_f32 v14, v14, v15
	v_cvt_pk_bf16_f32 v15, v16, v17
	v_cvt_pk_bf16_f32 v16, v10, v11
	v_cvt_pk_bf16_f32 v17, v12, v13
	s_andn2_b64 vcc, exec, s[4:5]
	s_mov_b64 s[4:5], -1
	v_cvt_pk_bf16_f32 v6, v6, v7
	v_cvt_pk_bf16_f32 v7, v8, v9
	v_cvt_pk_bf16_f32 v8, v2, v3
	v_cvt_pk_bf16_f32 v9, v4, v5
	global_store_dwordx4 v[18:19], v[14:17], off nt
	global_store_dwordx4 v[18:19], v[6:9], off offset:256 nt
	s_cbranch_vccnz .LBB0_296
	s_andn2_b64 vcc, exec, s[10:11]
	s_cbranch_vccnz .LBB0_295
	s_barrier
	s_branch .LBB0_295

; __device__ __forceinline__ u32x4 pk8(const f32x4 a, const f32x4 b) { u32x4 w; w.x = cvt_pk_bf16(a[0], a[1]); w.y = cvt_pk_bf16(a[2], a[3]); w.z = cvt_pk_bf16(b[0], b[1]); w.w = cvt_pk_bf16(b[2], b[3]); return w; }
;     __device__ __forceinline__ void operator()(const i32x4 (&acc)[2][2][4][2], const Unit& u, int wr, int wc, int fr, int fq) const {
;     ...
;             for (int m = 0; m < 4; ++m) {
;                 const int row = row0 + ai * HALF + m * 16;
;                 const float rf = rowinv[row];
;                 bf16_t* rowp = O + (size_t)row * 14336 + col0;
;                 f32x4 q[2][2];
; #pragma unroll
;                 for (int bj = 0; bj < 2; ++bj)
; #pragma unroll
;                     for (int n = 0; n < 2; ++n) { const i32x4 a = acc[ai][bj][m][n]; f32x4 t; t.x = (float)a.x; t.y = (float)a.y; t.z = (float)a.z; t.w = (float)a.w; q[bj][n] = t * rf * cs[bj][n]; }
;                 f32x4 a0 = q[0][0], a1 = q[0][1], b0 = q[1][0], b1 = q[1][1];
;                 if (rot) {
;                     const int pos = row < 16384 ? (row & 2047) : (row - 16384);
;                     const f32x4* rp = (const f32x4*)(rope + ((size_t)pos * 128 + wc * 32 + 8 * fq) * 2);
;                     const f32x4 r0 = rp[0], r1 = rp[1], r2 = rp[2], r3 = rp[3];
;                     const f32x4 c0 = {r0.x, r0.z, r1.x, r1.z}, s0 = {r0.y, r0.w, r1.y, r1.w}, c1 = {r2.x, r2.z, r3.x, r3.z}, s1 = {r2.y, r2.w, r3.y, r3.w};
;                     const f32x4 na0 = a0 * c0 - b0 * s0, nb0 = a0 * s0 + b0 * c0, na1 = a1 * c1 - b1 * s1, nb1 = a1 * s1 + b1 * c1;
;                     a0 = na0 * ksc; b0 = nb0 * ksc; a1 = na1 * ksc; b1 = nb1 * ksc;
;                 }
;                 *(u32x4*)(rowp) = pk8(a0, a1); *(u32x4*)(rowp + HALF) = pk8(b0, b1);
.LBB0_337:
	v_mov_b64_e32 v[154:155], s[8:9]
	v_mad_i64_i32 v[154:155], s[6:7], v144, s33, v[154:155]
	v_lshl_add_u64 v[154:155], v[142:143], 1, v[154:155]
	v_cvt_pk_bf16_f32 v162, v172, v173
	v_cvt_pk_bf16_f32 v163, v170, v171
	v_cvt_pk_bf16_f32 v164, v168, v169
	v_cvt_pk_bf16_f32 v165, v166, v167
	global_store_dwordx4 v[154:155], v[162:165], off nt
	v_cvt_pk_bf16_f32 v150, v150, v151
	v_cvt_pk_bf16_f32 v151, v156, v157
	v_cvt_pk_bf16_f32 v152, v152, v153
	v_cvt_pk_bf16_f32 v153, v160, v161
	global_store_dwordx4 v[154:155], v[150:153], off offset:256 nt
	v_cvt_f32_i32_e32 v113, v113
	v_cvt_f32_i32_e32 v112, v112
	v_or_b32_e32 v150, 16, v144
	v_ashrrev_i32_e32 v151, 31, v150
	v_lshl_add_u64 v[152:153], v[150:151], 2, s[14:15]
	global_load_dword v152, v[152:153], off
	v_cvt_f32_i32_e32 v111, v111
	v_cvt_f32_i32_e32 v110, v110
	v_cvt_f32_i32_e32 v109, v109
	v_cvt_f32_i32_e32 v108, v108
	v_cvt_f32_i32_e32 v107, v107
	v_cvt_f32_i32_e32 v106, v106
	v_cvt_f32_i32_e32 v105, v105
	v_cvt_f32_i32_e32 v104, v104
	v_cvt_f32_i32_e32 v103, v103
	v_cvt_f32_i32_e32 v102, v102
	v_cvt_f32_i32_e32 v101, v101
	v_cvt_f32_i32_e32 v100, v100
	v_cvt_f32_i32_e32 v99, v99
	v_cvt_f32_i32_e32 v98, v98
	v_cndmask_b32_e64 v145, 0, 1, s[52:53]
	v_cmp_ne_u32_e64 s[6:7], 1, v145
	s_andn2_b64 vcc, exec, s[52:53]
	s_waitcnt vmcnt(0)
	v_pk_mul_f32 v[110:111], v[152:153], v[110:111] op_sel_hi:[0,1]
	v_pk_mul_f32 v[112:113], v[152:153], v[112:113] op_sel_hi:[0,1]
	v_pk_mul_f32 v[106:107], v[152:153], v[106:107] op_sel_hi:[0,1]
	v_pk_mul_f32 v[108:109], v[152:153], v[108:109] op_sel_hi:[0,1]
	v_pk_mul_f32 v[102:103], v[152:153], v[102:103] op_sel_hi:[0,1]
	v_pk_mul_f32 v[104:105], v[152:153], v[104:105] op_sel_hi:[0,1]
	v_pk_mul_f32 v[160:161], v[152:153], v[98:99] op_sel_hi:[0,1]
	v_pk_mul_f32 v[100:101], v[152:153], v[100:101] op_sel_hi:[0,1]
	v_pk_mul_f32 v[154:155], v[122:123], v[112:113]
	v_pk_mul_f32 v[158:159], v[148:149], v[110:111]
	v_pk_mul_f32 v[152:153], v[120:121], v[108:109]
	v_pk_mul_f32 v[156:157], v[128:129], v[106:107]
	v_pk_mul_f32 v[104:105], v[118:119], v[104:105]
	v_pk_mul_f32 v[98:99], v[126:127], v[102:103]
	v_pk_mul_f32 v[108:109], v[116:117], v[100:101]
	v_pk_mul_f32 v[100:101], v[124:125], v[160:161]
	s_cbranch_vccnz .LBB0_339
	v_cmp_gt_i32_e32 vcc, s49, v150
	v_and_b32_e32 v102, 0x7df, v150
	v_add_u32_e32 v103, 0xffffc010, v144
	v_cndmask_b32_e32 v102, v103, v102, vcc
	v_ashrrev_i32_e32 v103, 31, v102
	v_lshlrev_b64 v[102:103], 10, v[102:103]
	v_lshl_add_u64 v[102:103], v[136:137], 0, v[102:103]
	global_load_dwordx4 v[160:163], v[102:103], off offset:48
	global_load_dwordx4 v[164:167], v[102:103], off offset:32
	global_load_dwordx4 v[168:171], v[102:103], off offset:16
	global_load_dwordx4 v[178:181], v[102:103], off
	s_waitcnt vmcnt(1)
	v_mov_b32_e32 v106, v169
	v_mov_b32_e32 v107, v171
	s_waitcnt vmcnt(0)
	v_mov_b32_e32 v112, v179
	v_mov_b32_e32 v113, v181
	v_mov_b32_e32 v179, v180
	v_mov_b32_e32 v169, v170
	v_pk_mul_f32 v[110:111], v[104:105], v[106:107]
	v_pk_mul_f32 v[102:103], v[98:99], v[112:113]
	v_pk_mul_f32 v[104:105], v[104:105], v[168:169]
	v_pk_mul_f32 v[98:99], v[98:99], v[178:179]
	v_pk_fma_f32 v[102:103], v[158:159], v[178:179], v[102:103] neg_lo:[0,0,1] neg_hi:[0,0,1]
	v_pk_fma_f32 v[110:111], v[154:155], v[168:169], v[110:111] neg_lo:[0,0,1] neg_hi:[0,0,1]
	v_pk_fma_f32 v[98:99], v[158:159], v[112:113], v[98:99]
	v_pk_fma_f32 v[104:105], v[154:155], v[106:107], v[104:105]
	v_mov_b32_e32 v154, v161
	v_mov_b32_e32 v155, v163
	v_mov_b32_e32 v158, v165
	v_mov_b32_e32 v159, v167
	v_mov_b32_e32 v165, v166
	v_mov_b32_e32 v161, v162
	v_pk_mul_f32 v[112:113], v[108:109], v[154:155]
	v_pk_mul_f32 v[106:107], v[100:101], v[158:159]
	v_pk_mul_f32 v[108:109], v[108:109], v[160:161]
	v_pk_mul_f32 v[100:101], v[100:101], v[164:165]
	v_pk_fma_f32 v[106:107], v[156:157], v[164:165], v[106:107] neg_lo:[0,0,1] neg_hi:[0,0,1]
	v_pk_fma_f32 v[112:113], v[152:153], v[160:161], v[112:113] neg_lo:[0,0,1] neg_hi:[0,0,1]
	v_pk_fma_f32 v[100:101], v[156:157], v[158:159], v[100:101]
	v_pk_fma_f32 v[108:109], v[152:153], v[154:155], v[108:109]
	v_mov_b32_e32 v160, v114
	v_mov_b32_e32 v161, v114
	v_pk_mul_f32 v[154:155], v[160:161], v[110:111]
	v_pk_mul_f32 v[158:159], v[114:115], v[102:103]
	v_pk_mul_f32 v[104:105], v[160:161], v[104:105]
	v_pk_mul_f32 v[98:99], v[114:115], v[98:99]
	v_pk_mul_f32 v[152:153], v[160:161], v[112:113]
	v_pk_mul_f32 v[156:157], v[114:115], v[106:107]
	v_pk_mul_f32 v[108:109], v[160:161], v[108:109]
	v_pk_mul_f32 v[100:101], v[114:115], v[100:101]
; __device__ __forceinline__ u32x4 pk8(const f32x4 a, const f32x4 b) { u32x4 w; w.x = cvt_pk_bf16(a[0], a[1]); w.y = cvt_pk_bf16(a[2], a[3]); w.z = cvt_pk_bf16(b[0], b[1]); w.w = cvt_pk_bf16(b[2], b[3]); return w; }
;     __device__ __forceinline__ void operator()(const i32x4 (&acc)[2][2][4][2], const Unit& u, int wr, int wc, int fr, int fq) const {
;     ...
;             for (int m = 0; m < 4; ++m) {
;                 const int row = row0 + ai * HALF + m * 16;
;                 const float rf = rowinv[row];
;                 bf16_t* rowp = O + (size_t)row * 14336 + col0;
;                 f32x4 q[2][2];
; #pragma unroll
;                 for (int bj = 0; bj < 2; ++bj)
; #pragma unroll
;                     for (int n = 0; n < 2; ++n) { const i32x4 a = acc[ai][bj][m][n]; f32x4 t; t.x = (float)a.x; t.y = (float)a.y; t.z = (float)a.z; t.w = (float)a.w; q[bj][n] = t * rf * cs[bj][n]; }
;                 f32x4 a0 = q[0][0], a1 = q[0][1], b0 = q[1][0], b1 = q[1][1];
;                 if (rot) {
;                     const int pos = row < 16384 ? (row & 2047) : (row - 16384);
;                     const f32x4* rp = (const f32x4*)(rope + ((size_t)pos * 128 + wc * 32 + 8 * fq) * 2);
;                     const f32x4 r0 = rp[0], r1 = rp[1], r2 = rp[2], r3 = rp[3];
;                     const f32x4 c0 = {r0.x, r0.z, r1.x, r1.z}, s0 = {r0.y, r0.w, r1.y, r1.w}, c1 = {r2.x, r2.z, r3.x, r3.z}, s1 = {r2.y, r2.w, r3.y, r3.w};
;                     const f32x4 na0 = a0 * c0 - b0 * s0, nb0 = a0 * s0 + b0 * c0, na1 = a1 * c1 - b1 * s1, nb1 = a1 * s1 + b1 * c1;
;                     a0 = na0 * ksc; b0 = nb0 * ksc; a1 = na1 * ksc; b1 = nb1 * ksc;
;                 }
;                 *(u32x4*)(rowp) = pk8(a0, a1); *(u32x4*)(rowp + HALF) = pk8(b0, b1);
.LBB0_339:
	v_mov_b64_e32 v[102:103], s[8:9]
	v_mad_i64_i32 v[102:103], s[30:31], v150, s33, v[102:103]
	v_lshl_add_u64 v[102:103], v[142:143], 1, v[102:103]
	v_cvt_pk_bf16_f32 v110, v158, v159
	v_cvt_pk_bf16_f32 v111, v154, v155
	v_cvt_pk_bf16_f32 v112, v156, v157
	v_cvt_pk_bf16_f32 v113, v152, v153
	global_store_dwordx4 v[102:103], v[110:113], off nt
	v_cvt_pk_bf16_f32 v98, v98, v99
	v_cvt_pk_bf16_f32 v99, v104, v105
	v_cvt_pk_bf16_f32 v100, v100, v101
	v_cvt_pk_bf16_f32 v101, v108, v109
	global_store_dwordx4 v[102:103], v[98:101], off offset:256 nt
	v_cvt_f32_i32_e32 v97, v97
	v_cvt_f32_i32_e32 v96, v96
	v_or_b32_e32 v98, 32, v144
	v_ashrrev_i32_e32 v99, 31, v98
	v_lshl_add_u64 v[100:101], v[98:99], 2, s[14:15]
	global_load_dword v100, v[100:101], off
	v_cvt_f32_i32_e32 v95, v95
	v_cvt_f32_i32_e32 v94, v94
	v_cvt_f32_i32_e32 v93, v93
	v_cvt_f32_i32_e32 v92, v92
	v_cvt_f32_i32_e32 v91, v91
	v_cvt_f32_i32_e32 v90, v90
	v_cvt_f32_i32_e32 v89, v89
	v_cvt_f32_i32_e32 v88, v88
	v_cvt_f32_i32_e32 v87, v87
	v_cvt_f32_i32_e32 v86, v86
	v_cvt_f32_i32_e32 v85, v85
	v_cvt_f32_i32_e32 v84, v84
	v_cvt_f32_i32_e32 v83, v83
	v_cvt_f32_i32_e32 v82, v82
	s_and_b64 vcc, exec, s[6:7]
	s_waitcnt vmcnt(0)
	v_pk_mul_f32 v[94:95], v[100:101], v[94:95] op_sel_hi:[0,1]
	v_pk_mul_f32 v[96:97], v[100:101], v[96:97] op_sel_hi:[0,1]
	v_pk_mul_f32 v[90:91], v[100:101], v[90:91] op_sel_hi:[0,1]
	v_pk_mul_f32 v[92:93], v[100:101], v[92:93] op_sel_hi:[0,1]
	v_pk_mul_f32 v[86:87], v[100:101], v[86:87] op_sel_hi:[0,1]
	v_pk_mul_f32 v[88:89], v[100:101], v[88:89] op_sel_hi:[0,1]
	v_pk_mul_f32 v[108:109], v[100:101], v[82:83] op_sel_hi:[0,1]
	v_pk_mul_f32 v[84:85], v[100:101], v[84:85] op_sel_hi:[0,1]
	v_pk_mul_f32 v[102:103], v[122:123], v[96:97]
	v_pk_mul_f32 v[106:107], v[148:149], v[94:95]
	v_pk_mul_f32 v[100:101], v[120:121], v[92:93]
	v_pk_mul_f32 v[104:105], v[128:129], v[90:91]
	v_pk_mul_f32 v[88:89], v[118:119], v[88:89]
	v_pk_mul_f32 v[82:83], v[126:127], v[86:87]
	v_pk_mul_f32 v[92:93], v[116:117], v[84:85]
	v_pk_mul_f32 v[84:85], v[124:125], v[108:109]
	s_cbranch_vccnz .LBB0_341
	v_cmp_gt_i32_e32 vcc, s49, v98
	v_and_b32_e32 v86, 0x7ef, v98
	v_add_u32_e32 v87, 0xffffc020, v144
	v_cndmask_b32_e32 v86, v87, v86, vcc
	v_ashrrev_i32_e32 v87, 31, v86
	v_lshlrev_b64 v[86:87], 10, v[86:87]
	v_lshl_add_u64 v[86:87], v[136:137], 0, v[86:87]
	global_load_dwordx4 v[108:111], v[86:87], off offset:48
	global_load_dwordx4 v[150:153], v[86:87], off offset:32
	global_load_dwordx4 v[154:157], v[86:87], off offset:16
	global_load_dwordx4 v[158:161], v[86:87], off
	s_waitcnt vmcnt(1)
	v_mov_b32_e32 v90, v155
	v_mov_b32_e32 v91, v157
	s_waitcnt vmcnt(0)
	v_mov_b32_e32 v96, v159
	v_mov_b32_e32 v97, v161
	v_mov_b32_e32 v159, v160
	v_mov_b32_e32 v155, v156
	v_pk_mul_f32 v[94:95], v[88:89], v[90:91]
	v_pk_mul_f32 v[86:87], v[82:83], v[96:97]
	v_pk_mul_f32 v[88:89], v[88:89], v[154:155]
	v_pk_mul_f32 v[82:83], v[82:83], v[158:159]
	v_pk_fma_f32 v[86:87], v[106:107], v[158:159], v[86:87] neg_lo:[0,0,1] neg_hi:[0,0,1]
	v_pk_fma_f32 v[94:95], v[102:103], v[154:155], v[94:95] neg_lo:[0,0,1] neg_hi:[0,0,1]
	v_pk_fma_f32 v[82:83], v[106:107], v[96:97], v[82:83]
	v_pk_fma_f32 v[88:89], v[102:103], v[90:91], v[88:89]
	v_mov_b32_e32 v102, v109
	v_mov_b32_e32 v103, v111
	v_mov_b32_e32 v106, v151
	v_mov_b32_e32 v107, v153
	v_mov_b32_e32 v151, v152
	v_mov_b32_e32 v109, v110
	v_pk_mul_f32 v[96:97], v[92:93], v[102:103]
	v_pk_mul_f32 v[90:91], v[84:85], v[106:107]
	v_pk_mul_f32 v[92:93], v[92:93], v[108:109]
	v_pk_mul_f32 v[84:85], v[84:85], v[150:151]
	v_pk_fma_f32 v[90:91], v[104:105], v[150:151], v[90:91] neg_lo:[0,0,1] neg_hi:[0,0,1]
	v_pk_fma_f32 v[96:97], v[100:101], v[108:109], v[96:97] neg_lo:[0,0,1] neg_hi:[0,0,1]
	v_pk_fma_f32 v[84:85], v[104:105], v[106:107], v[84:85]
	v_pk_fma_f32 v[92:93], v[100:101], v[102:103], v[92:93]
	v_mov_b32_e32 v108, v114
	v_mov_b32_e32 v109, v114
	v_pk_mul_f32 v[102:103], v[108:109], v[94:95]
	v_pk_mul_f32 v[106:107], v[114:115], v[86:87]
	v_pk_mul_f32 v[88:89], v[108:109], v[88:89]
	v_pk_mul_f32 v[82:83], v[114:115], v[82:83]
	v_pk_mul_f32 v[100:101], v[108:109], v[96:97]
	v_pk_mul_f32 v[104:105], v[114:115], v[90:91]
	v_pk_mul_f32 v[92:93], v[108:109], v[92:93]
	v_pk_mul_f32 v[84:85], v[114:115], v[84:85]
; __device__ __forceinline__ u32x4 pk8(const f32x4 a, const f32x4 b) { u32x4 w; w.x = cvt_pk_bf16(a[0], a[1]); w.y = cvt_pk_bf16(a[2], a[3]); w.z = cvt_pk_bf16(b[0], b[1]); w.w = cvt_pk_bf16(b[2], b[3]); return w; }
;     __device__ __forceinline__ void operator()(const i32x4 (&acc)[2][2][4][2], const Unit& u, int wr, int wc, int fr, int fq) const {
;     ...
;             for (int m = 0; m < 4; ++m) {
;                 const int row = row0 + ai * HALF + m * 16;
;                 const float rf = rowinv[row];
;                 bf16_t* rowp = O + (size_t)row * 14336 + col0;
;                 f32x4 q[2][2];
; #pragma unroll
;                 for (int bj = 0; bj < 2; ++bj)
; #pragma unroll
;                     for (int n = 0; n < 2; ++n) { const i32x4 a = acc[ai][bj][m][n]; f32x4 t; t.x = (float)a.x; t.y = (float)a.y; t.z = (float)a.z; t.w = (float)a.w; q[bj][n] = t * rf * cs[bj][n]; }
;                 f32x4 a0 = q[0][0], a1 = q[0][1], b0 = q[1][0], b1 = q[1][1];
;                 if (rot) {
;                     const int pos = row < 16384 ? (row & 2047) : (row - 16384);
;                     const f32x4* rp = (const f32x4*)(rope + ((size_t)pos * 128 + wc * 32 + 8 * fq) * 2);
;                     const f32x4 r0 = rp[0], r1 = rp[1], r2 = rp[2], r3 = rp[3];
;                     const f32x4 c0 = {r0.x, r0.z, r1.x, r1.z}, s0 = {r0.y, r0.w, r1.y, r1.w}, c1 = {r2.x, r2.z, r3.x, r3.z}, s1 = {r2.y, r2.w, r3.y, r3.w};
;                     const f32x4 na0 = a0 * c0 - b0 * s0, nb0 = a0 * s0 + b0 * c0, na1 = a1 * c1 - b1 * s1, nb1 = a1 * s1 + b1 * c1;
;                     a0 = na0 * ksc; b0 = nb0 * ksc; a1 = na1 * ksc; b1 = nb1 * ksc;
;                 }
;                 *(u32x4*)(rowp) = pk8(a0, a1); *(u32x4*)(rowp + HALF) = pk8(b0, b1);
.LBB0_341:
	v_mov_b64_e32 v[86:87], s[8:9]
	v_mad_i64_i32 v[86:87], s[30:31], v98, s33, v[86:87]
	v_lshl_add_u64 v[86:87], v[142:143], 1, v[86:87]
	v_cvt_pk_bf16_f32 v94, v106, v107
	v_cvt_pk_bf16_f32 v95, v102, v103
	v_cvt_pk_bf16_f32 v96, v104, v105
	v_cvt_pk_bf16_f32 v97, v100, v101
	global_store_dwordx4 v[86:87], v[94:97], off nt
	v_cvt_pk_bf16_f32 v82, v82, v83
	v_cvt_pk_bf16_f32 v83, v88, v89
	v_cvt_pk_bf16_f32 v84, v84, v85
	v_cvt_pk_bf16_f32 v85, v92, v93
	global_store_dwordx4 v[86:87], v[82:85], off offset:256 nt
	v_cvt_f32_i32_e32 v81, v81
	v_cvt_f32_i32_e32 v80, v80
	v_or_b32_e32 v82, 48, v144
	v_ashrrev_i32_e32 v83, 31, v82
	v_lshl_add_u64 v[84:85], v[82:83], 2, s[14:15]
	global_load_dword v84, v[84:85], off
	v_cvt_f32_i32_e32 v79, v79
	v_cvt_f32_i32_e32 v78, v78
	v_cvt_f32_i32_e32 v77, v77
	v_cvt_f32_i32_e32 v76, v76
	v_cvt_f32_i32_e32 v75, v75
	v_cvt_f32_i32_e32 v74, v74
	v_cvt_f32_i32_e32 v73, v73
	v_cvt_f32_i32_e32 v72, v72
	v_cvt_f32_i32_e32 v71, v71
	v_cvt_f32_i32_e32 v70, v70
	v_cvt_f32_i32_e32 v69, v69
	v_cvt_f32_i32_e32 v68, v68
	v_cvt_f32_i32_e32 v67, v67
	v_cvt_f32_i32_e32 v66, v66
	s_and_b64 vcc, exec, s[6:7]
	s_waitcnt vmcnt(0)
	v_pk_mul_f32 v[78:79], v[84:85], v[78:79] op_sel_hi:[0,1]
	v_pk_mul_f32 v[80:81], v[84:85], v[80:81] op_sel_hi:[0,1]
	v_pk_mul_f32 v[74:75], v[84:85], v[74:75] op_sel_hi:[0,1]
	v_pk_mul_f32 v[76:77], v[84:85], v[76:77] op_sel_hi:[0,1]
	v_pk_mul_f32 v[70:71], v[84:85], v[70:71] op_sel_hi:[0,1]
	v_pk_mul_f32 v[72:73], v[84:85], v[72:73] op_sel_hi:[0,1]
	v_pk_mul_f32 v[92:93], v[84:85], v[66:67] op_sel_hi:[0,1]
	v_pk_mul_f32 v[68:69], v[84:85], v[68:69] op_sel_hi:[0,1]
	v_pk_mul_f32 v[86:87], v[122:123], v[80:81]
	v_pk_mul_f32 v[90:91], v[148:149], v[78:79]
	v_pk_mul_f32 v[84:85], v[120:121], v[76:77]
	v_pk_mul_f32 v[88:89], v[128:129], v[74:75]
	v_pk_mul_f32 v[72:73], v[118:119], v[72:73]
	v_pk_mul_f32 v[66:67], v[126:127], v[70:71]
	v_pk_mul_f32 v[76:77], v[116:117], v[68:69]
	v_pk_mul_f32 v[68:69], v[124:125], v[92:93]
	s_cbranch_vccnz .LBB0_343
	v_cmp_gt_i32_e32 vcc, s49, v82
	v_and_b32_e32 v70, 0x7ff, v82
	v_add_u32_e32 v71, 0xffffc030, v144
	v_cndmask_b32_e32 v70, v71, v70, vcc
	v_ashrrev_i32_e32 v71, 31, v70
	v_lshlrev_b64 v[70:71], 10, v[70:71]
	v_lshl_add_u64 v[70:71], v[136:137], 0, v[70:71]
	global_load_dwordx4 v[92:95], v[70:71], off offset:48
	global_load_dwordx4 v[96:99], v[70:71], off offset:32
	global_load_dwordx4 v[100:103], v[70:71], off offset:16
	global_load_dwordx4 v[104:107], v[70:71], off
	s_waitcnt vmcnt(1)
	v_mov_b32_e32 v74, v101
	v_mov_b32_e32 v75, v103
	s_waitcnt vmcnt(0)
	v_mov_b32_e32 v80, v105
	v_mov_b32_e32 v81, v107
	v_mov_b32_e32 v105, v106
	v_mov_b32_e32 v101, v102
	v_pk_mul_f32 v[78:79], v[72:73], v[74:75]
	v_pk_mul_f32 v[70:71], v[66:67], v[80:81]
	v_pk_mul_f32 v[72:73], v[72:73], v[100:101]
	v_pk_mul_f32 v[66:67], v[66:67], v[104:105]
	v_pk_fma_f32 v[70:71], v[90:91], v[104:105], v[70:71] neg_lo:[0,0,1] neg_hi:[0,0,1]
	v_pk_fma_f32 v[78:79], v[86:87], v[100:101], v[78:79] neg_lo:[0,0,1] neg_hi:[0,0,1]
	v_pk_fma_f32 v[66:67], v[90:91], v[80:81], v[66:67]
	v_pk_fma_f32 v[72:73], v[86:87], v[74:75], v[72:73]
	v_mov_b32_e32 v86, v93
	v_mov_b32_e32 v87, v95
	v_mov_b32_e32 v90, v97
	v_mov_b32_e32 v91, v99
	v_mov_b32_e32 v97, v98
	v_mov_b32_e32 v93, v94
	v_pk_mul_f32 v[80:81], v[76:77], v[86:87]
	v_pk_mul_f32 v[74:75], v[68:69], v[90:91]
	v_pk_mul_f32 v[76:77], v[76:77], v[92:93]
	v_pk_mul_f32 v[68:69], v[68:69], v[96:97]
	v_pk_fma_f32 v[74:75], v[88:89], v[96:97], v[74:75] neg_lo:[0,0,1] neg_hi:[0,0,1]
	v_pk_fma_f32 v[80:81], v[84:85], v[92:93], v[80:81] neg_lo:[0,0,1] neg_hi:[0,0,1]
	v_pk_fma_f32 v[68:69], v[88:89], v[90:91], v[68:69]
	v_pk_fma_f32 v[76:77], v[84:85], v[86:87], v[76:77]
	v_mov_b32_e32 v92, v114
	v_mov_b32_e32 v93, v114
	v_pk_mul_f32 v[86:87], v[92:93], v[78:79]
	v_pk_mul_f32 v[90:91], v[114:115], v[70:71]
	v_pk_mul_f32 v[72:73], v[92:93], v[72:73]
	v_pk_mul_f32 v[66:67], v[114:115], v[66:67]
	v_pk_mul_f32 v[84:85], v[92:93], v[80:81]
	v_pk_mul_f32 v[88:89], v[114:115], v[74:75]
	v_pk_mul_f32 v[76:77], v[92:93], v[76:77]
	v_pk_mul_f32 v[68:69], v[114:115], v[68:69]
.LBB0_343:
	v_mov_b64_e32 v[70:71], s[8:9]
	v_mad_i64_i32 v[70:71], s[30:31], v82, s33, v[70:71]
	v_lshl_add_u64 v[70:71], v[142:143], 1, v[70:71]
	v_cvt_pk_bf16_f32 v78, v90, v91
	v_cvt_pk_bf16_f32 v79, v86, v87
	v_cvt_pk_bf16_f32 v80, v88, v89
	v_cvt_pk_bf16_f32 v81, v84, v85
	global_store_dwordx4 v[70:71], v[78:81], off nt
	v_cvt_pk_bf16_f32 v66, v66, v67
	v_cvt_pk_bf16_f32 v67, v72, v73
	v_cvt_pk_bf16_f32 v68, v68, v69
	v_cvt_pk_bf16_f32 v69, v76, v77
	global_store_dwordx4 v[70:71], v[66:69], off offset:256 nt
	global_load_dword v66, v[146:147], off offset:512
	v_cvt_f32_i32_e32 v65, v65
	v_cvt_f32_i32_e32 v64, v64
	v_cvt_f32_i32_e32 v63, v63
	v_cvt_f32_i32_e32 v62, v62
	v_cvt_f32_i32_e32 v61, v61
	v_cvt_f32_i32_e32 v60, v60
	v_cvt_f32_i32_e32 v59, v59
	v_cvt_f32_i32_e32 v58, v58
	v_cvt_f32_i32_e32 v57, v57
	v_cvt_f32_i32_e32 v56, v56
	v_cvt_f32_i32_e32 v55, v55
	v_cvt_f32_i32_e32 v54, v54
	v_cvt_f32_i32_e32 v53, v53
	v_cvt_f32_i32_e32 v52, v52
	v_cvt_f32_i32_e32 v51, v51
	v_cvt_f32_i32_e32 v50, v50
	v_add_u32_e32 v74, 0x80, v144
	s_and_b64 vcc, exec, s[6:7]
	s_waitcnt vmcnt(0)
	v_pk_mul_f32 v[62:63], v[66:67], v[62:63] op_sel_hi:[0,1]
	v_pk_mul_f32 v[64:65], v[66:67], v[64:65] op_sel_hi:[0,1]
	v_pk_mul_f32 v[58:59], v[66:67], v[58:59] op_sel_hi:[0,1]
	v_pk_mul_f32 v[60:61], v[66:67], v[60:61] op_sel_hi:[0,1]
	v_pk_mul_f32 v[54:55], v[66:67], v[54:55] op_sel_hi:[0,1]
	v_pk_mul_f32 v[56:57], v[66:67], v[56:57] op_sel_hi:[0,1]
	v_pk_mul_f32 v[76:77], v[66:67], v[50:51] op_sel_hi:[0,1]
	v_pk_mul_f32 v[52:53], v[66:67], v[52:53] op_sel_hi:[0,1]
	v_pk_mul_f32 v[68:69], v[122:123], v[64:65]
	v_pk_mul_f32 v[72:73], v[148:149], v[62:63]
	v_pk_mul_f32 v[66:67], v[120:121], v[60:61]
	v_pk_mul_f32 v[70:71], v[128:129], v[58:59]
	v_pk_mul_f32 v[56:57], v[118:119], v[56:57]
	v_pk_mul_f32 v[50:51], v[126:127], v[54:55]
	v_pk_mul_f32 v[60:61], v[116:117], v[52:53]
	v_pk_mul_f32 v[52:53], v[124:125], v[76:77]
	s_cbranch_vccnz .LBB0_345
; __device__ __forceinline__ u32x4 pk8(const f32x4 a, const f32x4 b) { u32x4 w; w.x = cvt_pk_bf16(a[0], a[1]); w.y = cvt_pk_bf16(a[2], a[3]); w.z = cvt_pk_bf16(b[0], b[1]); w.w = cvt_pk_bf16(b[2], b[3]); return w; }
;     __device__ __forceinline__ void operator()(const i32x4 (&acc)[2][2][4][2], const Unit& u, int wr, int wc, int fr, int fq) const {
;     ...
;             for (int m = 0; m < 4; ++m) {
;                 const int row = row0 + ai * HALF + m * 16;
;                 const float rf = rowinv[row];
;                 bf16_t* rowp = O + (size_t)row * 14336 + col0;
;                 f32x4 q[2][2];
; #pragma unroll
;                 for (int bj = 0; bj < 2; ++bj)
; #pragma unroll
;                     for (int n = 0; n < 2; ++n) { const i32x4 a = acc[ai][bj][m][n]; f32x4 t; t.x = (float)a.x; t.y = (float)a.y; t.z = (float)a.z; t.w = (float)a.w; q[bj][n] = t * rf * cs[bj][n]; }
;                 f32x4 a0 = q[0][0], a1 = q[0][1], b0 = q[1][0], b1 = q[1][1];
;                 if (rot) {
;                     const int pos = row < 16384 ? (row & 2047) : (row - 16384);
;                     const f32x4* rp = (const f32x4*)(rope + ((size_t)pos * 128 + wc * 32 + 8 * fq) * 2);
;                     const f32x4 r0 = rp[0], r1 = rp[1], r2 = rp[2], r3 = rp[3];
;                     const f32x4 c0 = {r0.x, r0.z, r1.x, r1.z}, s0 = {r0.y, r0.w, r1.y, r1.w}, c1 = {r2.x, r2.z, r3.x, r3.z}, s1 = {r2.y, r2.w, r3.y, r3.w};
;                     const f32x4 na0 = a0 * c0 - b0 * s0, nb0 = a0 * s0 + b0 * c0, na1 = a1 * c1 - b1 * s1, nb1 = a1 * s1 + b1 * c1;
;                     a0 = na0 * ksc; b0 = nb0 * ksc; a1 = na1 * ksc; b1 = nb1 * ksc;
;                 }
;                 *(u32x4*)(rowp) = pk8(a0, a1); *(u32x4*)(rowp + HALF) = pk8(b0, b1);
	s_movk_i32 s30, 0x3f80
	v_cmp_gt_i32_e32 vcc, s30, v144
	v_and_b32_e32 v54, 0x7cf, v74
	v_add_u32_e32 v55, 0xffffc080, v144
	v_cndmask_b32_e32 v54, v55, v54, vcc
	v_ashrrev_i32_e32 v55, 31, v54
	v_lshlrev_b64 v[54:55], 10, v[54:55]
	v_lshl_add_u64 v[54:55], v[136:137], 0, v[54:55]
	global_load_dwordx4 v[76:79], v[54:55], off offset:48
	global_load_dwordx4 v[80:83], v[54:55], off offset:32
	global_load_dwordx4 v[84:87], v[54:55], off offset:16
	global_load_dwordx4 v[88:91], v[54:55], off
	s_waitcnt vmcnt(1)
	v_mov_b32_e32 v58, v85
	v_mov_b32_e32 v59, v87
	s_waitcnt vmcnt(0)
	v_mov_b32_e32 v64, v89
	v_mov_b32_e32 v65, v91
	v_mov_b32_e32 v89, v90
	v_mov_b32_e32 v85, v86
	v_pk_mul_f32 v[62:63], v[56:57], v[58:59]
	v_pk_mul_f32 v[54:55], v[50:51], v[64:65]
	v_pk_mul_f32 v[56:57], v[56:57], v[84:85]
	v_pk_mul_f32 v[50:51], v[50:51], v[88:89]
	v_pk_fma_f32 v[54:55], v[72:73], v[88:89], v[54:55] neg_lo:[0,0,1] neg_hi:[0,0,1]
	v_pk_fma_f32 v[62:63], v[68:69], v[84:85], v[62:63] neg_lo:[0,0,1] neg_hi:[0,0,1]
	v_pk_fma_f32 v[50:51], v[72:73], v[64:65], v[50:51]
	v_pk_fma_f32 v[56:57], v[68:69], v[58:59], v[56:57]
	v_mov_b32_e32 v68, v77
	v_mov_b32_e32 v69, v79
	v_mov_b32_e32 v72, v81
	v_mov_b32_e32 v73, v83
	v_mov_b32_e32 v81, v82
	v_mov_b32_e32 v77, v78
	v_pk_mul_f32 v[64:65], v[60:61], v[68:69]
	v_pk_mul_f32 v[58:59], v[52:53], v[72:73]
	v_pk_mul_f32 v[60:61], v[60:61], v[76:77]
	v_pk_mul_f32 v[52:53], v[52:53], v[80:81]
	v_pk_fma_f32 v[58:59], v[70:71], v[80:81], v[58:59] neg_lo:[0,0,1] neg_hi:[0,0,1]
	v_pk_fma_f32 v[64:65], v[66:67], v[76:77], v[64:65] neg_lo:[0,0,1] neg_hi:[0,0,1]
	v_pk_fma_f32 v[52:53], v[70:71], v[72:73], v[52:53]
	v_pk_fma_f32 v[60:61], v[66:67], v[68:69], v[60:61]
	v_mov_b32_e32 v76, v114
	v_mov_b32_e32 v77, v114
	v_pk_mul_f32 v[68:69], v[76:77], v[62:63]
	v_pk_mul_f32 v[72:73], v[114:115], v[54:55]
	v_pk_mul_f32 v[56:57], v[76:77], v[56:57]
	v_pk_mul_f32 v[50:51], v[114:115], v[50:51]
	v_pk_mul_f32 v[66:67], v[76:77], v[64:65]
	v_pk_mul_f32 v[70:71], v[114:115], v[58:59]
	v_pk_mul_f32 v[60:61], v[76:77], v[60:61]
	v_pk_mul_f32 v[52:53], v[114:115], v[52:53]
.LBB0_345:
	v_mov_b64_e32 v[54:55], s[8:9]
	v_mad_i64_i32 v[54:55], s[30:31], v74, s33, v[54:55]
	v_lshl_add_u64 v[54:55], v[142:143], 1, v[54:55]
	v_cvt_pk_bf16_f32 v62, v72, v73
	v_cvt_pk_bf16_f32 v63, v68, v69
	v_cvt_pk_bf16_f32 v64, v70, v71
	v_cvt_pk_bf16_f32 v65, v66, v67
	global_store_dwordx4 v[54:55], v[62:65], off nt
	v_cvt_pk_bf16_f32 v50, v50, v51
	v_cvt_pk_bf16_f32 v51, v56, v57
	v_cvt_pk_bf16_f32 v52, v52, v53
	v_cvt_pk_bf16_f32 v53, v60, v61
	global_store_dwordx4 v[54:55], v[50:53], off offset:256 nt
	global_load_dword v50, v[146:147], off offset:576
	v_cvt_f32_i32_e32 v49, v49
	v_cvt_f32_i32_e32 v48, v48
	v_cvt_f32_i32_e32 v47, v47
	v_cvt_f32_i32_e32 v46, v46
	v_cvt_f32_i32_e32 v45, v45
	v_cvt_f32_i32_e32 v44, v44
	v_cvt_f32_i32_e32 v43, v43
	v_cvt_f32_i32_e32 v42, v42
	v_cvt_f32_i32_e32 v41, v41
	v_cvt_f32_i32_e32 v40, v40
	v_cvt_f32_i32_e32 v39, v39
	v_cvt_f32_i32_e32 v38, v38
	v_cvt_f32_i32_e32 v37, v37
	v_cvt_f32_i32_e32 v36, v36
	v_cvt_f32_i32_e32 v35, v35
	v_cvt_f32_i32_e32 v34, v34
	v_add_u32_e32 v58, 0x90, v144
	s_and_b64 vcc, exec, s[6:7]
	s_waitcnt vmcnt(0)
	v_pk_mul_f32 v[46:47], v[50:51], v[46:47] op_sel_hi:[0,1]
	v_pk_mul_f32 v[48:49], v[50:51], v[48:49] op_sel_hi:[0,1]
	v_pk_mul_f32 v[42:43], v[50:51], v[42:43] op_sel_hi:[0,1]
	v_pk_mul_f32 v[44:45], v[50:51], v[44:45] op_sel_hi:[0,1]
	v_pk_mul_f32 v[38:39], v[50:51], v[38:39] op_sel_hi:[0,1]
	v_pk_mul_f32 v[40:41], v[50:51], v[40:41] op_sel_hi:[0,1]
	v_pk_mul_f32 v[60:61], v[50:51], v[34:35] op_sel_hi:[0,1]
	v_pk_mul_f32 v[36:37], v[50:51], v[36:37] op_sel_hi:[0,1]
	v_pk_mul_f32 v[52:53], v[122:123], v[48:49]
	v_pk_mul_f32 v[56:57], v[148:149], v[46:47]
	v_pk_mul_f32 v[50:51], v[120:121], v[44:45]
	v_pk_mul_f32 v[54:55], v[128:129], v[42:43]
	v_pk_mul_f32 v[40:41], v[118:119], v[40:41]
	v_pk_mul_f32 v[34:35], v[126:127], v[38:39]
	v_pk_mul_f32 v[44:45], v[116:117], v[36:37]
	v_pk_mul_f32 v[36:37], v[124:125], v[60:61]
	s_cbranch_vccnz .LBB0_347
	s_movk_i32 s30, 0x3f70
	v_cmp_gt_i32_e32 vcc, s30, v144
	v_and_b32_e32 v38, 0x7df, v58
	v_add_u32_e32 v39, 0xffffc090, v144
	v_cndmask_b32_e32 v38, v39, v38, vcc
	v_ashrrev_i32_e32 v39, 31, v38
	v_lshlrev_b64 v[38:39], 10, v[38:39]
	v_lshl_add_u64 v[38:39], v[136:137], 0, v[38:39]
	global_load_dwordx4 v[60:63], v[38:39], off offset:48
	global_load_dwordx4 v[64:67], v[38:39], off offset:32
	global_load_dwordx4 v[68:71], v[38:39], off offset:16
	global_load_dwordx4 v[72:75], v[38:39], off
	s_waitcnt vmcnt(1)
	v_mov_b32_e32 v42, v69
	v_mov_b32_e32 v43, v71
	s_waitcnt vmcnt(0)
	v_mov_b32_e32 v48, v73
	v_mov_b32_e32 v49, v75
	v_mov_b32_e32 v73, v74
	v_mov_b32_e32 v69, v70
	v_pk_mul_f32 v[46:47], v[40:41], v[42:43]
	v_pk_mul_f32 v[38:39], v[34:35], v[48:49]
	v_pk_mul_f32 v[40:41], v[40:41], v[68:69]
	v_pk_mul_f32 v[34:35], v[34:35], v[72:73]
	v_pk_fma_f32 v[38:39], v[56:57], v[72:73], v[38:39] neg_lo:[0,0,1] neg_hi:[0,0,1]
	v_pk_fma_f32 v[46:47], v[52:53], v[68:69], v[46:47] neg_lo:[0,0,1] neg_hi:[0,0,1]
	v_pk_fma_f32 v[34:35], v[56:57], v[48:49], v[34:35]
	v_pk_fma_f32 v[40:41], v[52:53], v[42:43], v[40:41]
	v_mov_b32_e32 v52, v61
	v_mov_b32_e32 v53, v63
	v_mov_b32_e32 v56, v65
	v_mov_b32_e32 v57, v67
	v_mov_b32_e32 v65, v66
	v_mov_b32_e32 v61, v62
	v_pk_mul_f32 v[48:49], v[44:45], v[52:53]
	v_pk_mul_f32 v[42:43], v[36:37], v[56:57]
	v_pk_mul_f32 v[44:45], v[44:45], v[60:61]
	v_pk_mul_f32 v[36:37], v[36:37], v[64:65]
	v_pk_fma_f32 v[42:43], v[54:55], v[64:65], v[42:43] neg_lo:[0,0,1] neg_hi:[0,0,1]
	v_pk_fma_f32 v[48:49], v[50:51], v[60:61], v[48:49] neg_lo:[0,0,1] neg_hi:[0,0,1]
	v_pk_fma_f32 v[36:37], v[54:55], v[56:57], v[36:37]
	v_pk_fma_f32 v[44:45], v[50:51], v[52:53], v[44:45]
	v_mov_b32_e32 v60, v114
	v_mov_b32_e32 v61, v114
	v_pk_mul_f32 v[52:53], v[60:61], v[46:47]
	v_pk_mul_f32 v[56:57], v[114:115], v[38:39]
	v_pk_mul_f32 v[40:41], v[60:61], v[40:41]
	v_pk_mul_f32 v[34:35], v[114:115], v[34:35]
	v_pk_mul_f32 v[50:51], v[60:61], v[48:49]
	v_pk_mul_f32 v[54:55], v[114:115], v[42:43]
	v_pk_mul_f32 v[44:45], v[60:61], v[44:45]
	v_pk_mul_f32 v[36:37], v[114:115], v[36:37]
; __device__ __forceinline__ u32x4 pk8(const f32x4 a, const f32x4 b) { u32x4 w; w.x = cvt_pk_bf16(a[0], a[1]); w.y = cvt_pk_bf16(a[2], a[3]); w.z = cvt_pk_bf16(b[0], b[1]); w.w = cvt_pk_bf16(b[2], b[3]); return w; }
;     __device__ __forceinline__ void operator()(const i32x4 (&acc)[2][2][4][2], const Unit& u, int wr, int wc, int fr, int fq) const {
;     ...
;             for (int m = 0; m < 4; ++m) {
;                 const int row = row0 + ai * HALF + m * 16;
;                 const float rf = rowinv[row];
;                 bf16_t* rowp = O + (size_t)row * 14336 + col0;
;                 f32x4 q[2][2];
; #pragma unroll
;                 for (int bj = 0; bj < 2; ++bj)
; #pragma unroll
;                     for (int n = 0; n < 2; ++n) { const i32x4 a = acc[ai][bj][m][n]; f32x4 t; t.x = (float)a.x; t.y = (float)a.y; t.z = (float)a.z; t.w = (float)a.w; q[bj][n] = t * rf * cs[bj][n]; }
;                 f32x4 a0 = q[0][0], a1 = q[0][1], b0 = q[1][0], b1 = q[1][1];
;                 if (rot) {
;                     const int pos = row < 16384 ? (row & 2047) : (row - 16384);
;                     const f32x4* rp = (const f32x4*)(rope + ((size_t)pos * 128 + wc * 32 + 8 * fq) * 2);
;                     const f32x4 r0 = rp[0], r1 = rp[1], r2 = rp[2], r3 = rp[3];
;                     const f32x4 c0 = {r0.x, r0.z, r1.x, r1.z}, s0 = {r0.y, r0.w, r1.y, r1.w}, c1 = {r2.x, r2.z, r3.x, r3.z}, s1 = {r2.y, r2.w, r3.y, r3.w};
;                     const f32x4 na0 = a0 * c0 - b0 * s0, nb0 = a0 * s0 + b0 * c0, na1 = a1 * c1 - b1 * s1, nb1 = a1 * s1 + b1 * c1;
;                     a0 = na0 * ksc; b0 = nb0 * ksc; a1 = na1 * ksc; b1 = nb1 * ksc;
;                 }
;                 *(u32x4*)(rowp) = pk8(a0, a1); *(u32x4*)(rowp + HALF) = pk8(b0, b1);
.LBB0_347:
	v_mov_b64_e32 v[38:39], s[8:9]
	v_mad_i64_i32 v[38:39], s[30:31], v58, s33, v[38:39]
	v_lshl_add_u64 v[38:39], v[142:143], 1, v[38:39]
	v_cvt_pk_bf16_f32 v46, v56, v57
	v_cvt_pk_bf16_f32 v47, v52, v53
	v_cvt_pk_bf16_f32 v48, v54, v55
	v_cvt_pk_bf16_f32 v49, v50, v51
	global_store_dwordx4 v[38:39], v[46:49], off nt
	v_cvt_pk_bf16_f32 v34, v34, v35
	v_cvt_pk_bf16_f32 v35, v40, v41
	v_cvt_pk_bf16_f32 v36, v36, v37
	v_cvt_pk_bf16_f32 v37, v44, v45
	global_store_dwordx4 v[38:39], v[34:37], off offset:256 nt
	global_load_dword v34, v[146:147], off offset:640
	v_cvt_f32_i32_e32 v33, v33
	v_cvt_f32_i32_e32 v32, v32
	v_cvt_f32_i32_e32 v31, v31
	v_cvt_f32_i32_e32 v30, v30
	v_cvt_f32_i32_e32 v29, v29
	v_cvt_f32_i32_e32 v28, v28
	v_cvt_f32_i32_e32 v27, v27
	v_cvt_f32_i32_e32 v26, v26
	v_cvt_f32_i32_e32 v25, v25
	v_cvt_f32_i32_e32 v24, v24
	v_cvt_f32_i32_e32 v23, v23
	v_cvt_f32_i32_e32 v22, v22
	v_cvt_f32_i32_e32 v21, v21
	v_cvt_f32_i32_e32 v20, v20
	v_cvt_f32_i32_e32 v19, v19
	v_cvt_f32_i32_e32 v18, v18
	v_add_u32_e32 v42, 0xa0, v144
	s_and_b64 vcc, exec, s[6:7]
	s_waitcnt vmcnt(0)
	v_pk_mul_f32 v[30:31], v[34:35], v[30:31] op_sel_hi:[0,1]
	v_pk_mul_f32 v[32:33], v[34:35], v[32:33] op_sel_hi:[0,1]
	v_pk_mul_f32 v[26:27], v[34:35], v[26:27] op_sel_hi:[0,1]
	v_pk_mul_f32 v[28:29], v[34:35], v[28:29] op_sel_hi:[0,1]
	v_pk_mul_f32 v[22:23], v[34:35], v[22:23] op_sel_hi:[0,1]
	v_pk_mul_f32 v[24:25], v[34:35], v[24:25] op_sel_hi:[0,1]
	v_pk_mul_f32 v[44:45], v[34:35], v[18:19] op_sel_hi:[0,1]
	v_pk_mul_f32 v[20:21], v[34:35], v[20:21] op_sel_hi:[0,1]
	v_pk_mul_f32 v[36:37], v[122:123], v[32:33]
	v_pk_mul_f32 v[40:41], v[148:149], v[30:31]
	v_pk_mul_f32 v[34:35], v[120:121], v[28:29]
	v_pk_mul_f32 v[38:39], v[128:129], v[26:27]
	v_pk_mul_f32 v[24:25], v[118:119], v[24:25]
	v_pk_mul_f32 v[18:19], v[126:127], v[22:23]
	v_pk_mul_f32 v[28:29], v[116:117], v[20:21]
	v_pk_mul_f32 v[20:21], v[124:125], v[44:45]
	s_cbranch_vccnz .LBB0_349
	s_movk_i32 s30, 0x3f60
	v_cmp_gt_i32_e32 vcc, s30, v144
	v_and_b32_e32 v22, 0x7ef, v42
	v_add_u32_e32 v23, 0xffffc0a0, v144
	v_cndmask_b32_e32 v22, v23, v22, vcc
	v_ashrrev_i32_e32 v23, 31, v22
	v_lshlrev_b64 v[22:23], 10, v[22:23]
	v_lshl_add_u64 v[22:23], v[136:137], 0, v[22:23]
	global_load_dwordx4 v[44:47], v[22:23], off offset:48
	global_load_dwordx4 v[48:51], v[22:23], off offset:32
	global_load_dwordx4 v[52:55], v[22:23], off offset:16
	global_load_dwordx4 v[56:59], v[22:23], off
	s_waitcnt vmcnt(1)
	v_mov_b32_e32 v26, v53
	v_mov_b32_e32 v27, v55
	s_waitcnt vmcnt(0)
	v_mov_b32_e32 v32, v57
	v_mov_b32_e32 v33, v59
	v_mov_b32_e32 v57, v58
	v_mov_b32_e32 v53, v54
	v_pk_mul_f32 v[30:31], v[24:25], v[26:27]
	v_pk_mul_f32 v[22:23], v[18:19], v[32:33]
	v_pk_mul_f32 v[24:25], v[24:25], v[52:53]
	v_pk_mul_f32 v[18:19], v[18:19], v[56:57]
	v_pk_fma_f32 v[22:23], v[40:41], v[56:57], v[22:23] neg_lo:[0,0,1] neg_hi:[0,0,1]
	v_pk_fma_f32 v[30:31], v[36:37], v[52:53], v[30:31] neg_lo:[0,0,1] neg_hi:[0,0,1]
	v_pk_fma_f32 v[18:19], v[40:41], v[32:33], v[18:19]
	v_pk_fma_f32 v[24:25], v[36:37], v[26:27], v[24:25]
	v_mov_b32_e32 v36, v45
	v_mov_b32_e32 v37, v47
	v_mov_b32_e32 v40, v49
	v_mov_b32_e32 v41, v51
	v_mov_b32_e32 v49, v50
	v_mov_b32_e32 v45, v46
	v_pk_mul_f32 v[32:33], v[28:29], v[36:37]
	v_pk_mul_f32 v[26:27], v[20:21], v[40:41]
	v_pk_mul_f32 v[28:29], v[28:29], v[44:45]
	v_pk_mul_f32 v[20:21], v[20:21], v[48:49]
	v_pk_fma_f32 v[26:27], v[38:39], v[48:49], v[26:27] neg_lo:[0,0,1] neg_hi:[0,0,1]
	v_pk_fma_f32 v[32:33], v[34:35], v[44:45], v[32:33] neg_lo:[0,0,1] neg_hi:[0,0,1]
	v_pk_fma_f32 v[20:21], v[38:39], v[40:41], v[20:21]
	v_pk_fma_f32 v[28:29], v[34:35], v[36:37], v[28:29]
	v_mov_b32_e32 v44, v114
	v_mov_b32_e32 v45, v114
	v_pk_mul_f32 v[36:37], v[44:45], v[30:31]
	v_pk_mul_f32 v[40:41], v[114:115], v[22:23]
	v_pk_mul_f32 v[24:25], v[44:45], v[24:25]
	v_pk_mul_f32 v[18:19], v[114:115], v[18:19]
	v_pk_mul_f32 v[34:35], v[44:45], v[32:33]
	v_pk_mul_f32 v[38:39], v[114:115], v[26:27]
	v_pk_mul_f32 v[28:29], v[44:45], v[28:29]
	v_pk_mul_f32 v[20:21], v[114:115], v[20:21]
; #define PG8_BAR __builtin_amdgcn_s_barrier()
; __device__ __forceinline__ u32x4 pk8(const f32x4 a, const f32x4 b) { u32x4 w; w.x = cvt_pk_bf16(a[0], a[1]); w.y = cvt_pk_bf16(a[2], a[3]); w.z = cvt_pk_bf16(b[0], b[1]); w.w = cvt_pk_bf16(b[2], b[3]); return w; }
; template <class Epi, class Sched, bool ALIGN_EPI = false, bool SP2 = false, bool I8 = false, bool F16 = false>
; __device__ __forceinline__ void gemm_phase(PG8_LAS unsigned char* lds, const Gemm g, const Sched& S, const Epi& E) {
;     ...
;         cur = nxt; cA = nA; cB = nB; ++ui;
;         if constexpr (ALIGN_EPI) { if (wr == 1) PG8_BAR; }
;     __device__ __forceinline__ void operator()(const i32x4 (&acc)[2][2][4][2], const Unit& u, int wr, int wc, int fr, int fq) const {
;     ...
;             for (int m = 0; m < 4; ++m) {
;                 const int row = row0 + ai * HALF + m * 16;
;                 const float rf = rowinv[row];
;                 bf16_t* rowp = O + (size_t)row * 14336 + col0;
;                 f32x4 q[2][2];
; #pragma unroll
;                 for (int bj = 0; bj < 2; ++bj)
; #pragma unroll
;                     for (int n = 0; n < 2; ++n) { const i32x4 a = acc[ai][bj][m][n]; f32x4 t; t.x = (float)a.x; t.y = (float)a.y; t.z = (float)a.z; t.w = (float)a.w; q[bj][n] = t * rf * cs[bj][n]; }
;                 f32x4 a0 = q[0][0], a1 = q[0][1], b0 = q[1][0], b1 = q[1][1];
;                 if (rot) {
;                     const int pos = row < 16384 ? (row & 2047) : (row - 16384);
;                     const f32x4* rp = (const f32x4*)(rope + ((size_t)pos * 128 + wc * 32 + 8 * fq) * 2);
;                     const f32x4 r0 = rp[0], r1 = rp[1], r2 = rp[2], r3 = rp[3];
;                     const f32x4 c0 = {r0.x, r0.z, r1.x, r1.z}, s0 = {r0.y, r0.w, r1.y, r1.w}, c1 = {r2.x, r2.z, r3.x, r3.z}, s1 = {r2.y, r2.w, r3.y, r3.w};
;                     const f32x4 na0 = a0 * c0 - b0 * s0, nb0 = a0 * s0 + b0 * c0, na1 = a1 * c1 - b1 * s1, nb1 = a1 * s1 + b1 * c1;
;                     a0 = na0 * ksc; b0 = nb0 * ksc; a1 = na1 * ksc; b1 = nb1 * ksc;
;                 }
;                 *(u32x4*)(rowp) = pk8(a0, a1); *(u32x4*)(rowp + HALF) = pk8(b0, b1);
.LBB0_349:
	v_mov_b64_e32 v[22:23], s[8:9]
	v_mad_i64_i32 v[22:23], s[30:31], v42, s33, v[22:23]
	v_lshl_add_u64 v[22:23], v[142:143], 1, v[22:23]
	v_cvt_pk_bf16_f32 v30, v40, v41
	v_cvt_pk_bf16_f32 v31, v36, v37
	v_cvt_pk_bf16_f32 v32, v38, v39
	v_cvt_pk_bf16_f32 v33, v34, v35
	global_store_dwordx4 v[22:23], v[30:33], off nt
	v_cvt_pk_bf16_f32 v18, v18, v19
	v_cvt_pk_bf16_f32 v19, v24, v25
	v_cvt_pk_bf16_f32 v20, v20, v21
	v_cvt_pk_bf16_f32 v21, v28, v29
	global_store_dwordx4 v[22:23], v[18:21], off offset:256 nt
	global_load_dword v18, v[146:147], off offset:704
	v_cvt_f32_i32_e32 v17, v17
	v_cvt_f32_i32_e32 v16, v16
	v_cvt_f32_i32_e32 v15, v15
	v_cvt_f32_i32_e32 v14, v14
	v_cvt_f32_i32_e32 v13, v13
	v_cvt_f32_i32_e32 v12, v12
	v_cvt_f32_i32_e32 v11, v11
	v_cvt_f32_i32_e32 v10, v10
	v_cvt_f32_i32_e32 v9, v9
	v_cvt_f32_i32_e32 v8, v8
	v_cvt_f32_i32_e32 v7, v7
	v_cvt_f32_i32_e32 v6, v6
	v_cvt_f32_i32_e32 v5, v5
	v_cvt_f32_i32_e32 v4, v4
	v_cvt_f32_i32_e32 v3, v3
	v_cvt_f32_i32_e32 v2, v2
	v_add_u32_e32 v26, 0xb0, v144
	s_and_b64 vcc, exec, s[6:7]
	s_waitcnt vmcnt(0)
	v_pk_mul_f32 v[14:15], v[18:19], v[14:15] op_sel_hi:[0,1]
	v_pk_mul_f32 v[16:17], v[18:19], v[16:17] op_sel_hi:[0,1]
	v_pk_mul_f32 v[10:11], v[18:19], v[10:11] op_sel_hi:[0,1]
	v_pk_mul_f32 v[12:13], v[18:19], v[12:13] op_sel_hi:[0,1]
	v_pk_mul_f32 v[6:7], v[18:19], v[6:7] op_sel_hi:[0,1]
	v_pk_mul_f32 v[8:9], v[18:19], v[8:9] op_sel_hi:[0,1]
	v_pk_mul_f32 v[28:29], v[18:19], v[2:3] op_sel_hi:[0,1]
	v_pk_mul_f32 v[4:5], v[18:19], v[4:5] op_sel_hi:[0,1]
	v_pk_mul_f32 v[20:21], v[122:123], v[16:17]
	v_pk_mul_f32 v[24:25], v[148:149], v[14:15]
	v_pk_mul_f32 v[18:19], v[120:121], v[12:13]
	v_pk_mul_f32 v[22:23], v[128:129], v[10:11]
	v_pk_mul_f32 v[8:9], v[118:119], v[8:9]
	v_pk_mul_f32 v[2:3], v[126:127], v[6:7]
	v_pk_mul_f32 v[12:13], v[116:117], v[4:5]
	v_pk_mul_f32 v[4:5], v[124:125], v[28:29]
	s_cbranch_vccnz .LBB0_351
	s_movk_i32 s6, 0x3f50
	v_cmp_gt_i32_e32 vcc, s6, v144
	v_and_b32_e32 v6, 0x7ff, v26
	v_add_u32_e32 v7, 0xffffc0b0, v144
	v_cndmask_b32_e32 v6, v7, v6, vcc
	v_ashrrev_i32_e32 v7, 31, v6
	v_lshlrev_b64 v[6:7], 10, v[6:7]
	v_lshl_add_u64 v[6:7], v[136:137], 0, v[6:7]
	global_load_dwordx4 v[28:31], v[6:7], off offset:48
	global_load_dwordx4 v[32:35], v[6:7], off offset:32
	global_load_dwordx4 v[36:39], v[6:7], off offset:16
	global_load_dwordx4 v[40:43], v[6:7], off
	s_waitcnt vmcnt(1)
	v_mov_b32_e32 v10, v37
	v_mov_b32_e32 v11, v39
	s_waitcnt vmcnt(0)
	v_mov_b32_e32 v16, v41
	v_mov_b32_e32 v17, v43
	v_mov_b32_e32 v41, v42
	v_mov_b32_e32 v37, v38
	v_pk_mul_f32 v[14:15], v[8:9], v[10:11]
	v_pk_mul_f32 v[6:7], v[2:3], v[16:17]
	v_pk_mul_f32 v[8:9], v[8:9], v[36:37]
	v_pk_mul_f32 v[2:3], v[2:3], v[40:41]
	v_pk_fma_f32 v[6:7], v[24:25], v[40:41], v[6:7] neg_lo:[0,0,1] neg_hi:[0,0,1]
	v_pk_fma_f32 v[14:15], v[20:21], v[36:37], v[14:15] neg_lo:[0,0,1] neg_hi:[0,0,1]
	v_pk_fma_f32 v[2:3], v[24:25], v[16:17], v[2:3]
	v_pk_fma_f32 v[8:9], v[20:21], v[10:11], v[8:9]
	v_mov_b32_e32 v20, v29
	v_mov_b32_e32 v21, v31
	v_mov_b32_e32 v24, v33
	v_mov_b32_e32 v25, v35
	v_mov_b32_e32 v33, v34
	v_mov_b32_e32 v29, v30
	v_pk_mul_f32 v[16:17], v[12:13], v[20:21]
	v_pk_mul_f32 v[10:11], v[4:5], v[24:25]
	v_pk_mul_f32 v[12:13], v[12:13], v[28:29]
	v_pk_mul_f32 v[4:5], v[4:5], v[32:33]
	v_pk_fma_f32 v[10:11], v[22:23], v[32:33], v[10:11] neg_lo:[0,0,1] neg_hi:[0,0,1]
	v_pk_fma_f32 v[16:17], v[18:19], v[28:29], v[16:17] neg_lo:[0,0,1] neg_hi:[0,0,1]
	v_pk_fma_f32 v[4:5], v[22:23], v[24:25], v[4:5]
	v_pk_fma_f32 v[12:13], v[18:19], v[20:21], v[12:13]
	v_mov_b32_e32 v28, v114
	v_mov_b32_e32 v29, v114
	v_pk_mul_f32 v[20:21], v[28:29], v[14:15]
	v_pk_mul_f32 v[24:25], v[114:115], v[6:7]
	v_pk_mul_f32 v[8:9], v[28:29], v[8:9]
	v_pk_mul_f32 v[2:3], v[114:115], v[2:3]
	v_pk_mul_f32 v[18:19], v[28:29], v[16:17]
	v_pk_mul_f32 v[22:23], v[114:115], v[10:11]
	v_pk_mul_f32 v[12:13], v[28:29], v[12:13]
	v_pk_mul_f32 v[4:5], v[114:115], v[4:5]
.LBB0_351:
	v_mov_b64_e32 v[6:7], s[8:9]
	v_mad_i64_i32 v[6:7], s[6:7], v26, s33, v[6:7]
	v_lshl_add_u64 v[6:7], v[142:143], 1, v[6:7]
	s_andn2_b64 vcc, exec, s[4:5]
	s_mov_b64 s[4:5], -1
	v_cvt_pk_bf16_f32 v14, v24, v25
	v_cvt_pk_bf16_f32 v15, v20, v21
	v_cvt_pk_bf16_f32 v16, v22, v23
	v_cvt_pk_bf16_f32 v17, v18, v19
	global_store_dwordx4 v[6:7], v[14:17], off nt
	v_cvt_pk_bf16_f32 v2, v2, v3
	v_cvt_pk_bf16_f32 v3, v8, v9
	v_cvt_pk_bf16_f32 v4, v4, v5
	v_cvt_pk_bf16_f32 v5, v12, v13
	global_store_dwordx4 v[6:7], v[2:5], off offset:256 nt
	s_cbranch_vccnz .LBB0_328
	s_andn2_b64 vcc, exec, s[10:11]
	s_cbranch_vccnz .LBB0_327
	s_barrier
	s_branch .LBB0_327

; __device__ __forceinline__ unsigned pkh(float a, float b) { const f2v_t f = {a, b}; const h2v_t h = __builtin_convertvector(f, h2v_t); return __builtin_bit_cast(unsigned, h); }
; __device__ __forceinline__ float hlo(unsigned w) { return (float)__builtin_bit_cast(_Float16, (unsigned short)(w & 0xffffu)); }
; __device__ __forceinline__ float hhi(unsigned w) { return (float)__builtin_bit_cast(_Float16, (unsigned short)(w >> 16)); }
; __device__ __forceinline__ u32x4 pk8h(const f32x4 a, const f32x4 b) { u32x4 w; w.x = pkh(a[0], a[1]); w.y = pkh(a[2], a[3]); w.z = pkh(b[0], b[1]); w.w = pkh(b[2], b[3]); return w; }
; __device__ __forceinline__ f32x4 h4lo(const u32x4 w) { return (f32x4){hlo(w.x), hhi(w.x), hlo(w.y), hhi(w.y)}; }
; __device__ __forceinline__ f32x4 h4hi(const u32x4 w) { return (f32x4){hlo(w.z), hhi(w.z), hlo(w.w), hhi(w.w)}; }
;     __device__ __forceinline__ void operator()(const f32x4 (&acc)[2][2][4][2], const Unit& u, int wr, int wc, int fr, int fq) const {
;     ...
;         for (int ai = 0; ai < 2; ++ai) {
;             u32x4 y[4][2];
; #pragma unroll
;             for (int m = 0; m < 4; ++m) { const bf16_t* yp = Y + (size_t)(row0 + ai * HALF + m * 16) * 4096 + col0; y[m][0] = *(const u32x4*)yp; y[m][1] = *(const u32x4*)(yp + HALF); }
; #pragma unroll
;             for (int m = 0; m < 4; ++m) { bf16_t* rowp = X + (size_t)(row0 + ai * HALF + m * 16) * 4096 + col0;
; #pragma unroll
;                 for (int bj = 0; bj < 2; ++bj) *(u32x4*)(rowp + bj * HALF) = pk8h(h4lo(y[m][bj]) * alpha + acc[ai][bj][m][0], h4hi(y[m][bj]) * alpha + acc[ai][bj][m][1]); }
;             asm volatile("" ::: "memory");
.LBB0_919:
	v_lshl_or_b32 v132, s68, 8, v177
	v_lshl_add_u32 v130, s69, 8, v1
	v_ashrrev_i32_e32 v133, 31, v132
	v_lshlrev_b64 v[164:165], 1, v[132:133]
	v_ashrrev_i32_e32 v131, 31, v130
	v_lshl_add_u64 v[166:167], s[14:15], 0, v[164:165]
	v_lshlrev_b64 v[168:169], 13, v[130:131]
	v_lshl_add_u64 v[132:133], v[166:167], 0, v[168:169]
	global_load_dwordx4 v[198:201], v[132:133], off
	global_load_dwordx4 v[202:205], v[132:133], off offset:256
	v_or_b32_e32 v132, 16, v130
	v_ashrrev_i32_e32 v133, 31, v132
	v_lshlrev_b64 v[174:175], 13, v[132:133]
	v_lshl_add_u64 v[132:133], v[166:167], 0, v[174:175]
	global_load_dwordx4 v[150:153], v[132:133], off
	global_load_dwordx4 v[146:149], v[132:133], off offset:256
	v_or_b32_e32 v132, 32, v130
	v_ashrrev_i32_e32 v133, 31, v132
	v_lshlrev_b64 v[172:173], 13, v[132:133]
	v_lshl_add_u64 v[132:133], v[166:167], 0, v[172:173]
	global_load_dwordx4 v[142:145], v[132:133], off
	global_load_dwordx4 v[138:141], v[132:133], off offset:256
	v_or_b32_e32 v130, 48, v130
	v_ashrrev_i32_e32 v131, 31, v130
	v_lshlrev_b64 v[170:171], 13, v[130:131]
	v_lshl_add_u64 v[130:131], v[166:167], 0, v[170:171]
	global_load_dwordx4 v[134:137], v[130:131], off
	s_nop 0
	global_load_dwordx4 v[130:133], v[130:131], off offset:256
	v_lshl_add_u64 v[180:181], s[10:11], 0, v[168:169]
	v_lshl_add_u64 v[180:181], v[180:181], 0, v[164:165]
	s_mov_b64 s[30:31], 0x100000
	s_mov_b64 s[50:51], -1
	s_andn2_b64 vcc, exec, s[6:7]
	s_waitcnt vmcnt(0)
	v_cvt_f32_f16_e32 v206, v198
	v_cvt_f32_f16_sdwa v207, v198 dst_sel:DWORD dst_unused:UNUSED_PAD src0_sel:WORD_1
	v_cvt_f32_f16_e32 v198, v199
	v_cvt_f32_f16_sdwa v199, v199 dst_sel:DWORD dst_unused:UNUSED_PAD src0_sel:WORD_1
	v_pk_fma_f32 v[126:127], v[206:207], s[90:91], v[126:127] op_sel_hi:[1,0,1]
	v_pk_fma_f32 v[128:129], v[198:199], s[90:91], v[128:129] op_sel_hi:[1,0,1]
	v_cvt_f32_f16_e32 v198, v200
	v_cvt_f32_f16_sdwa v199, v200 dst_sel:DWORD dst_unused:UNUSED_PAD src0_sel:WORD_1
	v_cvt_f32_f16_e32 v200, v201
	v_cvt_f32_f16_sdwa v201, v201 dst_sel:DWORD dst_unused:UNUSED_PAD src0_sel:WORD_1
	v_pk_fma_f32 v[200:201], v[200:201], s[90:91], v[124:125] op_sel_hi:[1,0,1]
	v_pk_fma_f32 v[124:125], v[198:199], s[90:91], v[122:123] op_sel_hi:[1,0,1]
	v_cvt_pk_f16_f32 v122, v126, v127
	v_cvt_pk_f16_f32 v123, v128, v129
	v_cvt_pk_f16_f32 v124, v124, v125
	v_cvt_pk_f16_f32 v125, v200, v201
	global_store_dwordx4 v[180:181], v[122:125], off nt
	s_nop 1
	v_cvt_f32_f16_e32 v122, v202
	v_cvt_f32_f16_sdwa v123, v202 dst_sel:DWORD dst_unused:UNUSED_PAD src0_sel:WORD_1
	v_cvt_f32_f16_e32 v124, v203
	v_cvt_f32_f16_sdwa v125, v203 dst_sel:DWORD dst_unused:UNUSED_PAD src0_sel:WORD_1
	v_pk_fma_f32 v[118:119], v[122:123], s[90:91], v[118:119] op_sel_hi:[1,0,1]
	v_cvt_f32_f16_e32 v122, v204
	v_pk_fma_f32 v[120:121], v[124:125], s[90:91], v[120:121] op_sel_hi:[1,0,1]
	v_cvt_f32_f16_sdwa v123, v204 dst_sel:DWORD dst_unused:UNUSED_PAD src0_sel:WORD_1
	v_cvt_f32_f16_e32 v124, v205
	v_cvt_f32_f16_sdwa v125, v205 dst_sel:DWORD dst_unused:UNUSED_PAD src0_sel:WORD_1
	v_pk_fma_f32 v[124:125], v[124:125], s[90:91], v[116:117] op_sel_hi:[1,0,1]
	v_pk_fma_f32 v[116:117], v[122:123], s[90:91], v[114:115] op_sel_hi:[1,0,1]
	v_cvt_pk_f16_f32 v114, v118, v119
	v_cvt_pk_f16_f32 v115, v120, v121
	v_cvt_pk_f16_f32 v116, v116, v117
	v_cvt_pk_f16_f32 v117, v124, v125
	global_store_dwordx4 v[180:181], v[114:117], off offset:256 nt
	v_cvt_f32_f16_e32 v118, v151
	v_cvt_f32_f16_sdwa v119, v151 dst_sel:DWORD dst_unused:UNUSED_PAD src0_sel:WORD_1
	v_cvt_f32_f16_e32 v116, v150
	v_cvt_f32_f16_sdwa v117, v150 dst_sel:DWORD dst_unused:UNUSED_PAD src0_sel:WORD_1
	v_lshl_add_u64 v[114:115], s[10:11], 0, v[174:175]
	v_pk_fma_f32 v[112:113], v[118:119], s[90:91], v[112:113] op_sel_hi:[1,0,1]
	v_cvt_f32_f16_e32 v118, v153
	v_pk_fma_f32 v[110:111], v[116:117], s[90:91], v[110:111] op_sel_hi:[1,0,1]
	v_cvt_f32_f16_e32 v116, v152
	v_cvt_f32_f16_sdwa v117, v152 dst_sel:DWORD dst_unused:UNUSED_PAD src0_sel:WORD_1
	v_cvt_f32_f16_sdwa v119, v153 dst_sel:DWORD dst_unused:UNUSED_PAD src0_sel:WORD_1
	v_lshl_add_u64 v[114:115], v[114:115], 0, v[164:165]
	v_pk_fma_f32 v[118:119], v[118:119], s[90:91], v[108:109] op_sel_hi:[1,0,1]
	v_pk_fma_f32 v[108:109], v[116:117], s[90:91], v[106:107] op_sel_hi:[1,0,1]
	v_cvt_pk_f16_f32 v106, v110, v111
	v_cvt_pk_f16_f32 v107, v112, v113
	v_cvt_pk_f16_f32 v108, v108, v109
	v_cvt_pk_f16_f32 v109, v118, v119
	global_store_dwordx4 v[114:115], v[106:109], off nt
	s_nop 1
	v_cvt_f32_f16_e32 v106, v146
	v_cvt_f32_f16_sdwa v107, v146 dst_sel:DWORD dst_unused:UNUSED_PAD src0_sel:WORD_1
	v_cvt_f32_f16_e32 v108, v147
	v_cvt_f32_f16_sdwa v109, v147 dst_sel:DWORD dst_unused:UNUSED_PAD src0_sel:WORD_1
	v_pk_fma_f32 v[102:103], v[106:107], s[90:91], v[102:103] op_sel_hi:[1,0,1]
	v_cvt_f32_f16_e32 v106, v148
	v_pk_fma_f32 v[104:105], v[108:109], s[90:91], v[104:105] op_sel_hi:[1,0,1]
	v_cvt_f32_f16_sdwa v107, v148 dst_sel:DWORD dst_unused:UNUSED_PAD src0_sel:WORD_1
	v_cvt_f32_f16_e32 v108, v149
	v_cvt_f32_f16_sdwa v109, v149 dst_sel:DWORD dst_unused:UNUSED_PAD src0_sel:WORD_1
	v_pk_fma_f32 v[108:109], v[108:109], s[90:91], v[96:97] op_sel_hi:[1,0,1]
	v_pk_fma_f32 v[96:97], v[106:107], s[90:91], v[94:95] op_sel_hi:[1,0,1]
	v_cvt_pk_f16_f32 v94, v102, v103
	v_cvt_pk_f16_f32 v95, v104, v105
	v_cvt_pk_f16_f32 v96, v96, v97
	v_cvt_pk_f16_f32 v97, v108, v109
	global_store_dwordx4 v[114:115], v[94:97], off offset:256 nt
	v_cvt_f32_f16_e32 v102, v143
	v_cvt_f32_f16_sdwa v103, v143 dst_sel:DWORD dst_unused:UNUSED_PAD src0_sel:WORD_1
	v_cvt_f32_f16_e32 v96, v142
	v_cvt_f32_f16_sdwa v97, v142 dst_sel:DWORD dst_unused:UNUSED_PAD src0_sel:WORD_1
; __device__ __forceinline__ unsigned pkh(float a, float b) { const f2v_t f = {a, b}; const h2v_t h = __builtin_convertvector(f, h2v_t); return __builtin_bit_cast(unsigned, h); }
; __device__ __forceinline__ float hlo(unsigned w) { return (float)__builtin_bit_cast(_Float16, (unsigned short)(w & 0xffffu)); }
; __device__ __forceinline__ float hhi(unsigned w) { return (float)__builtin_bit_cast(_Float16, (unsigned short)(w >> 16)); }
; __device__ __forceinline__ u32x4 pk8h(const f32x4 a, const f32x4 b) { u32x4 w; w.x = pkh(a[0], a[1]); w.y = pkh(a[2], a[3]); w.z = pkh(b[0], b[1]); w.w = pkh(b[2], b[3]); return w; }
; __device__ __forceinline__ f32x4 h4lo(const u32x4 w) { return (f32x4){hlo(w.x), hhi(w.x), hlo(w.y), hhi(w.y)}; }
; __device__ __forceinline__ f32x4 h4hi(const u32x4 w) { return (f32x4){hlo(w.z), hhi(w.z), hlo(w.w), hhi(w.w)}; }
;     __device__ __forceinline__ void operator()(const f32x4 (&acc)[2][2][4][2], const Unit& u, int wr, int wc, int fr, int fq) const {
;     ...
;         for (int ai = 0; ai < 2; ++ai) {
;             u32x4 y[4][2];
; #pragma unroll
;             for (int m = 0; m < 4; ++m) { const bf16_t* yp = Y + (size_t)(row0 + ai * HALF + m * 16) * 4096 + col0; y[m][0] = *(const u32x4*)yp; y[m][1] = *(const u32x4*)(yp + HALF); }
; #pragma unroll
;             for (int m = 0; m < 4; ++m) { bf16_t* rowp = X + (size_t)(row0 + ai * HALF + m * 16) * 4096 + col0;
; #pragma unroll
;                 for (int bj = 0; bj < 2; ++bj) *(u32x4*)(rowp + bj * HALF) = pk8h(h4lo(y[m][bj]) * alpha + acc[ai][bj][m][0], h4hi(y[m][bj]) * alpha + acc[ai][bj][m][1]); }
;             asm volatile("" ::: "memory");
	v_lshl_add_u64 v[94:95], s[10:11], 0, v[172:173]
	v_pk_fma_f32 v[100:101], v[102:103], s[90:91], v[100:101] op_sel_hi:[1,0,1]
	v_cvt_f32_f16_e32 v102, v145
	v_pk_fma_f32 v[96:97], v[96:97], s[90:91], v[98:99] op_sel_hi:[1,0,1]
	v_cvt_f32_f16_e32 v98, v144
	v_cvt_f32_f16_sdwa v99, v144 dst_sel:DWORD dst_unused:UNUSED_PAD src0_sel:WORD_1
	v_cvt_f32_f16_sdwa v103, v145 dst_sel:DWORD dst_unused:UNUSED_PAD src0_sel:WORD_1
	v_lshl_add_u64 v[94:95], v[94:95], 0, v[164:165]
	v_pk_fma_f32 v[102:103], v[102:103], s[90:91], v[92:93] op_sel_hi:[1,0,1]
	v_pk_fma_f32 v[92:93], v[98:99], s[90:91], v[90:91] op_sel_hi:[1,0,1]
	v_cvt_pk_f16_f32 v90, v96, v97
	v_cvt_pk_f16_f32 v91, v100, v101
	v_cvt_pk_f16_f32 v92, v92, v93
	v_cvt_pk_f16_f32 v93, v102, v103
	global_store_dwordx4 v[94:95], v[90:93], off nt
	v_lshl_add_u64 v[100:101], v[168:169], 0, s[30:31]
	s_mov_b64 s[30:31], 0x120000
	v_cvt_f32_f16_e32 v90, v138
	v_cvt_f32_f16_sdwa v91, v138 dst_sel:DWORD dst_unused:UNUSED_PAD src0_sel:WORD_1
	v_cvt_f32_f16_e32 v92, v139
	v_cvt_f32_f16_sdwa v93, v139 dst_sel:DWORD dst_unused:UNUSED_PAD src0_sel:WORD_1
	v_lshl_add_u64 v[102:103], v[168:169], 0, s[30:31]
	v_pk_fma_f32 v[86:87], v[90:91], s[90:91], v[86:87] op_sel_hi:[1,0,1]
	v_cvt_f32_f16_e32 v90, v140
	v_pk_fma_f32 v[88:89], v[92:93], s[90:91], v[88:89] op_sel_hi:[1,0,1]
	v_cvt_f32_f16_sdwa v91, v140 dst_sel:DWORD dst_unused:UNUSED_PAD src0_sel:WORD_1
	v_cvt_f32_f16_e32 v92, v141
	v_cvt_f32_f16_sdwa v93, v141 dst_sel:DWORD dst_unused:UNUSED_PAD src0_sel:WORD_1
	s_mov_b64 s[30:31], 0x140000
	v_lshl_add_u64 v[104:105], v[168:169], 0, s[30:31]
	s_mov_b64 s[30:31], 0x160000
	v_pk_fma_f32 v[92:93], v[92:93], s[90:91], v[80:81] op_sel_hi:[1,0,1]
	v_pk_fma_f32 v[80:81], v[90:91], s[90:91], v[78:79] op_sel_hi:[1,0,1]
	v_cvt_pk_f16_f32 v78, v86, v87
	v_cvt_pk_f16_f32 v79, v88, v89
	v_cvt_pk_f16_f32 v80, v80, v81
	v_cvt_pk_f16_f32 v81, v92, v93
	global_store_dwordx4 v[94:95], v[78:81], off offset:256 nt
	v_cvt_f32_f16_e32 v86, v135
	v_cvt_f32_f16_sdwa v87, v135 dst_sel:DWORD dst_unused:UNUSED_PAD src0_sel:WORD_1
	v_cvt_f32_f16_e32 v80, v134
	v_cvt_f32_f16_sdwa v81, v134 dst_sel:DWORD dst_unused:UNUSED_PAD src0_sel:WORD_1
	v_lshl_add_u64 v[78:79], s[10:11], 0, v[170:171]
	v_pk_fma_f32 v[84:85], v[86:87], s[90:91], v[84:85] op_sel_hi:[1,0,1]
	v_cvt_f32_f16_e32 v86, v137
	v_pk_fma_f32 v[80:81], v[80:81], s[90:91], v[82:83] op_sel_hi:[1,0,1]
	v_cvt_f32_f16_e32 v82, v136
	v_cvt_f32_f16_sdwa v83, v136 dst_sel:DWORD dst_unused:UNUSED_PAD src0_sel:WORD_1
	v_cvt_f32_f16_sdwa v87, v137 dst_sel:DWORD dst_unused:UNUSED_PAD src0_sel:WORD_1
	v_lshl_add_u64 v[78:79], v[78:79], 0, v[164:165]
	v_pk_fma_f32 v[86:87], v[86:87], s[90:91], v[76:77] op_sel_hi:[1,0,1]
	v_pk_fma_f32 v[76:77], v[82:83], s[90:91], v[74:75] op_sel_hi:[1,0,1]
	v_cvt_pk_f16_f32 v74, v80, v81
	v_cvt_pk_f16_f32 v75, v84, v85
	v_cvt_pk_f16_f32 v76, v76, v77
	v_cvt_pk_f16_f32 v77, v86, v87
	global_store_dwordx4 v[78:79], v[74:77], off nt
	v_lshl_add_u64 v[82:83], v[168:169], 0, s[30:31]
	s_nop 0
	v_cvt_f32_f16_e32 v74, v130
	v_cvt_f32_f16_sdwa v75, v130 dst_sel:DWORD dst_unused:UNUSED_PAD src0_sel:WORD_1
	v_cvt_f32_f16_e32 v76, v131
	v_cvt_f32_f16_sdwa v77, v131 dst_sel:DWORD dst_unused:UNUSED_PAD src0_sel:WORD_1
	v_pk_fma_f32 v[70:71], v[74:75], s[90:91], v[70:71] op_sel_hi:[1,0,1]
	v_cvt_f32_f16_e32 v74, v132
	v_pk_fma_f32 v[72:73], v[76:77], s[90:91], v[72:73] op_sel_hi:[1,0,1]
	v_cvt_f32_f16_sdwa v75, v132 dst_sel:DWORD dst_unused:UNUSED_PAD src0_sel:WORD_1
	v_cvt_f32_f16_e32 v76, v133
	v_cvt_f32_f16_sdwa v77, v133 dst_sel:DWORD dst_unused:UNUSED_PAD src0_sel:WORD_1
	v_pk_fma_f32 v[76:77], v[76:77], s[90:91], v[68:69] op_sel_hi:[1,0,1]
	v_pk_fma_f32 v[68:69], v[74:75], s[90:91], v[66:67] op_sel_hi:[1,0,1]
	v_cvt_pk_f16_f32 v66, v70, v71
	v_cvt_pk_f16_f32 v67, v72, v73
	v_cvt_pk_f16_f32 v68, v68, v69
	v_cvt_pk_f16_f32 v69, v76, v77
	global_store_dwordx4 v[78:79], v[66:69], off offset:256 nt
	s_nop 1
	v_lshl_add_u64 v[66:67], v[166:167], 0, v[100:101]
	global_load_dwordx4 v[84:87], v[66:67], off
	global_load_dwordx4 v[88:91], v[66:67], off offset:256
	v_lshl_add_u64 v[66:67], v[166:167], 0, v[102:103]
	global_load_dwordx4 v[92:95], v[66:67], off
	global_load_dwordx4 v[96:99], v[66:67], off offset:256
	v_lshl_add_u64 v[66:67], v[166:167], 0, v[104:105]
	global_load_dwordx4 v[78:81], v[66:67], off
	global_load_dwordx4 v[74:77], v[66:67], off offset:256
	v_lshl_add_u64 v[66:67], v[166:167], 0, v[82:83]
	global_load_dwordx4 v[70:73], v[66:67], off
	s_nop 0
	global_load_dwordx4 v[66:69], v[66:67], off offset:256
	v_lshl_add_u64 v[100:101], s[10:11], 0, v[100:101]
	v_lshl_add_u64 v[100:101], v[100:101], 0, v[164:165]
	s_waitcnt vmcnt(7)
	v_cvt_f32_f16_e32 v106, v84
	v_cvt_f32_f16_sdwa v107, v84 dst_sel:DWORD dst_unused:UNUSED_PAD src0_sel:WORD_1
	v_cvt_f32_f16_e32 v84, v85
	v_cvt_f32_f16_sdwa v85, v85 dst_sel:DWORD dst_unused:UNUSED_PAD src0_sel:WORD_1
	v_pk_fma_f32 v[62:63], v[106:107], s[90:91], v[62:63] op_sel_hi:[1,0,1]
	v_pk_fma_f32 v[64:65], v[84:85], s[90:91], v[64:65] op_sel_hi:[1,0,1]
	v_cvt_f32_f16_e32 v84, v86
	v_cvt_f32_f16_sdwa v85, v86 dst_sel:DWORD dst_unused:UNUSED_PAD src0_sel:WORD_1
	v_cvt_f32_f16_e32 v86, v87
	v_cvt_f32_f16_sdwa v87, v87 dst_sel:DWORD dst_unused:UNUSED_PAD src0_sel:WORD_1
	v_pk_fma_f32 v[86:87], v[86:87], s[90:91], v[60:61] op_sel_hi:[1,0,1]
	v_pk_fma_f32 v[60:61], v[84:85], s[90:91], v[58:59] op_sel_hi:[1,0,1]
	v_cvt_pk_f16_f32 v58, v62, v63
	v_cvt_pk_f16_f32 v59, v64, v65
	v_cvt_pk_f16_f32 v60, v60, v61
	v_cvt_pk_f16_f32 v61, v86, v87
	global_store_dwordx4 v[100:101], v[58:61], off nt
	s_waitcnt vmcnt(7)
; __device__ __forceinline__ unsigned pkh(float a, float b) { const f2v_t f = {a, b}; const h2v_t h = __builtin_convertvector(f, h2v_t); return __builtin_bit_cast(unsigned, h); }
; __device__ __forceinline__ float hlo(unsigned w) { return (float)__builtin_bit_cast(_Float16, (unsigned short)(w & 0xffffu)); }
; __device__ __forceinline__ float hhi(unsigned w) { return (float)__builtin_bit_cast(_Float16, (unsigned short)(w >> 16)); }
; __device__ __forceinline__ u32x4 pk8h(const f32x4 a, const f32x4 b) { u32x4 w; w.x = pkh(a[0], a[1]); w.y = pkh(a[2], a[3]); w.z = pkh(b[0], b[1]); w.w = pkh(b[2], b[3]); return w; }
; __device__ __forceinline__ f32x4 h4lo(const u32x4 w) { return (f32x4){hlo(w.x), hhi(w.x), hlo(w.y), hhi(w.y)}; }
; __device__ __forceinline__ f32x4 h4hi(const u32x4 w) { return (f32x4){hlo(w.z), hhi(w.z), hlo(w.w), hhi(w.w)}; }
;     __device__ __forceinline__ void operator()(const f32x4 (&acc)[2][2][4][2], const Unit& u, int wr, int wc, int fr, int fq) const {
;     ...
;         for (int ai = 0; ai < 2; ++ai) {
;             u32x4 y[4][2];
; #pragma unroll
;             for (int m = 0; m < 4; ++m) { const bf16_t* yp = Y + (size_t)(row0 + ai * HALF + m * 16) * 4096 + col0; y[m][0] = *(const u32x4*)yp; y[m][1] = *(const u32x4*)(yp + HALF); }
; #pragma unroll
;             for (int m = 0; m < 4; ++m) { bf16_t* rowp = X + (size_t)(row0 + ai * HALF + m * 16) * 4096 + col0;
; #pragma unroll
;                 for (int bj = 0; bj < 2; ++bj) *(u32x4*)(rowp + bj * HALF) = pk8h(h4lo(y[m][bj]) * alpha + acc[ai][bj][m][0], h4hi(y[m][bj]) * alpha + acc[ai][bj][m][1]); }
;             asm volatile("" ::: "memory");
	s_nop 0
	v_cvt_f32_f16_e32 v58, v88
	v_cvt_f32_f16_sdwa v59, v88 dst_sel:DWORD dst_unused:UNUSED_PAD src0_sel:WORD_1
	v_cvt_f32_f16_e32 v60, v89
	v_cvt_f32_f16_sdwa v61, v89 dst_sel:DWORD dst_unused:UNUSED_PAD src0_sel:WORD_1
	v_pk_fma_f32 v[54:55], v[58:59], s[90:91], v[54:55] op_sel_hi:[1,0,1]
	v_cvt_f32_f16_e32 v58, v90
	v_pk_fma_f32 v[56:57], v[60:61], s[90:91], v[56:57] op_sel_hi:[1,0,1]
	v_cvt_f32_f16_sdwa v59, v90 dst_sel:DWORD dst_unused:UNUSED_PAD src0_sel:WORD_1
	v_cvt_f32_f16_e32 v60, v91
	v_cvt_f32_f16_sdwa v61, v91 dst_sel:DWORD dst_unused:UNUSED_PAD src0_sel:WORD_1
	v_pk_fma_f32 v[60:61], v[60:61], s[90:91], v[48:49] op_sel_hi:[1,0,1]
	v_pk_fma_f32 v[48:49], v[58:59], s[90:91], v[46:47] op_sel_hi:[1,0,1]
	v_cvt_pk_f16_f32 v46, v54, v55
	v_cvt_pk_f16_f32 v47, v56, v57
	v_cvt_pk_f16_f32 v48, v48, v49
	v_cvt_pk_f16_f32 v49, v60, v61
	global_store_dwordx4 v[100:101], v[46:49], off offset:256 nt
	s_waitcnt vmcnt(7)
	v_cvt_f32_f16_e32 v54, v93
	v_cvt_f32_f16_sdwa v55, v93 dst_sel:DWORD dst_unused:UNUSED_PAD src0_sel:WORD_1
	v_cvt_f32_f16_e32 v48, v92
	v_cvt_f32_f16_sdwa v49, v92 dst_sel:DWORD dst_unused:UNUSED_PAD src0_sel:WORD_1
	v_lshl_add_u64 v[46:47], s[10:11], 0, v[102:103]
	v_pk_fma_f32 v[52:53], v[54:55], s[90:91], v[52:53] op_sel_hi:[1,0,1]
	v_cvt_f32_f16_e32 v54, v95
	v_pk_fma_f32 v[48:49], v[48:49], s[90:91], v[50:51] op_sel_hi:[1,0,1]
	v_cvt_f32_f16_e32 v50, v94
	v_cvt_f32_f16_sdwa v51, v94 dst_sel:DWORD dst_unused:UNUSED_PAD src0_sel:WORD_1
	v_cvt_f32_f16_sdwa v55, v95 dst_sel:DWORD dst_unused:UNUSED_PAD src0_sel:WORD_1
	v_lshl_add_u64 v[46:47], v[46:47], 0, v[164:165]
	v_pk_fma_f32 v[54:55], v[54:55], s[90:91], v[44:45] op_sel_hi:[1,0,1]
	v_pk_fma_f32 v[44:45], v[50:51], s[90:91], v[42:43] op_sel_hi:[1,0,1]
	v_cvt_pk_f16_f32 v42, v48, v49
	v_cvt_pk_f16_f32 v43, v52, v53
	v_cvt_pk_f16_f32 v44, v44, v45
	v_cvt_pk_f16_f32 v45, v54, v55
	global_store_dwordx4 v[46:47], v[42:45], off nt
	s_waitcnt vmcnt(7)
	s_nop 0
	v_cvt_f32_f16_e32 v42, v96
	v_cvt_f32_f16_sdwa v43, v96 dst_sel:DWORD dst_unused:UNUSED_PAD src0_sel:WORD_1
	v_cvt_f32_f16_e32 v44, v97
	v_cvt_f32_f16_sdwa v45, v97 dst_sel:DWORD dst_unused:UNUSED_PAD src0_sel:WORD_1
	v_pk_fma_f32 v[38:39], v[42:43], s[90:91], v[38:39] op_sel_hi:[1,0,1]
	v_cvt_f32_f16_e32 v42, v98
	v_pk_fma_f32 v[40:41], v[44:45], s[90:91], v[40:41] op_sel_hi:[1,0,1]
	v_cvt_f32_f16_sdwa v43, v98 dst_sel:DWORD dst_unused:UNUSED_PAD src0_sel:WORD_1
	v_cvt_f32_f16_e32 v44, v99
	v_cvt_f32_f16_sdwa v45, v99 dst_sel:DWORD dst_unused:UNUSED_PAD src0_sel:WORD_1
	v_pk_fma_f32 v[44:45], v[44:45], s[90:91], v[32:33] op_sel_hi:[1,0,1]
	v_pk_fma_f32 v[32:33], v[42:43], s[90:91], v[30:31] op_sel_hi:[1,0,1]
	v_cvt_pk_f16_f32 v30, v38, v39
	v_cvt_pk_f16_f32 v31, v40, v41
	v_cvt_pk_f16_f32 v32, v32, v33
	v_cvt_pk_f16_f32 v33, v44, v45
	global_store_dwordx4 v[46:47], v[30:33], off offset:256 nt
	s_waitcnt vmcnt(7)
	v_cvt_f32_f16_e32 v38, v79
	v_cvt_f32_f16_sdwa v39, v79 dst_sel:DWORD dst_unused:UNUSED_PAD src0_sel:WORD_1
	v_cvt_f32_f16_e32 v32, v78
	v_cvt_f32_f16_sdwa v33, v78 dst_sel:DWORD dst_unused:UNUSED_PAD src0_sel:WORD_1
	v_lshl_add_u64 v[30:31], s[10:11], 0, v[104:105]
	v_pk_fma_f32 v[36:37], v[38:39], s[90:91], v[36:37] op_sel_hi:[1,0,1]
	v_cvt_f32_f16_e32 v38, v81
	v_pk_fma_f32 v[32:33], v[32:33], s[90:91], v[34:35] op_sel_hi:[1,0,1]
	v_cvt_f32_f16_e32 v34, v80
	v_cvt_f32_f16_sdwa v35, v80 dst_sel:DWORD dst_unused:UNUSED_PAD src0_sel:WORD_1
	v_cvt_f32_f16_sdwa v39, v81 dst_sel:DWORD dst_unused:UNUSED_PAD src0_sel:WORD_1
	v_lshl_add_u64 v[30:31], v[30:31], 0, v[164:165]
	v_pk_fma_f32 v[38:39], v[38:39], s[90:91], v[28:29] op_sel_hi:[1,0,1]
	v_pk_fma_f32 v[28:29], v[34:35], s[90:91], v[26:27] op_sel_hi:[1,0,1]
	v_cvt_pk_f16_f32 v26, v32, v33
	v_cvt_pk_f16_f32 v27, v36, v37
	v_cvt_pk_f16_f32 v28, v28, v29
	v_cvt_pk_f16_f32 v29, v38, v39
	global_store_dwordx4 v[30:31], v[26:29], off nt
	s_waitcnt vmcnt(7)
	s_nop 0
	v_cvt_f32_f16_e32 v26, v74
	v_cvt_f32_f16_sdwa v27, v74 dst_sel:DWORD dst_unused:UNUSED_PAD src0_sel:WORD_1
	v_cvt_f32_f16_e32 v28, v75
	v_cvt_f32_f16_sdwa v29, v75 dst_sel:DWORD dst_unused:UNUSED_PAD src0_sel:WORD_1
	v_pk_fma_f32 v[22:23], v[26:27], s[90:91], v[22:23] op_sel_hi:[1,0,1]
	v_cvt_f32_f16_e32 v26, v76
	v_pk_fma_f32 v[24:25], v[28:29], s[90:91], v[24:25] op_sel_hi:[1,0,1]
	v_cvt_f32_f16_sdwa v27, v76 dst_sel:DWORD dst_unused:UNUSED_PAD src0_sel:WORD_1
	v_cvt_f32_f16_e32 v28, v77
	v_cvt_f32_f16_sdwa v29, v77 dst_sel:DWORD dst_unused:UNUSED_PAD src0_sel:WORD_1
	v_pk_fma_f32 v[28:29], v[28:29], s[90:91], v[16:17] op_sel_hi:[1,0,1]
	v_pk_fma_f32 v[16:17], v[26:27], s[90:91], v[14:15] op_sel_hi:[1,0,1]
	v_cvt_pk_f16_f32 v14, v22, v23
	v_cvt_pk_f16_f32 v15, v24, v25
	v_cvt_pk_f16_f32 v16, v16, v17
	v_cvt_pk_f16_f32 v17, v28, v29
	global_store_dwordx4 v[30:31], v[14:17], off offset:256 nt
	s_waitcnt vmcnt(7)
	v_cvt_f32_f16_e32 v22, v71
	v_cvt_f32_f16_sdwa v23, v71 dst_sel:DWORD dst_unused:UNUSED_PAD src0_sel:WORD_1
	v_cvt_f32_f16_e32 v16, v70
	v_cvt_f32_f16_sdwa v17, v70 dst_sel:DWORD dst_unused:UNUSED_PAD src0_sel:WORD_1
	v_lshl_add_u64 v[14:15], s[10:11], 0, v[82:83]
	v_pk_fma_f32 v[20:21], v[22:23], s[90:91], v[20:21] op_sel_hi:[1,0,1]
	v_cvt_f32_f16_e32 v22, v73
	v_pk_fma_f32 v[16:17], v[16:17], s[90:91], v[18:19] op_sel_hi:[1,0,1]
	v_cvt_f32_f16_e32 v18, v72
	v_cvt_f32_f16_sdwa v19, v72 dst_sel:DWORD dst_unused:UNUSED_PAD src0_sel:WORD_1
	v_cvt_f32_f16_sdwa v23, v73 dst_sel:DWORD dst_unused:UNUSED_PAD src0_sel:WORD_1
	v_lshl_add_u64 v[14:15], v[14:15], 0, v[164:165]
	v_pk_fma_f32 v[22:23], v[22:23], s[90:91], v[12:13] op_sel_hi:[1,0,1]
	v_pk_fma_f32 v[12:13], v[18:19], s[90:91], v[10:11] op_sel_hi:[1,0,1]
	v_cvt_pk_f16_f32 v10, v16, v17
	v_cvt_pk_f16_f32 v11, v20, v21
	v_cvt_pk_f16_f32 v12, v12, v13
	v_cvt_pk_f16_f32 v13, v22, v23
	global_store_dwordx4 v[14:15], v[10:13], off nt
	s_waitcnt vmcnt(7)
	s_nop 0
	v_cvt_f32_f16_e32 v10, v66
	v_cvt_f32_f16_sdwa v11, v66 dst_sel:DWORD dst_unused:UNUSED_PAD src0_sel:WORD_1
	v_cvt_f32_f16_e32 v12, v67
	v_cvt_f32_f16_sdwa v13, v67 dst_sel:DWORD dst_unused:UNUSED_PAD src0_sel:WORD_1
	v_pk_fma_f32 v[6:7], v[10:11], s[90:91], v[6:7] op_sel_hi:[1,0,1]
	v_cvt_f32_f16_e32 v10, v68
	v_pk_fma_f32 v[8:9], v[12:13], s[90:91], v[8:9] op_sel_hi:[1,0,1]
	v_cvt_f32_f16_sdwa v11, v68 dst_sel:DWORD dst_unused:UNUSED_PAD src0_sel:WORD_1
	v_cvt_f32_f16_e32 v12, v69
	v_cvt_f32_f16_sdwa v13, v69 dst_sel:DWORD dst_unused:UNUSED_PAD src0_sel:WORD_1
	v_pk_fma_f32 v[12:13], v[12:13], s[90:91], v[4:5] op_sel_hi:[1,0,1]
	v_pk_fma_f32 v[4:5], v[10:11], s[90:91], v[2:3] op_sel_hi:[1,0,1]
	v_cvt_pk_f16_f32 v2, v6, v7
	v_cvt_pk_f16_f32 v3, v8, v9
	v_cvt_pk_f16_f32 v4, v4, v5
	v_cvt_pk_f16_f32 v5, v12, v13
	global_store_dwordx4 v[14:15], v[2:5], off offset:256 nt
	s_cbranch_vccnz .LBB0_912
	s_andn2_b64 vcc, exec, s[8:9]
	s_cbranch_vccnz .LBB0_911
	s_barrier
	s_branch .LBB0_911

; __device__ __forceinline__ unsigned cvt_pk_bf16(float lo, float hi) { unsigned r; asm volatile("v_cvt_pk_bf16_f32 %0, %1, %2" : "=v"(r) : "v"(lo), "v"(hi)); return r; }
;     __device__ __forceinline__ void operator()(const i32x4 (&acc)[2][2][4][2], const Unit& u, int wr, int wc, int fr, int fq) const {
;     ...
;         const float wdq = __builtin_bit_cast(float, *wmax_bits) * (1.0f / 127.0f);
; #pragma unroll
;         for (int ai = 0; ai < 2; ++ai)
; #pragma unroll
;             for (int m = 0; m < 4; ++m) {
;                 const int row = row0 + ai * HALF + m * 16;
;                 const float f = rowinv[row] * wdq;
;                 bf16_t* rowp = H + (size_t)row * 11008 + col0;
;                 f32x4 h0, h1;
; #pragma unroll
;                 for (int j = 0; j < 4; ++j) {
;                     const float g0 = (float)acc[ai][0][m][0][j] * f, g1 = (float)acc[ai][0][m][1][j] * f;
;                     h0[j] = g0 * __builtin_amdgcn_rcpf(1.0f + __expf(-g0)) * ((float)acc[ai][1][m][0][j] * f);
;                     h1[j] = g1 * __builtin_amdgcn_rcpf(1.0f + __expf(-g1)) * ((float)acc[ai][1][m][1][j] * f);
;                 }
;                 u32x4 w; w.x = cvt_pk_bf16(h0[0], h0[1]); w.y = cvt_pk_bf16(h0[2], h0[3]); w.z = cvt_pk_bf16(h1[0], h1[1]); w.w = cvt_pk_bf16(h1[2], h1[3]);
;                 *(u32x4*)(rowp) = w;
;             }
.LBB0_1060:
	global_load_dword v234, v183, s[16:17]
	v_lshl_add_u32 v140, s71, 8, v1
	v_ashrrev_i32_e32 v141, 31, v140
	v_lshl_add_u64 v[142:143], v[140:141], 2, s[14:15]
	global_load_dword v226, v[142:143], off
	global_load_dword v227, v[142:143], off offset:64
	global_load_dword v228, v[142:143], off offset:128
	global_load_dword v229, v[142:143], off offset:192
	global_load_dword v230, v[142:143], off offset:512
	global_load_dword v231, v[142:143], off offset:576
	global_load_dword v232, v[142:143], off offset:640
	global_load_dword v233, v[142:143], off offset:704
	v_cvt_f32_i32_e32 v157, v126
	v_cvt_f32_i32_e32 v156, v122
	v_cvt_f32_i32_e32 v127, v127
	v_cvt_f32_i32_e32 v126, v123
	v_cvt_f32_i32_e32 v119, v119
	v_lshl_or_b32 v146, s70, 7, v152
	v_ashrrev_i32_e32 v147, 31, v146
	v_mov_b64_e32 v[144:145], s[10:11]
	v_mad_i64_i32 v[150:151], s[30:31], v140, s89, v[144:145]
	v_cvt_f32_i32_e32 v111, v111
	v_cvt_f32_i32_e32 v103, v103
	v_cvt_f32_i32_e32 v95, v95
	v_cvt_f32_i32_e32 v87, v87
	v_cvt_f32_i32_e32 v79, v79
	v_cvt_f32_i32_e32 v71, v71
	v_cvt_f32_i32_e32 v63, v63
	v_cvt_f32_i32_e32 v55, v55
	v_cvt_f32_i32_e32 v47, v47
	v_cvt_f32_i32_e32 v39, v39
	v_cvt_f32_i32_e32 v31, v31
	v_cvt_f32_i32_e32 v23, v23
	v_cvt_f32_i32_e32 v15, v15
	v_cvt_f32_i32_e32 v7, v7
	s_mov_b64 s[52:53], -1
	s_andn2_b64 vcc, exec, s[6:7]
	s_waitcnt vmcnt(8)
	v_mul_f32_e32 v154, 0x3c010204, v234
	s_waitcnt vmcnt(7)
	v_mul_f32_e32 v148, v154, v226
	v_pk_mul_f32 v[156:157], v[148:149], v[156:157] op_sel_hi:[0,1]
	v_mul_f32_e32 v122, 0xbfb8aa3b, v157
	v_exp_f32_e32 v122, v122
	s_nop 0
	v_add_f32_e32 v122, 1.0, v122
	v_rcp_f32_e32 v122, v122
	s_nop 0
	v_mul_f32_e32 v122, v157, v122
	v_mul_f32_e32 v141, v156, v122
	v_cvt_f32_i32_e32 v157, v118
	v_cvt_f32_i32_e32 v156, v114
	v_pk_mul_f32 v[122:123], v[148:149], v[126:127] op_sel_hi:[0,1]
	v_cvt_f32_i32_e32 v118, v115
	v_pk_mul_f32 v[156:157], v[148:149], v[156:157] op_sel_hi:[0,1]
	v_mul_f32_e32 v114, 0xbfb8aa3b, v157
	v_exp_f32_e32 v114, v114
	s_nop 0
	v_add_f32_e32 v114, 1.0, v114
	v_rcp_f32_e32 v114, v114
	s_nop 0
	v_mul_f32_e32 v114, v157, v114
	v_mul_f32_e32 v155, v156, v114
	v_mul_f32_e32 v114, 0xbfb8aa3b, v123
	v_exp_f32_e32 v114, v114
	s_nop 0
	v_add_f32_e32 v114, 1.0, v114
	v_rcp_f32_e32 v114, v114
	s_nop 0
	v_mul_f32_e32 v114, v123, v114
	v_mul_f32_e32 v122, v122, v114
	v_pk_mul_f32 v[114:115], v[148:149], v[118:119] op_sel_hi:[0,1]
	v_mul_f32_e32 v118, 0xbfb8aa3b, v115
	v_exp_f32_e32 v118, v118
	s_nop 0
	v_add_f32_e32 v118, 1.0, v118
	v_rcp_f32_e32 v118, v118
	s_nop 0
	v_mul_f32_e32 v115, v115, v118
	v_mul_f32_e32 v118, v114, v115
	v_cvt_f32_i32_e32 v115, v128
	v_cvt_f32_i32_e32 v114, v124
	v_pk_mul_f32 v[114:115], v[148:149], v[114:115] op_sel_hi:[0,1]
	v_mul_f32_e32 v119, 0xbfb8aa3b, v115
	v_exp_f32_e32 v119, v119
	s_nop 0
	v_add_f32_e32 v119, 1.0, v119
	v_rcp_f32_e32 v119, v119
	s_nop 0
	v_mul_f32_e32 v115, v115, v119
	v_mul_f32_e32 v119, v114, v115
	v_cvt_f32_i32_e32 v115, v120
	v_cvt_f32_i32_e32 v114, v116
	v_pk_mul_f32 v[114:115], v[148:149], v[114:115] op_sel_hi:[0,1]
	v_mul_f32_e32 v116, 0xbfb8aa3b, v115
	v_exp_f32_e32 v116, v116
	s_nop 0
	v_add_f32_e32 v116, 1.0, v116
	v_rcp_f32_e32 v116, v116
	s_nop 0
	v_mul_f32_e32 v115, v115, v116
	v_mul_f32_e32 v123, v114, v115
	v_cvt_f32_i32_e32 v115, v129
	v_cvt_f32_i32_e32 v114, v125
	v_pk_mul_f32 v[114:115], v[148:149], v[114:115] op_sel_hi:[0,1]
	v_mul_f32_e32 v116, 0xbfb8aa3b, v115
	v_exp_f32_e32 v116, v116
	s_nop 0
	v_add_f32_e32 v116, 1.0, v116
	v_rcp_f32_e32 v116, v116
	s_nop 0
	v_mul_f32_e32 v115, v115, v116
	v_mul_f32_e32 v124, v114, v115
	v_cvt_f32_i32_e32 v115, v121
	v_cvt_f32_i32_e32 v114, v117
	v_pk_mul_f32 v[114:115], v[148:149], v[114:115] op_sel_hi:[0,1]
	v_mul_f32_e32 v116, 0xbfb8aa3b, v115
	v_exp_f32_e32 v116, v116
	s_nop 0
	v_add_f32_e32 v116, 1.0, v116
	v_rcp_f32_e32 v116, v116
	s_nop 0
	v_mul_f32_e32 v115, v115, v116
	v_mul_f32_e32 v125, v114, v115
	v_lshlrev_b64 v[114:115], 1, v[146:147]
	v_lshl_add_u64 v[120:121], v[150:151], 0, v[114:115]
	v_cvt_pk_bf16_f32 v116, v141, v122
	v_cvt_pk_bf16_f32 v117, v119, v124
	v_cvt_pk_bf16_f32 v118, v155, v118
	v_cvt_pk_bf16_f32 v119, v123, v125
	global_store_dwordx4 v[120:121], v[116:119], off nt
	v_cvt_f32_i32_e32 v121, v110
	v_cvt_f32_i32_e32 v120, v106
	v_or_b32_e32 v116, 16, v140
	v_cvt_f32_i32_e32 v110, v107
	s_waitcnt vmcnt(7)
; __device__ __forceinline__ unsigned cvt_pk_bf16(float lo, float hi) { unsigned r; asm volatile("v_cvt_pk_bf16_f32 %0, %1, %2" : "=v"(r) : "v"(lo), "v"(hi)); return r; }
;     __device__ __forceinline__ void operator()(const i32x4 (&acc)[2][2][4][2], const Unit& u, int wr, int wc, int fr, int fq) const {
;     ...
;         const float wdq = __builtin_bit_cast(float, *wmax_bits) * (1.0f / 127.0f);
; #pragma unroll
;         for (int ai = 0; ai < 2; ++ai)
; #pragma unroll
;             for (int m = 0; m < 4; ++m) {
;                 const int row = row0 + ai * HALF + m * 16;
;                 const float f = rowinv[row] * wdq;
;                 bf16_t* rowp = H + (size_t)row * 11008 + col0;
;                 f32x4 h0, h1;
; #pragma unroll
;                 for (int j = 0; j < 4; ++j) {
;                     const float g0 = (float)acc[ai][0][m][0][j] * f, g1 = (float)acc[ai][0][m][1][j] * f;
;                     h0[j] = g0 * __builtin_amdgcn_rcpf(1.0f + __expf(-g0)) * ((float)acc[ai][1][m][0][j] * f);
;                     h1[j] = g1 * __builtin_amdgcn_rcpf(1.0f + __expf(-g1)) * ((float)acc[ai][1][m][1][j] * f);
;                 }
;                 u32x4 w; w.x = cvt_pk_bf16(h0[0], h0[1]); w.y = cvt_pk_bf16(h0[2], h0[3]); w.z = cvt_pk_bf16(h1[0], h1[1]); w.w = cvt_pk_bf16(h1[2], h1[3]);
;                 *(u32x4*)(rowp) = w;
;             }
	v_mul_f32_e32 v118, v154, v227
	v_pk_mul_f32 v[120:121], v[118:119], v[120:121] op_sel_hi:[0,1]
	v_mul_f32_e32 v106, 0xbfb8aa3b, v121
	v_exp_f32_e32 v106, v106
	v_mad_i64_i32 v[116:117], s[30:31], v116, s89, v[144:145]
	v_add_f32_e32 v106, 1.0, v106
	v_rcp_f32_e32 v106, v106
	s_nop 0
	v_mul_f32_e32 v106, v121, v106
	v_mul_f32_e32 v119, v120, v106
	v_cvt_f32_i32_e32 v121, v102
	v_cvt_f32_i32_e32 v120, v98
	v_pk_mul_f32 v[106:107], v[118:119], v[110:111] op_sel_hi:[0,1]
	v_cvt_f32_i32_e32 v102, v99
	v_pk_mul_f32 v[120:121], v[118:119], v[120:121] op_sel_hi:[0,1]
	v_mul_f32_e32 v98, 0xbfb8aa3b, v121
	v_exp_f32_e32 v98, v98
	s_nop 0
	v_add_f32_e32 v98, 1.0, v98
	v_rcp_f32_e32 v98, v98
	s_nop 0
	v_mul_f32_e32 v98, v121, v98
	v_mul_f32_e32 v120, v120, v98
	v_mul_f32_e32 v98, 0xbfb8aa3b, v107
	v_exp_f32_e32 v98, v98
	s_nop 0
	v_add_f32_e32 v98, 1.0, v98
	v_rcp_f32_e32 v98, v98
	s_nop 0
	v_mul_f32_e32 v98, v107, v98
	v_mul_f32_e32 v106, v106, v98
	v_pk_mul_f32 v[98:99], v[118:119], v[102:103] op_sel_hi:[0,1]
	v_mul_f32_e32 v102, 0xbfb8aa3b, v99
	v_exp_f32_e32 v102, v102
	s_nop 0
	v_add_f32_e32 v102, 1.0, v102
	v_rcp_f32_e32 v102, v102
	s_nop 0
	v_mul_f32_e32 v99, v99, v102
	v_mul_f32_e32 v107, v98, v99
	v_cvt_f32_i32_e32 v99, v112
	v_cvt_f32_i32_e32 v98, v108
	v_pk_mul_f32 v[98:99], v[118:119], v[98:99] op_sel_hi:[0,1]
	v_mul_f32_e32 v102, 0xbfb8aa3b, v99
	v_exp_f32_e32 v102, v102
	s_nop 0
	v_add_f32_e32 v102, 1.0, v102
	v_rcp_f32_e32 v102, v102
	s_nop 0
	v_mul_f32_e32 v99, v99, v102
	v_mul_f32_e32 v108, v98, v99
	v_cvt_f32_i32_e32 v99, v104
	v_cvt_f32_i32_e32 v98, v100
	v_lshl_add_u64 v[102:103], v[116:117], 0, v[114:115]
	v_pk_mul_f32 v[98:99], v[118:119], v[98:99] op_sel_hi:[0,1]
	v_mul_f32_e32 v100, 0xbfb8aa3b, v99
	v_exp_f32_e32 v100, v100
	s_nop 0
	v_add_f32_e32 v100, 1.0, v100
	v_rcp_f32_e32 v100, v100
	s_nop 0
	v_mul_f32_e32 v99, v99, v100
	v_mul_f32_e32 v104, v98, v99
	v_cvt_f32_i32_e32 v99, v113
	v_cvt_f32_i32_e32 v98, v109
	v_pk_mul_f32 v[98:99], v[118:119], v[98:99] op_sel_hi:[0,1]
	v_mul_f32_e32 v100, 0xbfb8aa3b, v99
	v_exp_f32_e32 v100, v100
	s_nop 0
	v_add_f32_e32 v100, 1.0, v100
	v_rcp_f32_e32 v100, v100
	s_nop 0
	v_mul_f32_e32 v99, v99, v100
	v_mul_f32_e32 v100, v98, v99
	v_cvt_f32_i32_e32 v99, v105
	v_cvt_f32_i32_e32 v98, v101
	v_pk_mul_f32 v[98:99], v[118:119], v[98:99] op_sel_hi:[0,1]
	v_mul_f32_e32 v101, 0xbfb8aa3b, v99
	v_exp_f32_e32 v101, v101
	s_nop 0
	v_add_f32_e32 v101, 1.0, v101
	v_rcp_f32_e32 v101, v101
	s_nop 0
	v_mul_f32_e32 v99, v99, v101
	v_mul_f32_e32 v101, v98, v99
	v_cvt_pk_bf16_f32 v98, v119, v106
	v_cvt_pk_bf16_f32 v99, v108, v100
	v_cvt_pk_bf16_f32 v100, v120, v107
	v_cvt_pk_bf16_f32 v101, v104, v101
	global_store_dwordx4 v[102:103], v[98:101], off nt
	v_cvt_f32_i32_e32 v103, v94
	v_cvt_f32_i32_e32 v102, v90
	v_or_b32_e32 v98, 32, v140
	v_cvt_f32_i32_e32 v94, v91
	s_waitcnt vmcnt(7)
	v_mul_f32_e32 v100, v154, v228
	v_pk_mul_f32 v[102:103], v[100:101], v[102:103] op_sel_hi:[0,1]
	v_mul_f32_e32 v90, 0xbfb8aa3b, v103
	v_exp_f32_e32 v90, v90
	v_mad_i64_i32 v[98:99], s[30:31], v98, s89, v[144:145]
	v_add_f32_e32 v90, 1.0, v90
	v_rcp_f32_e32 v90, v90
	s_nop 0
	v_mul_f32_e32 v90, v103, v90
	v_mul_f32_e32 v101, v102, v90
	v_cvt_f32_i32_e32 v103, v86
	v_cvt_f32_i32_e32 v102, v82
	v_pk_mul_f32 v[90:91], v[100:101], v[94:95] op_sel_hi:[0,1]
	v_cvt_f32_i32_e32 v86, v83
	v_pk_mul_f32 v[102:103], v[100:101], v[102:103] op_sel_hi:[0,1]
	v_mul_f32_e32 v82, 0xbfb8aa3b, v103
	v_exp_f32_e32 v82, v82
	s_nop 0
	v_add_f32_e32 v82, 1.0, v82
	v_rcp_f32_e32 v82, v82
	s_nop 0
	v_mul_f32_e32 v82, v103, v82
	v_mul_f32_e32 v102, v102, v82
	v_mul_f32_e32 v82, 0xbfb8aa3b, v91
	v_exp_f32_e32 v82, v82
	s_nop 0
	v_add_f32_e32 v82, 1.0, v82
	v_rcp_f32_e32 v82, v82
	s_nop 0
	v_mul_f32_e32 v82, v91, v82
	v_mul_f32_e32 v90, v90, v82
	v_pk_mul_f32 v[82:83], v[100:101], v[86:87] op_sel_hi:[0,1]
	v_mul_f32_e32 v86, 0xbfb8aa3b, v83
	v_exp_f32_e32 v86, v86
	s_nop 0
	v_add_f32_e32 v86, 1.0, v86
	v_rcp_f32_e32 v86, v86
	s_nop 0
	v_mul_f32_e32 v83, v83, v86
	v_mul_f32_e32 v91, v82, v83
	v_cvt_f32_i32_e32 v83, v96
	v_cvt_f32_i32_e32 v82, v92
	v_pk_mul_f32 v[82:83], v[100:101], v[82:83] op_sel_hi:[0,1]
	v_mul_f32_e32 v86, 0xbfb8aa3b, v83
	v_exp_f32_e32 v86, v86
	s_nop 0
	v_add_f32_e32 v86, 1.0, v86
	v_rcp_f32_e32 v86, v86
	s_nop 0
	v_mul_f32_e32 v83, v83, v86
	v_mul_f32_e32 v92, v82, v83
	v_cvt_f32_i32_e32 v83, v88
	v_cvt_f32_i32_e32 v82, v84
	v_lshl_add_u64 v[86:87], v[98:99], 0, v[114:115]
	v_pk_mul_f32 v[82:83], v[100:101], v[82:83] op_sel_hi:[0,1]
	v_mul_f32_e32 v84, 0xbfb8aa3b, v83
	v_exp_f32_e32 v84, v84
	s_nop 0
	v_add_f32_e32 v84, 1.0, v84
	v_rcp_f32_e32 v84, v84
	s_nop 0
	v_mul_f32_e32 v83, v83, v84
	v_mul_f32_e32 v88, v82, v83
	v_cvt_f32_i32_e32 v83, v97
	v_cvt_f32_i32_e32 v82, v93
	v_pk_mul_f32 v[82:83], v[100:101], v[82:83] op_sel_hi:[0,1]
	v_mul_f32_e32 v84, 0xbfb8aa3b, v83
	v_exp_f32_e32 v84, v84
	s_nop 0
	v_add_f32_e32 v84, 1.0, v84
	v_rcp_f32_e32 v84, v84
	s_nop 0
	v_mul_f32_e32 v83, v83, v84
	v_mul_f32_e32 v84, v82, v83
	v_cvt_f32_i32_e32 v83, v89
	v_cvt_f32_i32_e32 v82, v85
	v_pk_mul_f32 v[82:83], v[100:101], v[82:83] op_sel_hi:[0,1]
	v_mul_f32_e32 v85, 0xbfb8aa3b, v83
	v_exp_f32_e32 v85, v85
	s_nop 0
	v_add_f32_e32 v85, 1.0, v85
	v_rcp_f32_e32 v85, v85
	s_nop 0
	v_mul_f32_e32 v83, v83, v85
	v_mul_f32_e32 v85, v82, v83
	v_cvt_pk_bf16_f32 v82, v101, v90
	v_cvt_pk_bf16_f32 v83, v92, v84
	v_cvt_pk_bf16_f32 v84, v102, v91
	v_cvt_pk_bf16_f32 v85, v88, v85
	global_store_dwordx4 v[86:87], v[82:85], off nt
	v_cvt_f32_i32_e32 v87, v78
	v_cvt_f32_i32_e32 v86, v74
	v_or_b32_e32 v82, 48, v140
	v_cvt_f32_i32_e32 v78, v75
	s_waitcnt vmcnt(7)
; __device__ __forceinline__ unsigned cvt_pk_bf16(float lo, float hi) { unsigned r; asm volatile("v_cvt_pk_bf16_f32 %0, %1, %2" : "=v"(r) : "v"(lo), "v"(hi)); return r; }
;     __device__ __forceinline__ void operator()(const i32x4 (&acc)[2][2][4][2], const Unit& u, int wr, int wc, int fr, int fq) const {
;     ...
;         const float wdq = __builtin_bit_cast(float, *wmax_bits) * (1.0f / 127.0f);
; #pragma unroll
;         for (int ai = 0; ai < 2; ++ai)
; #pragma unroll
;             for (int m = 0; m < 4; ++m) {
;                 const int row = row0 + ai * HALF + m * 16;
;                 const float f = rowinv[row] * wdq;
;                 bf16_t* rowp = H + (size_t)row * 11008 + col0;
;                 f32x4 h0, h1;
; #pragma unroll
;                 for (int j = 0; j < 4; ++j) {
;                     const float g0 = (float)acc[ai][0][m][0][j] * f, g1 = (float)acc[ai][0][m][1][j] * f;
;                     h0[j] = g0 * __builtin_amdgcn_rcpf(1.0f + __expf(-g0)) * ((float)acc[ai][1][m][0][j] * f);
;                     h1[j] = g1 * __builtin_amdgcn_rcpf(1.0f + __expf(-g1)) * ((float)acc[ai][1][m][1][j] * f);
;                 }
;                 u32x4 w; w.x = cvt_pk_bf16(h0[0], h0[1]); w.y = cvt_pk_bf16(h0[2], h0[3]); w.z = cvt_pk_bf16(h1[0], h1[1]); w.w = cvt_pk_bf16(h1[2], h1[3]);
;                 *(u32x4*)(rowp) = w;
;             }
	v_mul_f32_e32 v84, v154, v229
	v_pk_mul_f32 v[86:87], v[84:85], v[86:87] op_sel_hi:[0,1]
	v_mul_f32_e32 v74, 0xbfb8aa3b, v87
	v_exp_f32_e32 v74, v74
	v_mad_i64_i32 v[82:83], s[30:31], v82, s89, v[144:145]
	v_add_f32_e32 v74, 1.0, v74
	v_rcp_f32_e32 v74, v74
	s_nop 0
	v_mul_f32_e32 v74, v87, v74
	v_mul_f32_e32 v74, v86, v74
	v_cvt_f32_i32_e32 v87, v70
	v_cvt_f32_i32_e32 v86, v66
	v_cvt_f32_i32_e32 v70, v67
	v_pk_mul_f32 v[86:87], v[84:85], v[86:87] op_sel_hi:[0,1]
	v_mul_f32_e32 v66, 0xbfb8aa3b, v87
	v_exp_f32_e32 v66, v66
	s_nop 0
	v_add_f32_e32 v66, 1.0, v66
	v_rcp_f32_e32 v66, v66
	s_nop 0
	v_mul_f32_e32 v66, v87, v66
	v_mul_f32_e32 v85, v86, v66
	v_pk_mul_f32 v[78:79], v[84:85], v[78:79] op_sel_hi:[0,1]
	v_mul_f32_e32 v66, 0xbfb8aa3b, v79
	v_exp_f32_e32 v66, v66
	s_nop 0
	v_add_f32_e32 v66, 1.0, v66
	v_rcp_f32_e32 v66, v66
	s_nop 0
	v_mul_f32_e32 v66, v79, v66
	v_mul_f32_e32 v75, v78, v66
	v_pk_mul_f32 v[66:67], v[84:85], v[70:71] op_sel_hi:[0,1]
	v_mul_f32_e32 v70, 0xbfb8aa3b, v67
	v_exp_f32_e32 v70, v70
	s_nop 0
	v_add_f32_e32 v70, 1.0, v70
	v_rcp_f32_e32 v70, v70
	s_nop 0
	v_mul_f32_e32 v67, v67, v70
	v_mul_f32_e32 v78, v66, v67
	v_cvt_f32_i32_e32 v67, v80
	v_cvt_f32_i32_e32 v66, v76
	v_pk_mul_f32 v[66:67], v[84:85], v[66:67] op_sel_hi:[0,1]
	v_mul_f32_e32 v70, 0xbfb8aa3b, v67
	v_exp_f32_e32 v70, v70
	s_nop 0
	v_add_f32_e32 v70, 1.0, v70
	v_rcp_f32_e32 v70, v70
	s_nop 0
	v_mul_f32_e32 v67, v67, v70
	v_mul_f32_e32 v76, v66, v67
	v_cvt_f32_i32_e32 v67, v72
	v_cvt_f32_i32_e32 v66, v68
	v_lshl_add_u64 v[70:71], v[82:83], 0, v[114:115]
	v_pk_mul_f32 v[66:67], v[84:85], v[66:67] op_sel_hi:[0,1]
	v_mul_f32_e32 v68, 0xbfb8aa3b, v67
	v_exp_f32_e32 v68, v68
	s_nop 0
	v_add_f32_e32 v68, 1.0, v68
	v_rcp_f32_e32 v68, v68
	s_nop 0
	v_mul_f32_e32 v67, v67, v68
	v_mul_f32_e32 v72, v66, v67
	v_cvt_f32_i32_e32 v67, v81
	v_cvt_f32_i32_e32 v66, v77
	v_pk_mul_f32 v[66:67], v[84:85], v[66:67] op_sel_hi:[0,1]
	v_mul_f32_e32 v68, 0xbfb8aa3b, v67
	v_exp_f32_e32 v68, v68
	s_nop 0
	v_add_f32_e32 v68, 1.0, v68
	v_rcp_f32_e32 v68, v68
	s_nop 0
	v_mul_f32_e32 v67, v67, v68
	v_mul_f32_e32 v68, v66, v67
	v_cvt_f32_i32_e32 v67, v73
	v_cvt_f32_i32_e32 v66, v69
	v_pk_mul_f32 v[66:67], v[84:85], v[66:67] op_sel_hi:[0,1]
	v_mul_f32_e32 v69, 0xbfb8aa3b, v67
	v_exp_f32_e32 v69, v69
	s_nop 0
	v_add_f32_e32 v69, 1.0, v69
	v_rcp_f32_e32 v69, v69
	s_nop 0
	v_mul_f32_e32 v67, v67, v69
	v_mul_f32_e32 v69, v66, v67
	v_cvt_pk_bf16_f32 v66, v74, v75
	v_cvt_pk_bf16_f32 v67, v76, v68
	v_cvt_pk_bf16_f32 v68, v85, v78
	v_cvt_pk_bf16_f32 v69, v72, v69
	global_store_dwordx4 v[70:71], v[66:69], off nt
	v_cvt_f32_i32_e32 v71, v62
	v_cvt_f32_i32_e32 v70, v58
	v_cvt_f32_i32_e32 v62, v59
	v_add_u32_e32 v66, 0x80, v140
	s_waitcnt vmcnt(7)
	v_mul_f32_e32 v68, v154, v230
	v_pk_mul_f32 v[70:71], v[68:69], v[70:71] op_sel_hi:[0,1]
	v_mul_f32_e32 v58, 0xbfb8aa3b, v71
	v_exp_f32_e32 v58, v58
	v_mad_i64_i32 v[66:67], s[30:31], v66, s89, v[144:145]
	v_add_f32_e32 v58, 1.0, v58
	v_rcp_f32_e32 v58, v58
	s_nop 0
	v_mul_f32_e32 v58, v71, v58
	v_mul_f32_e32 v58, v70, v58
	v_cvt_f32_i32_e32 v71, v54
	v_cvt_f32_i32_e32 v70, v50
	v_cvt_f32_i32_e32 v54, v51
	v_pk_mul_f32 v[70:71], v[68:69], v[70:71] op_sel_hi:[0,1]
	v_mul_f32_e32 v50, 0xbfb8aa3b, v71
	v_exp_f32_e32 v50, v50
	s_nop 0
	v_add_f32_e32 v50, 1.0, v50
	v_rcp_f32_e32 v50, v50
	s_nop 0
	v_mul_f32_e32 v50, v71, v50
	v_mul_f32_e32 v69, v70, v50
	v_pk_mul_f32 v[62:63], v[68:69], v[62:63] op_sel_hi:[0,1]
	v_mul_f32_e32 v50, 0xbfb8aa3b, v63
	v_exp_f32_e32 v50, v50
	s_nop 0
	v_add_f32_e32 v50, 1.0, v50
	v_rcp_f32_e32 v50, v50
	s_nop 0
	v_mul_f32_e32 v50, v63, v50
	v_mul_f32_e32 v59, v62, v50
	v_pk_mul_f32 v[50:51], v[68:69], v[54:55] op_sel_hi:[0,1]
	v_mul_f32_e32 v54, 0xbfb8aa3b, v51
	v_exp_f32_e32 v54, v54
	s_nop 0
	v_add_f32_e32 v54, 1.0, v54
	v_rcp_f32_e32 v54, v54
	s_nop 0
	v_mul_f32_e32 v51, v51, v54
	v_mul_f32_e32 v62, v50, v51
	v_cvt_f32_i32_e32 v51, v64
	v_cvt_f32_i32_e32 v50, v60
	v_pk_mul_f32 v[50:51], v[68:69], v[50:51] op_sel_hi:[0,1]
	v_mul_f32_e32 v54, 0xbfb8aa3b, v51
	v_exp_f32_e32 v54, v54
	s_nop 0
	v_add_f32_e32 v54, 1.0, v54
	v_rcp_f32_e32 v54, v54
	s_nop 0
	v_mul_f32_e32 v51, v51, v54
	v_mul_f32_e32 v60, v50, v51
	v_cvt_f32_i32_e32 v51, v56
	v_cvt_f32_i32_e32 v50, v52
	v_lshl_add_u64 v[54:55], v[66:67], 0, v[114:115]
	v_pk_mul_f32 v[50:51], v[68:69], v[50:51] op_sel_hi:[0,1]
	v_mul_f32_e32 v52, 0xbfb8aa3b, v51
	v_exp_f32_e32 v52, v52
	s_nop 0
	v_add_f32_e32 v52, 1.0, v52
	v_rcp_f32_e32 v52, v52
	s_nop 0
	v_mul_f32_e32 v51, v51, v52
	v_mul_f32_e32 v56, v50, v51
	v_cvt_f32_i32_e32 v51, v65
	v_cvt_f32_i32_e32 v50, v61
	v_pk_mul_f32 v[50:51], v[68:69], v[50:51] op_sel_hi:[0,1]
	v_mul_f32_e32 v52, 0xbfb8aa3b, v51
	v_exp_f32_e32 v52, v52
	s_nop 0
	v_add_f32_e32 v52, 1.0, v52
	v_rcp_f32_e32 v52, v52
	s_nop 0
	v_mul_f32_e32 v51, v51, v52
	v_mul_f32_e32 v52, v50, v51
	v_cvt_f32_i32_e32 v51, v57
	v_cvt_f32_i32_e32 v50, v53
	v_pk_mul_f32 v[50:51], v[68:69], v[50:51] op_sel_hi:[0,1]
	v_mul_f32_e32 v53, 0xbfb8aa3b, v51
	v_exp_f32_e32 v53, v53
	s_nop 0
	v_add_f32_e32 v53, 1.0, v53
	v_rcp_f32_e32 v53, v53
	s_nop 0
	v_mul_f32_e32 v51, v51, v53
	v_mul_f32_e32 v53, v50, v51
	v_cvt_pk_bf16_f32 v50, v58, v59
	v_cvt_pk_bf16_f32 v51, v60, v52
	v_cvt_pk_bf16_f32 v52, v69, v62
	v_cvt_pk_bf16_f32 v53, v56, v53
	global_store_dwordx4 v[54:55], v[50:53], off nt
	v_cvt_f32_i32_e32 v55, v46
	v_cvt_f32_i32_e32 v54, v42
	v_cvt_f32_i32_e32 v46, v43
	v_add_u32_e32 v50, 0x90, v140
	s_waitcnt vmcnt(7)
; __device__ __forceinline__ unsigned cvt_pk_bf16(float lo, float hi) { unsigned r; asm volatile("v_cvt_pk_bf16_f32 %0, %1, %2" : "=v"(r) : "v"(lo), "v"(hi)); return r; }
;     __device__ __forceinline__ void operator()(const i32x4 (&acc)[2][2][4][2], const Unit& u, int wr, int wc, int fr, int fq) const {
;     ...
;         const float wdq = __builtin_bit_cast(float, *wmax_bits) * (1.0f / 127.0f);
; #pragma unroll
;         for (int ai = 0; ai < 2; ++ai)
; #pragma unroll
;             for (int m = 0; m < 4; ++m) {
;                 const int row = row0 + ai * HALF + m * 16;
;                 const float f = rowinv[row] * wdq;
;                 bf16_t* rowp = H + (size_t)row * 11008 + col0;
;                 f32x4 h0, h1;
; #pragma unroll
;                 for (int j = 0; j < 4; ++j) {
;                     const float g0 = (float)acc[ai][0][m][0][j] * f, g1 = (float)acc[ai][0][m][1][j] * f;
;                     h0[j] = g0 * __builtin_amdgcn_rcpf(1.0f + __expf(-g0)) * ((float)acc[ai][1][m][0][j] * f);
;                     h1[j] = g1 * __builtin_amdgcn_rcpf(1.0f + __expf(-g1)) * ((float)acc[ai][1][m][1][j] * f);
;                 }
;                 u32x4 w; w.x = cvt_pk_bf16(h0[0], h0[1]); w.y = cvt_pk_bf16(h0[2], h0[3]); w.z = cvt_pk_bf16(h1[0], h1[1]); w.w = cvt_pk_bf16(h1[2], h1[3]);
;                 *(u32x4*)(rowp) = w;
;             }
	v_mul_f32_e32 v52, v154, v231
	v_pk_mul_f32 v[54:55], v[52:53], v[54:55] op_sel_hi:[0,1]
	v_mul_f32_e32 v42, 0xbfb8aa3b, v55
	v_exp_f32_e32 v42, v42
	v_mad_i64_i32 v[50:51], s[30:31], v50, s89, v[144:145]
	v_add_f32_e32 v42, 1.0, v42
	v_rcp_f32_e32 v42, v42
	s_nop 0
	v_mul_f32_e32 v42, v55, v42
	v_mul_f32_e32 v42, v54, v42
	v_cvt_f32_i32_e32 v55, v38
	v_cvt_f32_i32_e32 v54, v34
	v_cvt_f32_i32_e32 v38, v35
	v_pk_mul_f32 v[54:55], v[52:53], v[54:55] op_sel_hi:[0,1]
	v_mul_f32_e32 v34, 0xbfb8aa3b, v55
	v_exp_f32_e32 v34, v34
	s_nop 0
	v_add_f32_e32 v34, 1.0, v34
	v_rcp_f32_e32 v34, v34
	s_nop 0
	v_mul_f32_e32 v34, v55, v34
	v_mul_f32_e32 v53, v54, v34
	v_pk_mul_f32 v[46:47], v[52:53], v[46:47] op_sel_hi:[0,1]
	v_mul_f32_e32 v34, 0xbfb8aa3b, v47
	v_exp_f32_e32 v34, v34
	s_nop 0
	v_add_f32_e32 v34, 1.0, v34
	v_rcp_f32_e32 v34, v34
	s_nop 0
	v_mul_f32_e32 v34, v47, v34
	v_mul_f32_e32 v43, v46, v34
	v_pk_mul_f32 v[34:35], v[52:53], v[38:39] op_sel_hi:[0,1]
	v_mul_f32_e32 v38, 0xbfb8aa3b, v35
	v_exp_f32_e32 v38, v38
	s_nop 0
	v_add_f32_e32 v38, 1.0, v38
	v_rcp_f32_e32 v38, v38
	s_nop 0
	v_mul_f32_e32 v35, v35, v38
	v_mul_f32_e32 v46, v34, v35
	v_cvt_f32_i32_e32 v35, v48
	v_cvt_f32_i32_e32 v34, v44
	v_pk_mul_f32 v[34:35], v[52:53], v[34:35] op_sel_hi:[0,1]
	v_mul_f32_e32 v38, 0xbfb8aa3b, v35
	v_exp_f32_e32 v38, v38
	s_nop 0
	v_add_f32_e32 v38, 1.0, v38
	v_rcp_f32_e32 v38, v38
	s_nop 0
	v_mul_f32_e32 v35, v35, v38
	v_mul_f32_e32 v44, v34, v35
	v_cvt_f32_i32_e32 v35, v40
	v_cvt_f32_i32_e32 v34, v36
	v_lshl_add_u64 v[38:39], v[50:51], 0, v[114:115]
	v_pk_mul_f32 v[34:35], v[52:53], v[34:35] op_sel_hi:[0,1]
	v_mul_f32_e32 v36, 0xbfb8aa3b, v35
	v_exp_f32_e32 v36, v36
	s_nop 0
	v_add_f32_e32 v36, 1.0, v36
	v_rcp_f32_e32 v36, v36
	s_nop 0
	v_mul_f32_e32 v35, v35, v36
	v_mul_f32_e32 v40, v34, v35
	v_cvt_f32_i32_e32 v35, v49
	v_cvt_f32_i32_e32 v34, v45
	v_pk_mul_f32 v[34:35], v[52:53], v[34:35] op_sel_hi:[0,1]
	v_mul_f32_e32 v36, 0xbfb8aa3b, v35
	v_exp_f32_e32 v36, v36
	s_nop 0
	v_add_f32_e32 v36, 1.0, v36
	v_rcp_f32_e32 v36, v36
	s_nop 0
	v_mul_f32_e32 v35, v35, v36
	v_mul_f32_e32 v36, v34, v35
	v_cvt_f32_i32_e32 v35, v41
	v_cvt_f32_i32_e32 v34, v37
	v_pk_mul_f32 v[34:35], v[52:53], v[34:35] op_sel_hi:[0,1]
	v_mul_f32_e32 v37, 0xbfb8aa3b, v35
	v_exp_f32_e32 v37, v37
	s_nop 0
	v_add_f32_e32 v37, 1.0, v37
	v_rcp_f32_e32 v37, v37
	s_nop 0
	v_mul_f32_e32 v35, v35, v37
	v_mul_f32_e32 v37, v34, v35
	v_cvt_pk_bf16_f32 v34, v42, v43
	v_cvt_pk_bf16_f32 v35, v44, v36
	v_cvt_pk_bf16_f32 v36, v53, v46
	v_cvt_pk_bf16_f32 v37, v40, v37
	global_store_dwordx4 v[38:39], v[34:37], off nt
	v_cvt_f32_i32_e32 v39, v30
	v_cvt_f32_i32_e32 v38, v26
	v_cvt_f32_i32_e32 v30, v27
	v_add_u32_e32 v34, 0xa0, v140
	s_waitcnt vmcnt(7)
; __device__ __forceinline__ unsigned cvt_pk_bf16(float lo, float hi) { unsigned r; asm volatile("v_cvt_pk_bf16_f32 %0, %1, %2" : "=v"(r) : "v"(lo), "v"(hi)); return r; }
;     __device__ __forceinline__ void operator()(const i32x4 (&acc)[2][2][4][2], const Unit& u, int wr, int wc, int fr, int fq) const {
;     ...
;         const float wdq = __builtin_bit_cast(float, *wmax_bits) * (1.0f / 127.0f);
; #pragma unroll
;         for (int ai = 0; ai < 2; ++ai)
; #pragma unroll
;             for (int m = 0; m < 4; ++m) {
;                 const int row = row0 + ai * HALF + m * 16;
;                 const float f = rowinv[row] * wdq;
;                 bf16_t* rowp = H + (size_t)row * 11008 + col0;
;                 f32x4 h0, h1;
; #pragma unroll
;                 for (int j = 0; j < 4; ++j) {
;                     const float g0 = (float)acc[ai][0][m][0][j] * f, g1 = (float)acc[ai][0][m][1][j] * f;
;                     h0[j] = g0 * __builtin_amdgcn_rcpf(1.0f + __expf(-g0)) * ((float)acc[ai][1][m][0][j] * f);
;                     h1[j] = g1 * __builtin_amdgcn_rcpf(1.0f + __expf(-g1)) * ((float)acc[ai][1][m][1][j] * f);
;                 }
;                 u32x4 w; w.x = cvt_pk_bf16(h0[0], h0[1]); w.y = cvt_pk_bf16(h0[2], h0[3]); w.z = cvt_pk_bf16(h1[0], h1[1]); w.w = cvt_pk_bf16(h1[2], h1[3]);
;                 *(u32x4*)(rowp) = w;
;             }
	v_mul_f32_e32 v36, v154, v232
	v_pk_mul_f32 v[38:39], v[36:37], v[38:39] op_sel_hi:[0,1]
	v_mul_f32_e32 v26, 0xbfb8aa3b, v39
	v_exp_f32_e32 v26, v26
	v_mad_i64_i32 v[34:35], s[30:31], v34, s89, v[144:145]
	v_add_f32_e32 v26, 1.0, v26
	v_rcp_f32_e32 v26, v26
	s_nop 0
	v_mul_f32_e32 v26, v39, v26
	v_mul_f32_e32 v26, v38, v26
	v_cvt_f32_i32_e32 v39, v22
	v_cvt_f32_i32_e32 v38, v18
	v_cvt_f32_i32_e32 v22, v19
	v_pk_mul_f32 v[38:39], v[36:37], v[38:39] op_sel_hi:[0,1]
	v_mul_f32_e32 v18, 0xbfb8aa3b, v39
	v_exp_f32_e32 v18, v18
	s_nop 0
	v_add_f32_e32 v18, 1.0, v18
	v_rcp_f32_e32 v18, v18
	s_nop 0
	v_mul_f32_e32 v18, v39, v18
	v_mul_f32_e32 v37, v38, v18
	v_pk_mul_f32 v[30:31], v[36:37], v[30:31] op_sel_hi:[0,1]
	v_mul_f32_e32 v18, 0xbfb8aa3b, v31
	v_exp_f32_e32 v18, v18
	s_nop 0
	v_add_f32_e32 v18, 1.0, v18
	v_rcp_f32_e32 v18, v18
	s_nop 0
	v_mul_f32_e32 v18, v31, v18
	v_mul_f32_e32 v27, v30, v18
	v_pk_mul_f32 v[18:19], v[36:37], v[22:23] op_sel_hi:[0,1]
	v_mul_f32_e32 v22, 0xbfb8aa3b, v19
	v_exp_f32_e32 v22, v22
	s_nop 0
	v_add_f32_e32 v22, 1.0, v22
	v_rcp_f32_e32 v22, v22
	s_nop 0
	v_mul_f32_e32 v19, v19, v22
	v_mul_f32_e32 v30, v18, v19
	v_cvt_f32_i32_e32 v19, v32
	v_cvt_f32_i32_e32 v18, v28
	v_pk_mul_f32 v[18:19], v[36:37], v[18:19] op_sel_hi:[0,1]
	v_mul_f32_e32 v22, 0xbfb8aa3b, v19
	v_exp_f32_e32 v22, v22
	s_nop 0
	v_add_f32_e32 v22, 1.0, v22
	v_rcp_f32_e32 v22, v22
	s_nop 0
	v_mul_f32_e32 v19, v19, v22
	v_mul_f32_e32 v28, v18, v19
	v_cvt_f32_i32_e32 v19, v24
	v_cvt_f32_i32_e32 v18, v20
	v_lshl_add_u64 v[22:23], v[34:35], 0, v[114:115]
	v_pk_mul_f32 v[18:19], v[36:37], v[18:19] op_sel_hi:[0,1]
	v_mul_f32_e32 v20, 0xbfb8aa3b, v19
	v_exp_f32_e32 v20, v20
	s_nop 0
	v_add_f32_e32 v20, 1.0, v20
	v_rcp_f32_e32 v20, v20
	s_nop 0
	v_mul_f32_e32 v19, v19, v20
	v_mul_f32_e32 v24, v18, v19
	v_cvt_f32_i32_e32 v19, v33
	v_cvt_f32_i32_e32 v18, v29
	v_pk_mul_f32 v[18:19], v[36:37], v[18:19] op_sel_hi:[0,1]
	v_mul_f32_e32 v20, 0xbfb8aa3b, v19
	v_exp_f32_e32 v20, v20
	s_nop 0
	v_add_f32_e32 v20, 1.0, v20
	v_rcp_f32_e32 v20, v20
	s_nop 0
	v_mul_f32_e32 v19, v19, v20
	v_mul_f32_e32 v20, v18, v19
	v_cvt_f32_i32_e32 v19, v25
	v_cvt_f32_i32_e32 v18, v21
	v_pk_mul_f32 v[18:19], v[36:37], v[18:19] op_sel_hi:[0,1]
	v_mul_f32_e32 v21, 0xbfb8aa3b, v19
	v_exp_f32_e32 v21, v21
	s_nop 0
	v_add_f32_e32 v21, 1.0, v21
	v_rcp_f32_e32 v21, v21
	s_nop 0
	v_mul_f32_e32 v19, v19, v21
	v_mul_f32_e32 v21, v18, v19
	v_cvt_pk_bf16_f32 v18, v26, v27
	v_cvt_pk_bf16_f32 v19, v28, v20
	v_cvt_pk_bf16_f32 v20, v37, v30
	v_cvt_pk_bf16_f32 v21, v24, v21
	global_store_dwordx4 v[22:23], v[18:21], off nt
	v_cvt_f32_i32_e32 v23, v14
	v_cvt_f32_i32_e32 v22, v10
	v_cvt_f32_i32_e32 v14, v11
	v_add_u32_e32 v18, 0xb0, v140
	s_waitcnt vmcnt(7)
	v_mul_f32_e32 v20, v154, v233
	v_pk_mul_f32 v[22:23], v[20:21], v[22:23] op_sel_hi:[0,1]
	v_mul_f32_e32 v10, 0xbfb8aa3b, v23
	v_exp_f32_e32 v10, v10
	v_mad_i64_i32 v[18:19], s[30:31], v18, s89, v[144:145]
	v_add_f32_e32 v10, 1.0, v10
	v_rcp_f32_e32 v10, v10
	s_nop 0
	v_mul_f32_e32 v10, v23, v10
	v_mul_f32_e32 v21, v22, v10
	v_cvt_f32_i32_e32 v23, v6
	v_cvt_f32_i32_e32 v22, v2
	v_pk_mul_f32 v[10:11], v[20:21], v[14:15] op_sel_hi:[0,1]
	v_cvt_f32_i32_e32 v6, v3
	v_pk_mul_f32 v[22:23], v[20:21], v[22:23] op_sel_hi:[0,1]
	v_mul_f32_e32 v2, 0xbfb8aa3b, v23
	v_exp_f32_e32 v2, v2
	s_nop 0
	v_add_f32_e32 v2, 1.0, v2
	v_rcp_f32_e32 v2, v2
	s_nop 0
	v_mul_f32_e32 v2, v23, v2
	v_mul_f32_e32 v22, v22, v2
	v_mul_f32_e32 v2, 0xbfb8aa3b, v11
	v_exp_f32_e32 v2, v2
	s_nop 0
	v_add_f32_e32 v2, 1.0, v2
	v_rcp_f32_e32 v2, v2
	s_nop 0
	v_mul_f32_e32 v2, v11, v2
	v_mul_f32_e32 v10, v10, v2
	v_pk_mul_f32 v[2:3], v[20:21], v[6:7] op_sel_hi:[0,1]
	v_mul_f32_e32 v6, 0xbfb8aa3b, v3
	v_exp_f32_e32 v6, v6
	s_nop 0
	v_add_f32_e32 v6, 1.0, v6
	v_rcp_f32_e32 v6, v6
	s_nop 0
	v_mul_f32_e32 v3, v3, v6
	v_mul_f32_e32 v11, v2, v3
	v_cvt_f32_i32_e32 v3, v16
	v_cvt_f32_i32_e32 v2, v12
	v_pk_mul_f32 v[2:3], v[20:21], v[2:3] op_sel_hi:[0,1]
	v_mul_f32_e32 v6, 0xbfb8aa3b, v3
	v_exp_f32_e32 v6, v6
	s_nop 0
	v_add_f32_e32 v6, 1.0, v6
	v_rcp_f32_e32 v6, v6
	s_nop 0
	v_mul_f32_e32 v3, v3, v6
	v_mul_f32_e32 v12, v2, v3
	v_cvt_f32_i32_e32 v3, v8
	v_cvt_f32_i32_e32 v2, v4
	v_lshl_add_u64 v[6:7], v[18:19], 0, v[114:115]
	v_pk_mul_f32 v[2:3], v[20:21], v[2:3] op_sel_hi:[0,1]
	v_mul_f32_e32 v4, 0xbfb8aa3b, v3
	v_exp_f32_e32 v4, v4
	s_nop 0
	v_add_f32_e32 v4, 1.0, v4
	v_rcp_f32_e32 v4, v4
	s_nop 0
	v_mul_f32_e32 v3, v3, v4
	v_mul_f32_e32 v8, v2, v3
	v_cvt_f32_i32_e32 v3, v17
	v_cvt_f32_i32_e32 v2, v13
	v_pk_mul_f32 v[2:3], v[20:21], v[2:3] op_sel_hi:[0,1]
	v_mul_f32_e32 v4, 0xbfb8aa3b, v3
	v_exp_f32_e32 v4, v4
	s_nop 0
	v_add_f32_e32 v4, 1.0, v4
	v_rcp_f32_e32 v4, v4
	s_nop 0
	v_mul_f32_e32 v3, v3, v4
	v_mul_f32_e32 v4, v2, v3
	v_cvt_f32_i32_e32 v3, v9
	v_cvt_f32_i32_e32 v2, v5
	v_pk_mul_f32 v[2:3], v[20:21], v[2:3] op_sel_hi:[0,1]
	v_mul_f32_e32 v5, 0xbfb8aa3b, v3
	v_exp_f32_e32 v5, v5
	s_nop 0
	v_add_f32_e32 v5, 1.0, v5
	v_rcp_f32_e32 v5, v5
	s_nop 0
	v_mul_f32_e32 v3, v3, v5
	v_mul_f32_e32 v5, v2, v3
	v_cvt_pk_bf16_f32 v2, v21, v10
	v_cvt_pk_bf16_f32 v3, v12, v4
	v_cvt_pk_bf16_f32 v4, v22, v11
	v_cvt_pk_bf16_f32 v5, v8, v5
	global_store_dwordx4 v[6:7], v[2:5], off nt
	s_cbranch_vccnz .LBB0_1053
	s_andn2_b64 vcc, exec, s[8:9]
	s_cbranch_vccnz .LBB0_1052
	s_barrier
	s_branch .LBB0_1052

; __device__ __forceinline__ u32x4 pk8h(const f32x4 a, const f32x4 b) { u32x4 w; w.x = pkh(a[0], a[1]); w.y = pkh(a[2], a[3]); w.z = pkh(b[0], b[1]); w.w = pkh(b[2], b[3]); return w; }
; __device__ __forceinline__ f32x4 h4lo(const u32x4 w) { return (f32x4){hlo(w.x), hhi(w.x), hlo(w.y), hhi(w.y)}; }
; __device__ __forceinline__ f32x4 h4hi(const u32x4 w) { return (f32x4){hlo(w.z), hhi(w.z), hlo(w.w), hhi(w.w)}; }
;     __device__ __forceinline__ void operator()(const i32x4 (&acc)[2][2][4][2], const Unit& u, int wr, int wc, int fr, int fq) const {
;         const int row0 = u.pm * BM + wr * 64 + fr, col0 = u.pn * BM + wc * 32 + 8 * fq;
;         const float wdq = __builtin_bit_cast(float, *wmax_bits) * (1.0f / 127.0f);
; #pragma unroll
;         for (int ai = 0; ai < 2; ++ai) {
;             u32x4 y[4][2]; float mean[4], rstd[4], f[4];
; #pragma unroll
;             for (int m = 0; m < 4; ++m) { const int row = row0 + ai * HALF + m * 16; const bf16_t* yp = X + (size_t)row * 4096 + col0; y[m][0] = *(const u32x4*)yp; y[m][1] = *(const u32x4*)(yp + HALF);
;                 mean[m] = stats[2 * row]; rstd[m] = stats[2 * row + 1]; f[m] = rowinv[row] * wdq; }
; #pragma unroll
;             for (int m = 0; m < 4; ++m) { bf16_t* rowp = X + (size_t)(row0 + ai * HALF + m * 16) * 4096 + col0;
; #pragma unroll
;                 for (int bj = 0; bj < 2; ++bj) { const int c = col0 + bj * HALF; const float ra = rstd[m] * alpha;
;                     const f32x4 g0 = *(const f32x4*)(g + c) * ra, g1 = *(const f32x4*)(g + c + 4) * ra, b0 = *(const f32x4*)(b + c) * alpha, b1 = *(const f32x4*)(b + c + 4) * alpha;
;                     const i32x4 a0 = acc[ai][bj][m][0], a1 = acc[ai][bj][m][1];
;                     f32x4 q0, q1; q0.x = (float)a0.x; q0.y = (float)a0.y; q0.z = (float)a0.z; q0.w = (float)a0.w; q1.x = (float)a1.x; q1.y = (float)a1.y; q1.z = (float)a1.z; q1.w = (float)a1.w;
;                     *(u32x4*)(rowp + bj * HALF) = pk8h((h4lo(y[m][bj]) - mean[m]) * g0 + b0 + q0 * f[m], (h4hi(y[m][bj]) - mean[m]) * g1 + b1 + q1 * f[m]); } }
.LBB0_1203:
	v_lshl_add_u32 v150, s85, 8, v1
	v_lshl_or_b32 v142, s83, 8, v157
	v_lshlrev_b32_e32 v140, 1, v150
	v_ashrrev_i32_e32 v143, 31, v142
	v_ashrrev_i32_e32 v141, 31, v140
	v_ashrrev_i32_e32 v151, 31, v150
	v_lshl_add_u64 v[140:141], v[140:141], 2, s[36:37]
	v_lshlrev_b64 v[146:147], 2, v[142:143]
	v_lshlrev_b64 v[144:145], 1, v[142:143]
	global_load_dword v185, v183, s[16:17]
	v_lshl_add_u64 v[148:149], v[150:151], 2, s[14:15]
	global_load_dwordx2 v[154:155], v[140:141], off
	global_load_dword v186, v[148:149], off
	v_lshl_add_u64 v[140:141], s[44:45], 0, v[146:147]
	v_lshl_add_u64 v[142:143], s[42:43], 0, v[146:147]
	v_lshl_add_u64 v[146:147], s[10:11], 0, v[144:145]
	v_lshlrev_b64 v[180:181], 13, v[150:151]
	v_lshl_add_u64 v[198:199], v[146:147], 0, v[180:181]
	global_load_dwordx4 v[160:163], v[140:141], off offset:16
	global_load_dwordx4 v[164:167], v[140:141], off
	global_load_dwordx4 v[168:171], v[142:143], off offset:16
	global_load_dwordx4 v[172:175], v[142:143], off
	global_load_dwordx4 v[176:179], v[198:199], off
	v_or_b32_e32 v210, 16, v150
	v_or_b32_e32 v152, 32, v150
	v_cvt_f32_i32_e32 v202, v126
	v_cvt_f32_i32_e32 v206, v122
	v_cvt_f32_i32_e32 v208, v124
	v_or_b32_e32 v126, 48, v150
	v_lshlrev_b32_e32 v122, 1, v210
	v_lshlrev_b32_e32 v124, 1, v152
	v_cvt_f32_i32_e32 v204, v128
	v_cvt_f32_i32_e32 v207, v123
	v_cvt_f32_i32_e32 v209, v125
	v_ashrrev_i32_e32 v211, 31, v210
	v_ashrrev_i32_e32 v153, 31, v152
	v_lshlrev_b32_e32 v128, 1, v126
	v_ashrrev_i32_e32 v123, 31, v122
	v_ashrrev_i32_e32 v125, 31, v124
	v_cvt_f32_i32_e32 v203, v127
	v_cvt_f32_i32_e32 v205, v129
	v_ashrrev_i32_e32 v127, 31, v126
	v_lshl_add_u64 v[226:227], v[210:211], 2, s[14:15]
	v_lshl_add_u64 v[228:229], v[152:153], 2, s[14:15]
	v_ashrrev_i32_e32 v129, 31, v128
	v_lshl_add_u64 v[122:123], v[122:123], 2, s[36:37]
	v_lshl_add_u64 v[124:125], v[124:125], 2, s[36:37]
	v_lshl_add_u64 v[230:231], v[126:127], 2, s[14:15]
	v_lshl_add_u64 v[232:233], v[128:129], 2, s[36:37]
	global_load_dwordx4 v[198:201], v[198:199], off offset:256
	s_nop 0
	global_load_dwordx2 v[128:129], v[122:123], off
	global_load_dword v189, v[226:227], off
	s_nop 0
	global_load_dwordx2 v[124:125], v[124:125], off
	s_nop 0
	global_load_dword v192, v[228:229], off
	global_load_dwordx2 v[122:123], v[232:233], off
	global_load_dword v159, v[230:231], off
	v_lshl_add_u64 v[180:181], s[10:11], 0, v[180:181]
	v_lshl_add_u64 v[180:181], v[180:181], 0, v[144:145]
	v_cvt_f32_i32_e32 v119, v119
	v_cvt_f32_i32_e32 v118, v118
	v_cvt_f32_i32_e32 v121, v121
	v_cvt_f32_i32_e32 v120, v120
	v_cvt_f32_i32_e32 v111, v111
	v_cvt_f32_i32_e32 v110, v110
	v_cvt_f32_i32_e32 v113, v113
	v_cvt_f32_i32_e32 v112, v112
	v_cvt_f32_i32_e32 v103, v103
	v_cvt_f32_i32_e32 v102, v102
	v_cvt_f32_i32_e32 v105, v105
	v_cvt_f32_i32_e32 v104, v104
	v_lshlrev_b64 v[152:153], 13, v[152:153]
	v_cvt_f32_i32_e32 v95, v95
	v_cvt_f32_i32_e32 v94, v94
	v_cvt_f32_i32_e32 v97, v97
	v_cvt_f32_i32_e32 v96, v96
	v_cvt_f32_i32_e32 v87, v87
	v_cvt_f32_i32_e32 v86, v86
	v_cvt_f32_i32_e32 v89, v89
	v_cvt_f32_i32_e32 v88, v88
	v_cvt_f32_i32_e32 v79, v79
	v_cvt_f32_i32_e32 v78, v78
	v_cvt_f32_i32_e32 v81, v81
	v_cvt_f32_i32_e32 v80, v80
	v_cvt_f32_i32_e32 v71, v71
	v_cvt_f32_i32_e32 v70, v70
	v_cvt_f32_i32_e32 v73, v73
	v_cvt_f32_i32_e32 v72, v72
	v_cvt_f32_i32_e32 v67, v67
	v_cvt_f32_i32_e32 v66, v66
	v_cvt_f32_i32_e32 v69, v69
	v_cvt_f32_i32_e32 v68, v68
	v_cvt_f32_i32_e32 v55, v55
	v_cvt_f32_i32_e32 v54, v54
	v_cvt_f32_i32_e32 v57, v57
	v_cvt_f32_i32_e32 v56, v56
	v_cvt_f32_i32_e32 v51, v51
	v_cvt_f32_i32_e32 v50, v50
	v_cvt_f32_i32_e32 v53, v53
	s_waitcnt vmcnt(0)
	v_mul_f32_e32 v151, 0x3c010204, v185
	v_mul_f32_e32 v190, 0x3fb504f3, v155
	v_mul_f32_e32 v186, v151, v186
	v_cvt_f32_i32_e32 v52, v52
	v_cvt_f32_i32_e32 v47, v47
	v_cvt_f32_i32_e32 v46, v46
	v_cvt_f32_i32_e32 v49, v49
	v_pk_mul_f32 v[162:163], v[162:163], s[90:91] op_sel_hi:[1,0]
	v_pk_mul_f32 v[166:167], v[166:167], s[90:91] op_sel_hi:[1,0]
	v_pk_mul_f32 v[164:165], v[164:165], s[90:91] op_sel_hi:[1,0]
	v_cvt_f32_f16_sdwa v155, v176 dst_sel:DWORD dst_unused:UNUSED_PAD src0_sel:WORD_1
	v_cvt_f32_f16_e32 v185, v176
	v_cvt_f32_f16_sdwa v225, v177 dst_sel:DWORD dst_unused:UNUSED_PAD src0_sel:WORD_1
	v_cvt_f32_f16_e32 v176, v177
	v_cvt_f32_f16_sdwa v229, v178 dst_sel:DWORD dst_unused:UNUSED_PAD src0_sel:WORD_1
	v_cvt_f32_f16_e32 v228, v178
	v_cvt_f32_f16_sdwa v227, v179 dst_sel:DWORD dst_unused:UNUSED_PAD src0_sel:WORD_1
	v_cvt_f32_f16_e32 v226, v179
	v_pk_mul_f32 v[160:161], v[160:161], s[90:91] op_sel_hi:[1,0]
	v_pk_mul_f32 v[174:175], v[190:191], v[174:175] op_sel_hi:[0,1]
	v_pk_mul_f32 v[172:173], v[190:191], v[172:173] op_sel_hi:[0,1]
	v_pk_mul_f32 v[170:171], v[190:191], v[170:171] op_sel_hi:[0,1]
	v_pk_mul_f32 v[168:169], v[190:191], v[168:169] op_sel_hi:[0,1]
	v_sub_f32_e32 v176, v176, v154
	v_sub_f32_e32 v177, v225, v154
	v_sub_f32_e32 v178, v185, v154
	v_sub_f32_e32 v179, v155, v154
	v_sub_f32_e32 v226, v226, v154
	v_sub_f32_e32 v227, v227, v154
	v_sub_f32_e32 v228, v228, v154
	v_sub_f32_e32 v229, v229, v154
	v_pk_fma_f32 v[164:165], v[178:179], v[172:173], v[164:165]
	v_pk_fma_f32 v[166:167], v[176:177], v[174:175], v[166:167]
	v_pk_fma_f32 v[160:161], v[228:229], v[168:169], v[160:161]
	v_pk_fma_f32 v[162:163], v[226:227], v[170:171], v[162:163]
	v_pk_fma_f32 v[166:167], v[186:187], v[204:205], v[166:167] op_sel_hi:[0,1,1]
	v_pk_fma_f32 v[164:165], v[186:187], v[202:203], v[164:165] op_sel_hi:[0,1,1]
	v_pk_fma_f32 v[168:169], v[186:187], v[208:209], v[162:163] op_sel_hi:[0,1,1]
	v_pk_fma_f32 v[162:163], v[186:187], v[206:207], v[160:161] op_sel_hi:[0,1,1]
; __device__ __forceinline__ u32x4 pk8h(const f32x4 a, const f32x4 b) { u32x4 w; w.x = pkh(a[0], a[1]); w.y = pkh(a[2], a[3]); w.z = pkh(b[0], b[1]); w.w = pkh(b[2], b[3]); return w; }
; __device__ __forceinline__ f32x4 h4lo(const u32x4 w) { return (f32x4){hlo(w.x), hhi(w.x), hlo(w.y), hhi(w.y)}; }
; __device__ __forceinline__ f32x4 h4hi(const u32x4 w) { return (f32x4){hlo(w.z), hhi(w.z), hlo(w.w), hhi(w.w)}; }
;     __device__ __forceinline__ void operator()(const i32x4 (&acc)[2][2][4][2], const Unit& u, int wr, int wc, int fr, int fq) const {
;     ...
;             for (int m = 0; m < 4; ++m) { const int row = row0 + ai * HALF + m * 16; const bf16_t* yp = X + (size_t)row * 4096 + col0; y[m][0] = *(const u32x4*)yp; y[m][1] = *(const u32x4*)(yp + HALF);
;                 mean[m] = stats[2 * row]; rstd[m] = stats[2 * row + 1]; f[m] = rowinv[row] * wdq; }
; #pragma unroll
;             for (int m = 0; m < 4; ++m) { bf16_t* rowp = X + (size_t)(row0 + ai * HALF + m * 16) * 4096 + col0;
; #pragma unroll
;                 for (int bj = 0; bj < 2; ++bj) { const int c = col0 + bj * HALF; const float ra = rstd[m] * alpha;
;                     const f32x4 g0 = *(const f32x4*)(g + c) * ra, g1 = *(const f32x4*)(g + c + 4) * ra, b0 = *(const f32x4*)(b + c) * alpha, b1 = *(const f32x4*)(b + c + 4) * alpha;
;                     const i32x4 a0 = acc[ai][bj][m][0], a1 = acc[ai][bj][m][1];
;                     f32x4 q0, q1; q0.x = (float)a0.x; q0.y = (float)a0.y; q0.z = (float)a0.z; q0.w = (float)a0.w; q1.x = (float)a1.x; q1.y = (float)a1.y; q1.z = (float)a1.z; q1.w = (float)a1.w;
;                     *(u32x4*)(rowp + bj * HALF) = pk8h((h4lo(y[m][bj]) - mean[m]) * g0 + b0 + q0 * f[m], (h4hi(y[m][bj]) - mean[m]) * g1 + b1 + q1 * f[m]); } }
	v_cvt_pk_f16_f32 v160, v164, v165
	v_cvt_pk_f16_f32 v161, v166, v167
	v_cvt_pk_f16_f32 v162, v162, v163
	v_cvt_pk_f16_f32 v163, v168, v169
	global_store_dwordx4 v[180:181], v[160:163], off nt
	global_load_dwordx4 v[160:163], v[142:143], off offset:512
	s_nop 0
	global_load_dwordx4 v[164:167], v[142:143], off offset:528
	global_load_dwordx4 v[168:171], v[140:141], off offset:512
	global_load_dwordx4 v[172:175], v[140:141], off offset:528
	v_lshlrev_b64 v[202:203], 13, v[210:211]
	v_cvt_f32_f16_sdwa v155, v198 dst_sel:DWORD dst_unused:UNUSED_PAD src0_sel:WORD_1
	v_cvt_f32_f16_e32 v185, v198
	v_cvt_f32_f16_sdwa v206, v199 dst_sel:DWORD dst_unused:UNUSED_PAD src0_sel:WORD_1
	v_cvt_f32_f16_e32 v198, v199
	v_cvt_f32_f16_sdwa v209, v200 dst_sel:DWORD dst_unused:UNUSED_PAD src0_sel:WORD_1
	v_cvt_f32_f16_e32 v208, v200
	v_cvt_f32_f16_sdwa v207, v201 dst_sel:DWORD dst_unused:UNUSED_PAD src0_sel:WORD_1
	v_cvt_f32_f16_e32 v210, v201
	v_cvt_f32_i32_e32 v177, v115
	v_cvt_f32_i32_e32 v176, v114
	v_cvt_f32_i32_e32 v179, v117
	v_cvt_f32_i32_e32 v178, v116
	v_lshl_add_u64 v[204:205], v[146:147], 0, v[202:203]
	v_sub_f32_e32 v198, v198, v154
	v_sub_f32_e32 v199, v206, v154
	v_sub_f32_e32 v200, v185, v154
	v_sub_f32_e32 v201, v155, v154
	v_sub_f32_e32 v206, v210, v154
	v_sub_f32_e32 v207, v207, v154
	v_sub_f32_e32 v208, v208, v154
	v_sub_f32_e32 v209, v209, v154
	global_load_dwordx4 v[114:117], v[204:205], off
	v_cvt_f32_i32_e32 v48, v48
	v_cvt_f32_i32_e32 v43, v43
	v_cvt_f32_i32_e32 v42, v42
	v_cvt_f32_i32_e32 v45, v45
	v_cvt_f32_i32_e32 v44, v44
	v_cvt_f32_i32_e32 v39, v39
	v_cvt_f32_i32_e32 v38, v38
	v_cvt_f32_i32_e32 v41, v41
	v_cvt_f32_i32_e32 v40, v40
	v_cvt_f32_i32_e32 v31, v31
	v_cvt_f32_i32_e32 v30, v30
	v_cvt_f32_i32_e32 v33, v33
	v_cvt_f32_i32_e32 v32, v32
	v_cvt_f32_i32_e32 v23, v23
	v_cvt_f32_i32_e32 v22, v22
	v_cvt_f32_i32_e32 v25, v25
	v_cvt_f32_i32_e32 v24, v24
	v_cvt_f32_i32_e32 v19, v19
	v_cvt_f32_i32_e32 v18, v18
	v_cvt_f32_i32_e32 v21, v21
	v_cvt_f32_i32_e32 v20, v20
	v_cvt_f32_i32_e32 v15, v15
	v_cvt_f32_i32_e32 v14, v14
	v_cvt_f32_i32_e32 v17, v17
	v_cvt_f32_i32_e32 v16, v16
	v_cvt_f32_i32_e32 v11, v11
	v_cvt_f32_i32_e32 v10, v10
	v_cvt_f32_i32_e32 v13, v13
	v_cvt_f32_i32_e32 v12, v12
	v_cvt_f32_i32_e32 v7, v7
	v_cvt_f32_i32_e32 v6, v6
	v_cvt_f32_i32_e32 v9, v9
	v_cvt_f32_i32_e32 v8, v8
	v_cvt_f32_i32_e32 v3, v3
	v_cvt_f32_i32_e32 v2, v2
	v_cvt_f32_i32_e32 v5, v5
	v_cvt_f32_i32_e32 v4, v4
	v_readlane_b32 s34, v251, 3
	s_and_b64 vcc, exec, s[4:5]
	s_mov_b64 s[4:5], -1
	v_readlane_b32 s35, v251, 4
	s_waitcnt vmcnt(4)
	v_pk_mul_f32 v[154:155], v[190:191], v[162:163] op_sel_hi:[0,1]
	v_pk_mul_f32 v[160:161], v[190:191], v[160:161] op_sel_hi:[0,1]
	s_waitcnt vmcnt(3)
	v_pk_mul_f32 v[162:163], v[190:191], v[166:167] op_sel_hi:[0,1]
	v_pk_mul_f32 v[164:165], v[190:191], v[164:165] op_sel_hi:[0,1]
	s_waitcnt vmcnt(2)
	v_pk_mul_f32 v[166:167], v[170:171], s[90:91] op_sel_hi:[1,0]
	v_pk_mul_f32 v[168:169], v[168:169], s[90:91] op_sel_hi:[1,0]
	s_waitcnt vmcnt(1)
	v_pk_mul_f32 v[170:171], v[174:175], s[90:91] op_sel_hi:[1,0]
	v_pk_mul_f32 v[172:173], v[172:173], s[90:91] op_sel_hi:[1,0]
	v_pk_fma_f32 v[160:161], v[200:201], v[160:161], v[168:169]
	v_pk_fma_f32 v[154:155], v[198:199], v[154:155], v[166:167]
	v_pk_fma_f32 v[164:165], v[208:209], v[164:165], v[172:173]
	v_pk_fma_f32 v[162:163], v[206:207], v[162:163], v[170:171]
	v_pk_fma_f32 v[120:121], v[186:187], v[120:121], v[154:155] op_sel_hi:[0,1,1]
	v_pk_fma_f32 v[118:119], v[186:187], v[118:119], v[160:161] op_sel_hi:[0,1,1]
	v_pk_fma_f32 v[154:155], v[186:187], v[178:179], v[162:163] op_sel_hi:[0,1,1]
	v_pk_fma_f32 v[160:161], v[186:187], v[176:177], v[164:165] op_sel_hi:[0,1,1]
	v_cvt_pk_f16_f32 v118, v118, v119
	v_cvt_pk_f16_f32 v119, v120, v121
	v_cvt_pk_f16_f32 v120, v160, v161
	v_cvt_pk_f16_f32 v121, v154, v155
	global_store_dwordx4 v[180:181], v[118:121], off offset:256 nt
	global_load_dwordx4 v[118:121], v[142:143], off
	s_nop 0
	global_load_dwordx4 v[160:163], v[142:143], off offset:16
	global_load_dwordx4 v[164:167], v[140:141], off
	global_load_dwordx4 v[168:171], v[140:141], off offset:16
	v_mul_f32_e32 v178, 0x3fb504f3, v129
	v_cvt_f32_i32_e32 v155, v107
	v_cvt_f32_i32_e32 v154, v106
	v_cvt_f32_i32_e32 v173, v109
	s_waitcnt vmcnt(5)
	v_cvt_f32_f16_sdwa v129, v114 dst_sel:DWORD dst_unused:UNUSED_PAD src0_sel:WORD_1
	v_cvt_f32_f16_e32 v177, v114
	v_cvt_f32_f16_sdwa v179, v115 dst_sel:DWORD dst_unused:UNUSED_PAD src0_sel:WORD_1
	v_cvt_f32_f16_e32 v114, v115
	v_cvt_f32_f16_sdwa v185, v116 dst_sel:DWORD dst_unused:UNUSED_PAD src0_sel:WORD_1
	v_cvt_f32_f16_e32 v186, v116
	v_cvt_f32_f16_sdwa v181, v117 dst_sel:DWORD dst_unused:UNUSED_PAD src0_sel:WORD_1
	v_cvt_f32_f16_e32 v180, v117
	v_cvt_f32_i32_e32 v172, v108
	v_sub_f32_e32 v114, v114, v128
	v_sub_f32_e32 v115, v179, v128
	v_sub_f32_e32 v116, v177, v128
	v_sub_f32_e32 v117, v129, v128
	v_sub_f32_e32 v180, v180, v128
	v_sub_f32_e32 v181, v181, v128
	v_sub_f32_e32 v198, v186, v128
	v_sub_f32_e32 v199, v185, v128
	global_load_dwordx4 v[106:109], v[204:205], off offset:256
	v_mul_f32_e32 v176, v151, v189
	v_lshl_add_u64 v[174:175], s[10:11], 0, v[202:203]
	v_lshl_add_u64 v[174:175], v[174:175], 0, v[144:145]
	s_waitcnt vmcnt(4)
	v_pk_mul_f32 v[120:121], v[178:179], v[120:121] op_sel_hi:[0,1]
	v_pk_mul_f32 v[118:119], v[178:179], v[118:119] op_sel_hi:[0,1]
	s_waitcnt vmcnt(3)
	v_pk_mul_f32 v[162:163], v[178:179], v[162:163] op_sel_hi:[0,1]
	v_pk_mul_f32 v[160:161], v[178:179], v[160:161] op_sel_hi:[0,1]
	s_waitcnt vmcnt(2)
	v_pk_mul_f32 v[166:167], v[166:167], s[90:91] op_sel_hi:[1,0]
	v_pk_mul_f32 v[164:165], v[164:165], s[90:91] op_sel_hi:[1,0]
	s_waitcnt vmcnt(1)
; __device__ __forceinline__ u32x4 pk8h(const f32x4 a, const f32x4 b) { u32x4 w; w.x = pkh(a[0], a[1]); w.y = pkh(a[2], a[3]); w.z = pkh(b[0], b[1]); w.w = pkh(b[2], b[3]); return w; }
; __device__ __forceinline__ f32x4 h4lo(const u32x4 w) { return (f32x4){hlo(w.x), hhi(w.x), hlo(w.y), hhi(w.y)}; }
; __device__ __forceinline__ f32x4 h4hi(const u32x4 w) { return (f32x4){hlo(w.z), hhi(w.z), hlo(w.w), hhi(w.w)}; }
;     __device__ __forceinline__ void operator()(const i32x4 (&acc)[2][2][4][2], const Unit& u, int wr, int wc, int fr, int fq) const {
;     ...
;             for (int m = 0; m < 4; ++m) { const int row = row0 + ai * HALF + m * 16; const bf16_t* yp = X + (size_t)row * 4096 + col0; y[m][0] = *(const u32x4*)yp; y[m][1] = *(const u32x4*)(yp + HALF);
;                 mean[m] = stats[2 * row]; rstd[m] = stats[2 * row + 1]; f[m] = rowinv[row] * wdq; }
; #pragma unroll
;             for (int m = 0; m < 4; ++m) { bf16_t* rowp = X + (size_t)(row0 + ai * HALF + m * 16) * 4096 + col0;
; #pragma unroll
;                 for (int bj = 0; bj < 2; ++bj) { const int c = col0 + bj * HALF; const float ra = rstd[m] * alpha;
;                     const f32x4 g0 = *(const f32x4*)(g + c) * ra, g1 = *(const f32x4*)(g + c + 4) * ra, b0 = *(const f32x4*)(b + c) * alpha, b1 = *(const f32x4*)(b + c + 4) * alpha;
;                     const i32x4 a0 = acc[ai][bj][m][0], a1 = acc[ai][bj][m][1];
;                     f32x4 q0, q1; q0.x = (float)a0.x; q0.y = (float)a0.y; q0.z = (float)a0.z; q0.w = (float)a0.w; q1.x = (float)a1.x; q1.y = (float)a1.y; q1.z = (float)a1.z; q1.w = (float)a1.w;
;                     *(u32x4*)(rowp + bj * HALF) = pk8h((h4lo(y[m][bj]) - mean[m]) * g0 + b0 + q0 * f[m], (h4hi(y[m][bj]) - mean[m]) * g1 + b1 + q1 * f[m]); } }
	v_pk_mul_f32 v[170:171], v[170:171], s[90:91] op_sel_hi:[1,0]
	v_pk_mul_f32 v[168:169], v[168:169], s[90:91] op_sel_hi:[1,0]
	v_pk_fma_f32 v[116:117], v[116:117], v[118:119], v[164:165]
	v_pk_fma_f32 v[114:115], v[114:115], v[120:121], v[166:167]
	v_pk_fma_f32 v[118:119], v[198:199], v[160:161], v[168:169]
	v_pk_fma_f32 v[120:121], v[180:181], v[162:163], v[170:171]
	v_pk_fma_f32 v[112:113], v[176:177], v[112:113], v[114:115] op_sel_hi:[0,1,1]
	v_pk_fma_f32 v[110:111], v[176:177], v[110:111], v[116:117] op_sel_hi:[0,1,1]
	v_pk_fma_f32 v[114:115], v[176:177], v[172:173], v[120:121] op_sel_hi:[0,1,1]
	v_pk_fma_f32 v[116:117], v[176:177], v[154:155], v[118:119] op_sel_hi:[0,1,1]
	v_cvt_pk_f16_f32 v110, v110, v111
	v_cvt_pk_f16_f32 v111, v112, v113
	v_cvt_pk_f16_f32 v112, v116, v117
	v_cvt_pk_f16_f32 v113, v114, v115
	global_store_dwordx4 v[174:175], v[110:113], off nt
	global_load_dwordx4 v[110:113], v[142:143], off offset:512
	s_nop 0
	global_load_dwordx4 v[114:117], v[142:143], off offset:528
	global_load_dwordx4 v[118:121], v[140:141], off offset:512
	global_load_dwordx4 v[160:163], v[140:141], off offset:528
	v_cvt_f32_i32_e32 v155, v99
	v_cvt_f32_i32_e32 v154, v98
	v_cvt_f32_i32_e32 v165, v101
	s_waitcnt vmcnt(5)
	v_cvt_f32_f16_sdwa v129, v106 dst_sel:DWORD dst_unused:UNUSED_PAD src0_sel:WORD_1
	v_cvt_f32_f16_e32 v168, v106
	v_cvt_f32_f16_sdwa v169, v107 dst_sel:DWORD dst_unused:UNUSED_PAD src0_sel:WORD_1
	v_cvt_f32_f16_e32 v106, v107
	v_cvt_f32_f16_sdwa v171, v108 dst_sel:DWORD dst_unused:UNUSED_PAD src0_sel:WORD_1
	v_cvt_f32_f16_e32 v170, v108
	v_cvt_f32_f16_sdwa v172, v109 dst_sel:DWORD dst_unused:UNUSED_PAD src0_sel:WORD_1
	v_cvt_f32_f16_e32 v173, v109
	v_cvt_f32_i32_e32 v164, v100
	v_lshl_add_u64 v[166:167], v[146:147], 0, v[152:153]
	v_sub_f32_e32 v106, v106, v128
	v_sub_f32_e32 v107, v169, v128
	v_sub_f32_e32 v108, v168, v128
	v_sub_f32_e32 v109, v129, v128
	v_sub_f32_e32 v168, v173, v128
	v_sub_f32_e32 v169, v172, v128
	v_sub_f32_e32 v170, v170, v128
	v_sub_f32_e32 v171, v171, v128
	global_load_dwordx4 v[98:101], v[166:167], off
	s_waitcnt vmcnt(4)
	v_pk_mul_f32 v[112:113], v[178:179], v[112:113] op_sel_hi:[0,1]
	v_pk_mul_f32 v[110:111], v[178:179], v[110:111] op_sel_hi:[0,1]
	s_waitcnt vmcnt(3)
	v_pk_mul_f32 v[116:117], v[178:179], v[116:117] op_sel_hi:[0,1]
	v_pk_mul_f32 v[114:115], v[178:179], v[114:115] op_sel_hi:[0,1]
	s_waitcnt vmcnt(2)
	v_pk_mul_f32 v[120:121], v[120:121], s[90:91] op_sel_hi:[1,0]
	v_pk_mul_f32 v[118:119], v[118:119], s[90:91] op_sel_hi:[1,0]
	s_waitcnt vmcnt(1)
	v_pk_mul_f32 v[128:129], v[162:163], s[90:91] op_sel_hi:[1,0]
	v_pk_mul_f32 v[160:161], v[160:161], s[90:91] op_sel_hi:[1,0]
	v_pk_fma_f32 v[108:109], v[108:109], v[110:111], v[118:119]
	v_pk_fma_f32 v[106:107], v[106:107], v[112:113], v[120:121]
	v_pk_fma_f32 v[110:111], v[170:171], v[114:115], v[160:161]
	v_pk_fma_f32 v[112:113], v[168:169], v[116:117], v[128:129]
	v_pk_fma_f32 v[104:105], v[176:177], v[104:105], v[106:107] op_sel_hi:[0,1,1]
	v_pk_fma_f32 v[102:103], v[176:177], v[102:103], v[108:109] op_sel_hi:[0,1,1]
	v_pk_fma_f32 v[106:107], v[176:177], v[164:165], v[112:113] op_sel_hi:[0,1,1]
	v_pk_fma_f32 v[108:109], v[176:177], v[154:155], v[110:111] op_sel_hi:[0,1,1]
	v_cvt_pk_f16_f32 v102, v102, v103
	v_cvt_pk_f16_f32 v103, v104, v105
	v_cvt_pk_f16_f32 v104, v108, v109
	v_cvt_pk_f16_f32 v105, v106, v107
	global_store_dwordx4 v[174:175], v[102:105], off offset:256 nt
	global_load_dwordx4 v[102:105], v[142:143], off
	s_nop 0
	global_load_dwordx4 v[106:109], v[142:143], off offset:16
	global_load_dwordx4 v[110:113], v[140:141], off
	global_load_dwordx4 v[114:117], v[140:141], off offset:16
	v_lshl_add_u64 v[128:129], s[10:11], 0, v[152:153]
	v_mul_f32_e32 v154, 0x3fb504f3, v125
	v_cvt_f32_i32_e32 v119, v91
	s_waitcnt vmcnt(5)
	v_cvt_f32_f16_sdwa v125, v98 dst_sel:DWORD dst_unused:UNUSED_PAD src0_sel:WORD_1
	v_cvt_f32_f16_e32 v153, v98
	v_cvt_f32_f16_sdwa v155, v99 dst_sel:DWORD dst_unused:UNUSED_PAD src0_sel:WORD_1
	v_cvt_f32_f16_e32 v98, v99
	v_cvt_f32_f16_sdwa v163, v100 dst_sel:DWORD dst_unused:UNUSED_PAD src0_sel:WORD_1
	v_cvt_f32_f16_e32 v162, v100
	v_cvt_f32_f16_sdwa v161, v101 dst_sel:DWORD dst_unused:UNUSED_PAD src0_sel:WORD_1
	v_cvt_f32_f16_e32 v160, v101
	v_cvt_f32_i32_e32 v118, v90
	v_cvt_f32_i32_e32 v121, v93
	v_cvt_f32_i32_e32 v120, v92
	v_sub_f32_e32 v98, v98, v124
	v_sub_f32_e32 v99, v155, v124
	v_sub_f32_e32 v100, v153, v124
	v_sub_f32_e32 v101, v125, v124
	v_sub_f32_e32 v160, v160, v124
	v_sub_f32_e32 v161, v161, v124
	v_sub_f32_e32 v162, v162, v124
	v_sub_f32_e32 v163, v163, v124
	global_load_dwordx4 v[90:93], v[166:167], off offset:256
	v_mul_f32_e32 v152, v151, v192
	v_lshl_add_u64 v[128:129], v[128:129], 0, v[144:145]
	s_waitcnt vmcnt(4)
	v_pk_mul_f32 v[104:105], v[154:155], v[104:105] op_sel_hi:[0,1]
	v_pk_mul_f32 v[102:103], v[154:155], v[102:103] op_sel_hi:[0,1]
	s_waitcnt vmcnt(3)
	v_pk_mul_f32 v[108:109], v[154:155], v[108:109] op_sel_hi:[0,1]
	v_pk_mul_f32 v[106:107], v[154:155], v[106:107] op_sel_hi:[0,1]
	s_waitcnt vmcnt(2)
	v_pk_mul_f32 v[112:113], v[112:113], s[90:91] op_sel_hi:[1,0]
	v_pk_mul_f32 v[110:111], v[110:111], s[90:91] op_sel_hi:[1,0]
	s_waitcnt vmcnt(1)
; __device__ __forceinline__ u32x4 pk8h(const f32x4 a, const f32x4 b) { u32x4 w; w.x = pkh(a[0], a[1]); w.y = pkh(a[2], a[3]); w.z = pkh(b[0], b[1]); w.w = pkh(b[2], b[3]); return w; }
; __device__ __forceinline__ f32x4 h4lo(const u32x4 w) { return (f32x4){hlo(w.x), hhi(w.x), hlo(w.y), hhi(w.y)}; }
; __device__ __forceinline__ f32x4 h4hi(const u32x4 w) { return (f32x4){hlo(w.z), hhi(w.z), hlo(w.w), hhi(w.w)}; }
;     __device__ __forceinline__ void operator()(const i32x4 (&acc)[2][2][4][2], const Unit& u, int wr, int wc, int fr, int fq) const {
;     ...
;             for (int m = 0; m < 4; ++m) { const int row = row0 + ai * HALF + m * 16; const bf16_t* yp = X + (size_t)row * 4096 + col0; y[m][0] = *(const u32x4*)yp; y[m][1] = *(const u32x4*)(yp + HALF);
;                 mean[m] = stats[2 * row]; rstd[m] = stats[2 * row + 1]; f[m] = rowinv[row] * wdq; }
; #pragma unroll
;             for (int m = 0; m < 4; ++m) { bf16_t* rowp = X + (size_t)(row0 + ai * HALF + m * 16) * 4096 + col0;
; #pragma unroll
;                 for (int bj = 0; bj < 2; ++bj) { const int c = col0 + bj * HALF; const float ra = rstd[m] * alpha;
;                     const f32x4 g0 = *(const f32x4*)(g + c) * ra, g1 = *(const f32x4*)(g + c + 4) * ra, b0 = *(const f32x4*)(b + c) * alpha, b1 = *(const f32x4*)(b + c + 4) * alpha;
;                     const i32x4 a0 = acc[ai][bj][m][0], a1 = acc[ai][bj][m][1];
;                     f32x4 q0, q1; q0.x = (float)a0.x; q0.y = (float)a0.y; q0.z = (float)a0.z; q0.w = (float)a0.w; q1.x = (float)a1.x; q1.y = (float)a1.y; q1.z = (float)a1.z; q1.w = (float)a1.w;
;                     *(u32x4*)(rowp + bj * HALF) = pk8h((h4lo(y[m][bj]) - mean[m]) * g0 + b0 + q0 * f[m], (h4hi(y[m][bj]) - mean[m]) * g1 + b1 + q1 * f[m]); } }
	v_pk_mul_f32 v[116:117], v[116:117], s[90:91] op_sel_hi:[1,0]
	v_pk_mul_f32 v[114:115], v[114:115], s[90:91] op_sel_hi:[1,0]
	v_pk_fma_f32 v[100:101], v[100:101], v[102:103], v[110:111]
	v_pk_fma_f32 v[98:99], v[98:99], v[104:105], v[112:113]
	v_pk_fma_f32 v[102:103], v[162:163], v[106:107], v[114:115]
	v_pk_fma_f32 v[104:105], v[160:161], v[108:109], v[116:117]
	v_pk_fma_f32 v[96:97], v[152:153], v[96:97], v[98:99] op_sel_hi:[0,1,1]
	v_pk_fma_f32 v[94:95], v[152:153], v[94:95], v[100:101] op_sel_hi:[0,1,1]
	v_pk_fma_f32 v[98:99], v[152:153], v[120:121], v[104:105] op_sel_hi:[0,1,1]
	v_pk_fma_f32 v[100:101], v[152:153], v[118:119], v[102:103] op_sel_hi:[0,1,1]
	v_cvt_pk_f16_f32 v94, v94, v95
	v_cvt_pk_f16_f32 v95, v96, v97
	v_cvt_pk_f16_f32 v96, v100, v101
	v_cvt_pk_f16_f32 v97, v98, v99
	global_store_dwordx4 v[128:129], v[94:97], off nt
	global_load_dwordx4 v[94:97], v[142:143], off offset:512
	s_nop 0
	global_load_dwordx4 v[98:101], v[142:143], off offset:528
	global_load_dwordx4 v[102:105], v[140:141], off offset:512
	global_load_dwordx4 v[106:109], v[140:141], off offset:528
	v_lshlrev_b64 v[114:115], 13, v[126:127]
	v_cvt_f32_i32_e32 v111, v83
	v_cvt_f32_i32_e32 v110, v82
	v_cvt_f32_i32_e32 v113, v85
	s_waitcnt vmcnt(5)
	v_cvt_f32_f16_sdwa v118, v90 dst_sel:DWORD dst_unused:UNUSED_PAD src0_sel:WORD_1
	v_cvt_f32_f16_e32 v119, v90
	v_cvt_f32_f16_sdwa v120, v91 dst_sel:DWORD dst_unused:UNUSED_PAD src0_sel:WORD_1
	v_cvt_f32_f16_e32 v90, v91
	v_cvt_f32_f16_sdwa v121, v92 dst_sel:DWORD dst_unused:UNUSED_PAD src0_sel:WORD_1
	v_cvt_f32_f16_e32 v125, v92
	v_cvt_f32_f16_sdwa v126, v93 dst_sel:DWORD dst_unused:UNUSED_PAD src0_sel:WORD_1
	v_cvt_f32_f16_e32 v127, v93
	v_cvt_f32_i32_e32 v112, v84
	v_lshl_add_u64 v[116:117], v[146:147], 0, v[114:115]
	v_sub_f32_e32 v90, v90, v124
	v_sub_f32_e32 v91, v120, v124
	v_sub_f32_e32 v92, v119, v124
	v_sub_f32_e32 v93, v118, v124
	v_sub_f32_e32 v118, v127, v124
	v_sub_f32_e32 v119, v126, v124
	v_sub_f32_e32 v120, v125, v124
	v_sub_f32_e32 v121, v121, v124
	global_load_dwordx4 v[82:85], v[116:117], off
	s_waitcnt vmcnt(4)
	v_pk_mul_f32 v[96:97], v[154:155], v[96:97] op_sel_hi:[0,1]
	v_pk_mul_f32 v[94:95], v[154:155], v[94:95] op_sel_hi:[0,1]
	s_waitcnt vmcnt(3)
	v_pk_mul_f32 v[100:101], v[154:155], v[100:101] op_sel_hi:[0,1]
	v_pk_mul_f32 v[98:99], v[154:155], v[98:99] op_sel_hi:[0,1]
	s_waitcnt vmcnt(2)
	v_pk_mul_f32 v[104:105], v[104:105], s[90:91] op_sel_hi:[1,0]
	v_pk_mul_f32 v[102:103], v[102:103], s[90:91] op_sel_hi:[1,0]
	s_waitcnt vmcnt(1)
	v_pk_mul_f32 v[108:109], v[108:109], s[90:91] op_sel_hi:[1,0]
	v_pk_mul_f32 v[106:107], v[106:107], s[90:91] op_sel_hi:[1,0]
	v_pk_fma_f32 v[92:93], v[92:93], v[94:95], v[102:103]
	v_pk_fma_f32 v[90:91], v[90:91], v[96:97], v[104:105]
	v_pk_fma_f32 v[94:95], v[120:121], v[98:99], v[106:107]
	v_pk_fma_f32 v[96:97], v[118:119], v[100:101], v[108:109]
	v_pk_fma_f32 v[88:89], v[152:153], v[88:89], v[90:91] op_sel_hi:[0,1,1]
	v_pk_fma_f32 v[86:87], v[152:153], v[86:87], v[92:93] op_sel_hi:[0,1,1]
	v_pk_fma_f32 v[90:91], v[152:153], v[112:113], v[96:97] op_sel_hi:[0,1,1]
	v_pk_fma_f32 v[92:93], v[152:153], v[110:111], v[94:95] op_sel_hi:[0,1,1]
	v_cvt_pk_f16_f32 v86, v86, v87
	v_cvt_pk_f16_f32 v87, v88, v89
	v_cvt_pk_f16_f32 v88, v92, v93
	v_cvt_pk_f16_f32 v89, v90, v91
	global_store_dwordx4 v[128:129], v[86:89], off offset:256 nt
	global_load_dwordx4 v[86:89], v[142:143], off
	s_nop 0
	global_load_dwordx4 v[90:93], v[142:143], off offset:16
	global_load_dwordx4 v[94:97], v[140:141], off
	global_load_dwordx4 v[98:101], v[140:141], off offset:16
	v_cvt_f32_i32_e32 v103, v75
	v_cvt_f32_i32_e32 v102, v74
	v_cvt_f32_i32_e32 v105, v77
	v_cvt_f32_i32_e32 v104, v76
	v_lshl_add_u64 v[106:107], s[10:11], 0, v[114:115]
	global_load_dwordx4 v[74:77], v[116:117], off offset:256
	s_waitcnt vmcnt(6)
	v_cvt_f32_f16_sdwa v109, v82 dst_sel:DWORD dst_unused:UNUSED_PAD src0_sel:WORD_1
	v_cvt_f32_f16_e32 v111, v82
	v_cvt_f32_f16_sdwa v112, v83 dst_sel:DWORD dst_unused:UNUSED_PAD src0_sel:WORD_1
	v_cvt_f32_f16_e32 v82, v83
	v_cvt_f32_f16_sdwa v115, v84 dst_sel:DWORD dst_unused:UNUSED_PAD src0_sel:WORD_1
	v_cvt_f32_f16_e32 v114, v84
	v_cvt_f32_f16_sdwa v113, v85 dst_sel:DWORD dst_unused:UNUSED_PAD src0_sel:WORD_1
	v_cvt_f32_f16_e32 v116, v85
	v_mul_f32_e32 v110, 0x3fb504f3, v123
	v_sub_f32_e32 v82, v82, v122
	v_sub_f32_e32 v83, v112, v122
	v_sub_f32_e32 v84, v111, v122
	v_sub_f32_e32 v85, v109, v122
	v_sub_f32_e32 v112, v116, v122
	v_sub_f32_e32 v113, v113, v122
	v_sub_f32_e32 v114, v114, v122
	v_sub_f32_e32 v115, v115, v122
	v_mul_f32_e32 v108, v151, v159
	v_lshl_add_u64 v[106:107], v[106:107], 0, v[144:145]
	v_cvt_f32_i32_e32 v116, v58
	v_cvt_f32_i32_e32 v120, v60
	v_add_u32_e32 v58, 0x90, v150
	v_add_u32_e32 v60, 0xb0, v150
	v_cvt_f32_i32_e32 v118, v64
	v_cvt_f32_i32_e32 v117, v59
	v_cvt_f32_i32_e32 v121, v61
	v_ashrrev_i32_e32 v59, 31, v58
	v_ashrrev_i32_e32 v61, 31, v60
	v_cvt_f32_i32_e32 v119, v65
	s_waitcnt vmcnt(4)
	v_pk_mul_f32 v[88:89], v[110:111], v[88:89] op_sel_hi:[0,1]
	v_pk_mul_f32 v[86:87], v[110:111], v[86:87] op_sel_hi:[0,1]
	s_waitcnt vmcnt(3)
	v_pk_mul_f32 v[92:93], v[110:111], v[92:93] op_sel_hi:[0,1]
	v_pk_mul_f32 v[90:91], v[110:111], v[90:91] op_sel_hi:[0,1]
	s_waitcnt vmcnt(2)
	v_pk_mul_f32 v[96:97], v[96:97], s[90:91] op_sel_hi:[1,0]
	v_pk_mul_f32 v[94:95], v[94:95], s[90:91] op_sel_hi:[1,0]
	s_waitcnt vmcnt(1)
; __device__ __forceinline__ u32x4 pk8h(const f32x4 a, const f32x4 b) { u32x4 w; w.x = pkh(a[0], a[1]); w.y = pkh(a[2], a[3]); w.z = pkh(b[0], b[1]); w.w = pkh(b[2], b[3]); return w; }
; __device__ __forceinline__ f32x4 h4lo(const u32x4 w) { return (f32x4){hlo(w.x), hhi(w.x), hlo(w.y), hhi(w.y)}; }
; __device__ __forceinline__ f32x4 h4hi(const u32x4 w) { return (f32x4){hlo(w.z), hhi(w.z), hlo(w.w), hhi(w.w)}; }
;     __device__ __forceinline__ void operator()(const i32x4 (&acc)[2][2][4][2], const Unit& u, int wr, int wc, int fr, int fq) const {
;     ...
;             for (int m = 0; m < 4; ++m) { const int row = row0 + ai * HALF + m * 16; const bf16_t* yp = X + (size_t)row * 4096 + col0; y[m][0] = *(const u32x4*)yp; y[m][1] = *(const u32x4*)(yp + HALF);
;                 mean[m] = stats[2 * row]; rstd[m] = stats[2 * row + 1]; f[m] = rowinv[row] * wdq; }
; #pragma unroll
;             for (int m = 0; m < 4; ++m) { bf16_t* rowp = X + (size_t)(row0 + ai * HALF + m * 16) * 4096 + col0;
; #pragma unroll
;                 for (int bj = 0; bj < 2; ++bj) { const int c = col0 + bj * HALF; const float ra = rstd[m] * alpha;
;                     const f32x4 g0 = *(const f32x4*)(g + c) * ra, g1 = *(const f32x4*)(g + c + 4) * ra, b0 = *(const f32x4*)(b + c) * alpha, b1 = *(const f32x4*)(b + c + 4) * alpha;
;                     const i32x4 a0 = acc[ai][bj][m][0], a1 = acc[ai][bj][m][1];
;                     f32x4 q0, q1; q0.x = (float)a0.x; q0.y = (float)a0.y; q0.z = (float)a0.z; q0.w = (float)a0.w; q1.x = (float)a1.x; q1.y = (float)a1.y; q1.z = (float)a1.z; q1.w = (float)a1.w;
;                     *(u32x4*)(rowp + bj * HALF) = pk8h((h4lo(y[m][bj]) - mean[m]) * g0 + b0 + q0 * f[m], (h4hi(y[m][bj]) - mean[m]) * g1 + b1 + q1 * f[m]); } }
	v_pk_mul_f32 v[100:101], v[100:101], s[90:91] op_sel_hi:[1,0]
	v_pk_mul_f32 v[98:99], v[98:99], s[90:91] op_sel_hi:[1,0]
	v_pk_fma_f32 v[84:85], v[84:85], v[86:87], v[94:95]
	v_pk_fma_f32 v[82:83], v[82:83], v[88:89], v[96:97]
	v_pk_fma_f32 v[86:87], v[114:115], v[90:91], v[98:99]
	v_pk_fma_f32 v[88:89], v[112:113], v[92:93], v[100:101]
	v_pk_fma_f32 v[80:81], v[108:109], v[80:81], v[82:83] op_sel_hi:[0,1,1]
	v_pk_fma_f32 v[78:79], v[108:109], v[78:79], v[84:85] op_sel_hi:[0,1,1]
	v_pk_fma_f32 v[82:83], v[108:109], v[104:105], v[88:89] op_sel_hi:[0,1,1]
	v_pk_fma_f32 v[84:85], v[108:109], v[102:103], v[86:87] op_sel_hi:[0,1,1]
	v_cvt_pk_f16_f32 v78, v78, v79
	v_cvt_pk_f16_f32 v79, v80, v81
	v_cvt_pk_f16_f32 v80, v84, v85
	v_cvt_pk_f16_f32 v81, v82, v83
	global_store_dwordx4 v[106:107], v[78:81], off nt
	global_load_dwordx4 v[78:81], v[142:143], off offset:512
	s_nop 0
	global_load_dwordx4 v[82:85], v[142:143], off offset:528
	global_load_dwordx4 v[86:89], v[140:141], off offset:512
	global_load_dwordx4 v[90:93], v[140:141], off offset:528
	s_waitcnt vmcnt(5)
	v_cvt_f32_f16_sdwa v95, v74 dst_sel:DWORD dst_unused:UNUSED_PAD src0_sel:WORD_1
	v_cvt_f32_f16_e32 v98, v74
	v_cvt_f32_f16_sdwa v99, v75 dst_sel:DWORD dst_unused:UNUSED_PAD src0_sel:WORD_1
	v_cvt_f32_f16_e32 v74, v75
	v_cvt_f32_f16_sdwa v101, v76 dst_sel:DWORD dst_unused:UNUSED_PAD src0_sel:WORD_1
	v_cvt_f32_f16_e32 v100, v76
	v_cvt_f32_f16_sdwa v102, v77 dst_sel:DWORD dst_unused:UNUSED_PAD src0_sel:WORD_1
	v_cvt_f32_f16_e32 v103, v77
	v_sub_f32_e32 v74, v74, v122
	v_sub_f32_e32 v75, v99, v122
	v_sub_f32_e32 v76, v98, v122
	v_sub_f32_e32 v77, v95, v122
	v_sub_f32_e32 v98, v103, v122
	v_sub_f32_e32 v99, v102, v122
	v_sub_f32_e32 v100, v100, v122
	v_sub_f32_e32 v101, v101, v122
	v_add_u32_e32 v94, 0x80, v150
	v_lshlrev_b32_e32 v96, 1, v94
	v_ashrrev_i32_e32 v95, 31, v94
	v_ashrrev_i32_e32 v97, 31, v96
	v_lshl_add_u64 v[96:97], v[96:97], 2, s[36:37]
	v_cvt_f32_i32_e32 v114, v62
	v_lshlrev_b32_e32 v62, 1, v58
	v_cvt_f32_i32_e32 v115, v63
	v_ashrrev_i32_e32 v63, 31, v62
	s_waitcnt vmcnt(3)
	v_pk_mul_f32 v[80:81], v[110:111], v[80:81] op_sel_hi:[0,1]
	v_pk_mul_f32 v[78:79], v[110:111], v[78:79] op_sel_hi:[0,1]
	s_waitcnt vmcnt(2)
	v_pk_mul_f32 v[84:85], v[110:111], v[84:85] op_sel_hi:[0,1]
	v_pk_mul_f32 v[82:83], v[110:111], v[82:83] op_sel_hi:[0,1]
	s_waitcnt vmcnt(1)
	v_pk_mul_f32 v[88:89], v[88:89], s[90:91] op_sel_hi:[1,0]
	v_pk_mul_f32 v[86:87], v[86:87], s[90:91] op_sel_hi:[1,0]
	s_waitcnt vmcnt(0)
	v_pk_mul_f32 v[92:93], v[92:93], s[90:91] op_sel_hi:[1,0]
	v_pk_mul_f32 v[90:91], v[90:91], s[90:91] op_sel_hi:[1,0]
	v_pk_fma_f32 v[76:77], v[76:77], v[78:79], v[86:87]
	v_pk_fma_f32 v[74:75], v[74:75], v[80:81], v[88:89]
	v_pk_fma_f32 v[78:79], v[100:101], v[82:83], v[90:91]
	v_pk_fma_f32 v[80:81], v[98:99], v[84:85], v[92:93]
	v_pk_fma_f32 v[72:73], v[108:109], v[72:73], v[74:75] op_sel_hi:[0,1,1]
	v_pk_fma_f32 v[70:71], v[108:109], v[70:71], v[76:77] op_sel_hi:[0,1,1]
	v_pk_fma_f32 v[74:75], v[108:109], v[68:69], v[80:81] op_sel_hi:[0,1,1]
	v_pk_fma_f32 v[68:69], v[108:109], v[66:67], v[78:79] op_sel_hi:[0,1,1]
	v_cvt_pk_f16_f32 v66, v70, v71
	v_cvt_pk_f16_f32 v67, v72, v73
	v_cvt_pk_f16_f32 v68, v68, v69
	v_cvt_pk_f16_f32 v69, v74, v75
	global_store_dwordx4 v[106:107], v[66:69], off offset:256 nt
	v_lshlrev_b64 v[86:87], 13, v[94:95]
	v_lshl_add_u64 v[88:89], v[146:147], 0, v[86:87]
	global_load_dwordx2 v[100:101], v[96:97], off
	global_load_dword v107, v[148:149], off offset:512
	global_load_dwordx4 v[66:69], v[140:141], off offset:16
	global_load_dwordx4 v[70:73], v[140:141], off
	global_load_dwordx4 v[82:85], v[88:89], off
	global_load_dwordx4 v[78:81], v[142:143], off
	global_load_dwordx4 v[74:77], v[142:143], off offset:16
	v_add_u32_e32 v106, 0xa0, v150
	v_lshlrev_b32_e32 v64, 1, v106
	v_lshlrev_b32_e32 v90, 1, v60
	v_lshlrev_b64 v[110:111], 13, v[58:59]
	v_ashrrev_i32_e32 v65, 31, v64
	v_lshlrev_b64 v[98:99], 13, v[60:61]
	v_ashrrev_i32_e32 v91, 31, v90
	v_lshl_add_u64 v[92:93], v[146:147], 0, v[110:111]
	v_lshl_add_u64 v[96:97], v[62:63], 2, s[36:37]
	v_lshl_add_u64 v[58:59], v[64:65], 2, s[36:37]
	v_lshl_add_u64 v[94:95], v[146:147], 0, v[98:99]
	v_lshl_add_u64 v[104:105], v[90:91], 2, s[36:37]
	v_lshl_add_u64 v[60:61], s[10:11], 0, v[86:87]
	v_lshl_add_u64 v[112:113], v[60:61], 0, v[144:145]
	global_load_dwordx4 v[86:89], v[88:89], off offset:256
	s_nop 0
	global_load_dwordx4 v[62:65], v[92:93], off
	global_load_dwordx2 v[102:103], v[58:59], off
	s_nop 0
	global_load_dwordx4 v[58:61], v[94:95], off
	global_load_dword v124, v[148:149], off offset:576
	global_load_dword v123, v[148:149], off offset:640
	global_load_dword v122, v[148:149], off offset:704
	global_load_dwordx2 v[108:109], v[96:97], off
	s_nop 0
	global_load_dwordx4 v[90:93], v[92:93], off offset:256
	s_nop 0
	global_load_dwordx2 v[104:105], v[104:105], off
	s_nop 0
	global_load_dwordx4 v[94:97], v[94:95], off offset:256
	s_waitcnt vmcnt(17)
	v_mul_f32_e32 v128, 0x3fb504f3, v101
	s_waitcnt vmcnt(16)
	v_mul_f32_e32 v126, v151, v107
	s_waitcnt vmcnt(13)
	v_cvt_f32_f16_sdwa v101, v82 dst_sel:DWORD dst_unused:UNUSED_PAD src0_sel:WORD_1
	v_cvt_f32_f16_e32 v107, v82
	v_cvt_f32_f16_sdwa v125, v83 dst_sel:DWORD dst_unused:UNUSED_PAD src0_sel:WORD_1
	v_cvt_f32_f16_e32 v82, v83
	v_cvt_f32_f16_sdwa v127, v84 dst_sel:DWORD dst_unused:UNUSED_PAD src0_sel:WORD_1
	v_cvt_f32_f16_e32 v129, v84
	v_cvt_f32_f16_sdwa v149, v85 dst_sel:DWORD dst_unused:UNUSED_PAD src0_sel:WORD_1
	v_cvt_f32_f16_e32 v148, v85
	v_pk_mul_f32 v[72:73], v[72:73], s[90:91] op_sel_hi:[1,0]
	v_pk_mul_f32 v[70:71], v[70:71], s[90:91] op_sel_hi:[1,0]
	v_pk_mul_f32 v[68:69], v[68:69], s[90:91] op_sel_hi:[1,0]
	v_pk_mul_f32 v[66:67], v[66:67], s[90:91] op_sel_hi:[1,0]
	s_waitcnt vmcnt(12)
; __device__ __forceinline__ u32x4 pk8h(const f32x4 a, const f32x4 b) { u32x4 w; w.x = pkh(a[0], a[1]); w.y = pkh(a[2], a[3]); w.z = pkh(b[0], b[1]); w.w = pkh(b[2], b[3]); return w; }
; __device__ __forceinline__ f32x4 h4lo(const u32x4 w) { return (f32x4){hlo(w.x), hhi(w.x), hlo(w.y), hhi(w.y)}; }
; __device__ __forceinline__ f32x4 h4hi(const u32x4 w) { return (f32x4){hlo(w.z), hhi(w.z), hlo(w.w), hhi(w.w)}; }
;     __device__ __forceinline__ void operator()(const i32x4 (&acc)[2][2][4][2], const Unit& u, int wr, int wc, int fr, int fq) const {
;     ...
;             for (int m = 0; m < 4; ++m) { const int row = row0 + ai * HALF + m * 16; const bf16_t* yp = X + (size_t)row * 4096 + col0; y[m][0] = *(const u32x4*)yp; y[m][1] = *(const u32x4*)(yp + HALF);
;                 mean[m] = stats[2 * row]; rstd[m] = stats[2 * row + 1]; f[m] = rowinv[row] * wdq; }
; #pragma unroll
;             for (int m = 0; m < 4; ++m) { bf16_t* rowp = X + (size_t)(row0 + ai * HALF + m * 16) * 4096 + col0;
; #pragma unroll
;                 for (int bj = 0; bj < 2; ++bj) { const int c = col0 + bj * HALF; const float ra = rstd[m] * alpha;
;                     const f32x4 g0 = *(const f32x4*)(g + c) * ra, g1 = *(const f32x4*)(g + c + 4) * ra, b0 = *(const f32x4*)(b + c) * alpha, b1 = *(const f32x4*)(b + c + 4) * alpha;
;                     const i32x4 a0 = acc[ai][bj][m][0], a1 = acc[ai][bj][m][1];
;                     f32x4 q0, q1; q0.x = (float)a0.x; q0.y = (float)a0.y; q0.z = (float)a0.z; q0.w = (float)a0.w; q1.x = (float)a1.x; q1.y = (float)a1.y; q1.z = (float)a1.z; q1.w = (float)a1.w;
;                     *(u32x4*)(rowp + bj * HALF) = pk8h((h4lo(y[m][bj]) - mean[m]) * g0 + b0 + q0 * f[m], (h4hi(y[m][bj]) - mean[m]) * g1 + b1 + q1 * f[m]); } }
	v_pk_mul_f32 v[80:81], v[128:129], v[80:81] op_sel_hi:[0,1]
	v_pk_mul_f32 v[78:79], v[128:129], v[78:79] op_sel_hi:[0,1]
	s_waitcnt vmcnt(11)
	v_pk_mul_f32 v[76:77], v[128:129], v[76:77] op_sel_hi:[0,1]
	v_pk_mul_f32 v[74:75], v[128:129], v[74:75] op_sel_hi:[0,1]
	v_sub_f32_e32 v82, v82, v100
	v_sub_f32_e32 v83, v125, v100
	v_sub_f32_e32 v84, v107, v100
	v_sub_f32_e32 v85, v101, v100
	v_sub_f32_e32 v148, v148, v100
	v_sub_f32_e32 v149, v149, v100
	v_sub_f32_e32 v152, v129, v100
	v_sub_f32_e32 v153, v127, v100
	v_pk_fma_f32 v[70:71], v[84:85], v[78:79], v[70:71]
	v_pk_fma_f32 v[72:73], v[82:83], v[80:81], v[72:73]
	v_pk_fma_f32 v[66:67], v[152:153], v[74:75], v[66:67]
	v_pk_fma_f32 v[68:69], v[148:149], v[76:77], v[68:69]
	v_pk_fma_f32 v[72:73], v[126:127], v[118:119], v[72:73] op_sel_hi:[0,1,1]
	v_pk_fma_f32 v[70:71], v[126:127], v[114:115], v[70:71] op_sel_hi:[0,1,1]
	v_pk_fma_f32 v[74:75], v[126:127], v[120:121], v[68:69] op_sel_hi:[0,1,1]
	v_pk_fma_f32 v[68:69], v[126:127], v[116:117], v[66:67] op_sel_hi:[0,1,1]
	v_cvt_pk_f16_f32 v66, v70, v71
	v_cvt_pk_f16_f32 v67, v72, v73
	v_cvt_pk_f16_f32 v68, v68, v69
	v_cvt_pk_f16_f32 v69, v74, v75
	global_store_dwordx4 v[112:113], v[66:69], off nt
	global_load_dwordx4 v[66:69], v[142:143], off offset:512
	s_nop 0
	global_load_dwordx4 v[70:73], v[142:143], off offset:528
	global_load_dwordx4 v[74:77], v[140:141], off offset:512
	global_load_dwordx4 v[78:81], v[140:141], off offset:528
	s_waitcnt vmcnt(15)
	v_cvt_f32_f16_sdwa v85, v86 dst_sel:DWORD dst_unused:UNUSED_PAD src0_sel:WORD_1
	v_cvt_f32_f16_e32 v84, v86
	v_cvt_f32_f16_sdwa v83, v87 dst_sel:DWORD dst_unused:UNUSED_PAD src0_sel:WORD_1
	v_cvt_f32_f16_e32 v82, v87
	v_cvt_f32_f16_sdwa v101, v88 dst_sel:DWORD dst_unused:UNUSED_PAD src0_sel:WORD_1
	v_cvt_f32_f16_e32 v88, v88
	v_cvt_f32_f16_sdwa v87, v89 dst_sel:DWORD dst_unused:UNUSED_PAD src0_sel:WORD_1
	v_cvt_f32_f16_e32 v86, v89
	v_sub_f32_e32 v82, v82, v100
	v_sub_f32_e32 v83, v83, v100
	v_sub_f32_e32 v84, v84, v100
	v_sub_f32_e32 v85, v85, v100
	v_sub_f32_e32 v86, v86, v100
	v_sub_f32_e32 v87, v87, v100
	v_sub_f32_e32 v88, v88, v100
	v_sub_f32_e32 v89, v101, v100
	v_ashrrev_i32_e32 v107, 31, v106
	s_waitcnt vmcnt(3)
	v_pk_mul_f32 v[68:69], v[128:129], v[68:69] op_sel_hi:[0,1]
	v_pk_mul_f32 v[66:67], v[128:129], v[66:67] op_sel_hi:[0,1]
	s_waitcnt vmcnt(2)
	v_pk_mul_f32 v[72:73], v[128:129], v[72:73] op_sel_hi:[0,1]
	v_pk_mul_f32 v[70:71], v[128:129], v[70:71] op_sel_hi:[0,1]
	s_waitcnt vmcnt(1)
	v_pk_mul_f32 v[76:77], v[76:77], s[90:91] op_sel_hi:[1,0]
	v_pk_mul_f32 v[74:75], v[74:75], s[90:91] op_sel_hi:[1,0]
	s_waitcnt vmcnt(0)
	v_pk_mul_f32 v[80:81], v[80:81], s[90:91] op_sel_hi:[1,0]
	v_pk_mul_f32 v[78:79], v[78:79], s[90:91] op_sel_hi:[1,0]
	v_pk_fma_f32 v[66:67], v[84:85], v[66:67], v[74:75]
	v_pk_fma_f32 v[68:69], v[82:83], v[68:69], v[76:77]
	v_pk_fma_f32 v[70:71], v[88:89], v[70:71], v[78:79]
	v_pk_fma_f32 v[72:73], v[86:87], v[72:73], v[80:81]
	v_pk_fma_f32 v[56:57], v[126:127], v[56:57], v[68:69] op_sel_hi:[0,1,1]
	v_pk_fma_f32 v[54:55], v[126:127], v[54:55], v[66:67] op_sel_hi:[0,1,1]
	v_pk_fma_f32 v[66:67], v[126:127], v[52:53], v[72:73] op_sel_hi:[0,1,1]
	v_pk_fma_f32 v[52:53], v[126:127], v[50:51], v[70:71] op_sel_hi:[0,1,1]
	v_cvt_pk_f16_f32 v50, v54, v55
	v_cvt_pk_f16_f32 v51, v56, v57
	v_cvt_pk_f16_f32 v52, v52, v53
	v_cvt_pk_f16_f32 v53, v66, v67
	global_store_dwordx4 v[112:113], v[50:53], off offset:256 nt
	global_load_dwordx4 v[50:53], v[142:143], off
	s_nop 0
	global_load_dwordx4 v[54:57], v[142:143], off offset:16
	global_load_dwordx4 v[66:69], v[140:141], off
	global_load_dwordx4 v[70:73], v[140:141], off offset:16
	v_cvt_f32_f16_sdwa v77, v62 dst_sel:DWORD dst_unused:UNUSED_PAD src0_sel:WORD_1
	v_cvt_f32_f16_e32 v79, v62
	v_cvt_f32_f16_sdwa v80, v63 dst_sel:DWORD dst_unused:UNUSED_PAD src0_sel:WORD_1
	v_cvt_f32_f16_e32 v62, v63
	v_cvt_f32_f16_sdwa v83, v64 dst_sel:DWORD dst_unused:UNUSED_PAD src0_sel:WORD_1
	v_cvt_f32_f16_e32 v82, v64
	v_cvt_f32_f16_sdwa v81, v65 dst_sel:DWORD dst_unused:UNUSED_PAD src0_sel:WORD_1
	v_cvt_f32_f16_e32 v84, v65
	v_mul_f32_e32 v78, 0x3fb504f3, v109
	v_sub_f32_e32 v62, v62, v108
	v_sub_f32_e32 v63, v80, v108
	v_sub_f32_e32 v64, v79, v108
	v_sub_f32_e32 v65, v77, v108
	v_sub_f32_e32 v80, v84, v108
	v_sub_f32_e32 v81, v81, v108
	v_sub_f32_e32 v82, v82, v108
	v_sub_f32_e32 v83, v83, v108
	v_mul_f32_e32 v76, v151, v124
	v_lshl_add_u64 v[74:75], s[10:11], 0, v[110:111]
	v_lshl_add_u64 v[74:75], v[74:75], 0, v[144:145]
	s_waitcnt vmcnt(3)
	v_pk_mul_f32 v[52:53], v[78:79], v[52:53] op_sel_hi:[0,1]
	v_pk_mul_f32 v[50:51], v[78:79], v[50:51] op_sel_hi:[0,1]
	s_waitcnt vmcnt(2)
	v_pk_mul_f32 v[56:57], v[78:79], v[56:57] op_sel_hi:[0,1]
	v_pk_mul_f32 v[54:55], v[78:79], v[54:55] op_sel_hi:[0,1]
	s_waitcnt vmcnt(1)
	v_pk_mul_f32 v[68:69], v[68:69], s[90:91] op_sel_hi:[1,0]
	v_pk_mul_f32 v[66:67], v[66:67], s[90:91] op_sel_hi:[1,0]
	s_waitcnt vmcnt(0)
; __device__ __forceinline__ u32x4 pk8h(const f32x4 a, const f32x4 b) { u32x4 w; w.x = pkh(a[0], a[1]); w.y = pkh(a[2], a[3]); w.z = pkh(b[0], b[1]); w.w = pkh(b[2], b[3]); return w; }
; __device__ __forceinline__ f32x4 h4lo(const u32x4 w) { return (f32x4){hlo(w.x), hhi(w.x), hlo(w.y), hhi(w.y)}; }
; __device__ __forceinline__ f32x4 h4hi(const u32x4 w) { return (f32x4){hlo(w.z), hhi(w.z), hlo(w.w), hhi(w.w)}; }
;     __device__ __forceinline__ void operator()(const i32x4 (&acc)[2][2][4][2], const Unit& u, int wr, int wc, int fr, int fq) const {
;     ...
;             for (int m = 0; m < 4; ++m) { const int row = row0 + ai * HALF + m * 16; const bf16_t* yp = X + (size_t)row * 4096 + col0; y[m][0] = *(const u32x4*)yp; y[m][1] = *(const u32x4*)(yp + HALF);
;                 mean[m] = stats[2 * row]; rstd[m] = stats[2 * row + 1]; f[m] = rowinv[row] * wdq; }
; #pragma unroll
;             for (int m = 0; m < 4; ++m) { bf16_t* rowp = X + (size_t)(row0 + ai * HALF + m * 16) * 4096 + col0;
; #pragma unroll
;                 for (int bj = 0; bj < 2; ++bj) { const int c = col0 + bj * HALF; const float ra = rstd[m] * alpha;
;                     const f32x4 g0 = *(const f32x4*)(g + c) * ra, g1 = *(const f32x4*)(g + c + 4) * ra, b0 = *(const f32x4*)(b + c) * alpha, b1 = *(const f32x4*)(b + c + 4) * alpha;
;                     const i32x4 a0 = acc[ai][bj][m][0], a1 = acc[ai][bj][m][1];
;                     f32x4 q0, q1; q0.x = (float)a0.x; q0.y = (float)a0.y; q0.z = (float)a0.z; q0.w = (float)a0.w; q1.x = (float)a1.x; q1.y = (float)a1.y; q1.z = (float)a1.z; q1.w = (float)a1.w;
;                     *(u32x4*)(rowp + bj * HALF) = pk8h((h4lo(y[m][bj]) - mean[m]) * g0 + b0 + q0 * f[m], (h4hi(y[m][bj]) - mean[m]) * g1 + b1 + q1 * f[m]); } }
	v_pk_mul_f32 v[72:73], v[72:73], s[90:91] op_sel_hi:[1,0]
	v_pk_mul_f32 v[70:71], v[70:71], s[90:91] op_sel_hi:[1,0]
	v_pk_fma_f32 v[50:51], v[64:65], v[50:51], v[66:67]
	v_pk_fma_f32 v[52:53], v[62:63], v[52:53], v[68:69]
	v_pk_fma_f32 v[54:55], v[82:83], v[54:55], v[70:71]
	v_pk_fma_f32 v[56:57], v[80:81], v[56:57], v[72:73]
	v_pk_fma_f32 v[48:49], v[76:77], v[48:49], v[52:53] op_sel_hi:[0,1,1]
	v_pk_fma_f32 v[46:47], v[76:77], v[46:47], v[50:51] op_sel_hi:[0,1,1]
	v_pk_fma_f32 v[50:51], v[76:77], v[44:45], v[56:57] op_sel_hi:[0,1,1]
	v_pk_fma_f32 v[44:45], v[76:77], v[42:43], v[54:55] op_sel_hi:[0,1,1]
	v_cvt_pk_f16_f32 v42, v46, v47
	v_cvt_pk_f16_f32 v43, v48, v49
	v_cvt_pk_f16_f32 v44, v44, v45
	v_cvt_pk_f16_f32 v45, v50, v51
	global_store_dwordx4 v[74:75], v[42:45], off nt
	global_load_dwordx4 v[42:45], v[142:143], off offset:512
	s_nop 0
	global_load_dwordx4 v[46:49], v[142:143], off offset:528
	global_load_dwordx4 v[50:53], v[140:141], off offset:512
	global_load_dwordx4 v[54:57], v[140:141], off offset:528
	v_cvt_f32_f16_sdwa v73, v90 dst_sel:DWORD dst_unused:UNUSED_PAD src0_sel:WORD_1
	v_cvt_f32_f16_e32 v72, v90
	v_cvt_f32_f16_sdwa v71, v91 dst_sel:DWORD dst_unused:UNUSED_PAD src0_sel:WORD_1
	v_cvt_f32_f16_e32 v70, v91
	v_cvt_f32_f16_sdwa v77, v92 dst_sel:DWORD dst_unused:UNUSED_PAD src0_sel:WORD_1
	v_cvt_f32_f16_e32 v79, v92
	v_cvt_f32_f16_sdwa v81, v93 dst_sel:DWORD dst_unused:UNUSED_PAD src0_sel:WORD_1
	v_cvt_f32_f16_e32 v80, v93
	v_cvt_f32_i32_e32 v63, v35
	v_cvt_f32_i32_e32 v62, v34
	v_cvt_f32_i32_e32 v65, v37
	v_cvt_f32_i32_e32 v64, v36
	v_lshlrev_b64 v[66:67], 13, v[106:107]
	v_lshl_add_u64 v[68:69], v[146:147], 0, v[66:67]
	v_sub_f32_e32 v70, v70, v108
	v_sub_f32_e32 v71, v71, v108
	v_sub_f32_e32 v72, v72, v108
	v_sub_f32_e32 v73, v73, v108
	v_sub_f32_e32 v80, v80, v108
	v_sub_f32_e32 v81, v81, v108
	v_sub_f32_e32 v82, v79, v108
	v_sub_f32_e32 v83, v77, v108
	global_load_dwordx4 v[34:37], v[68:69], off
	s_waitcnt vmcnt(4)
	v_pk_mul_f32 v[44:45], v[78:79], v[44:45] op_sel_hi:[0,1]
	v_pk_mul_f32 v[42:43], v[78:79], v[42:43] op_sel_hi:[0,1]
	s_waitcnt vmcnt(3)
	v_pk_mul_f32 v[48:49], v[78:79], v[48:49] op_sel_hi:[0,1]
	v_pk_mul_f32 v[46:47], v[78:79], v[46:47] op_sel_hi:[0,1]
	s_waitcnt vmcnt(2)
	v_pk_mul_f32 v[52:53], v[52:53], s[90:91] op_sel_hi:[1,0]
	v_pk_mul_f32 v[50:51], v[50:51], s[90:91] op_sel_hi:[1,0]
	s_waitcnt vmcnt(1)
	v_pk_mul_f32 v[56:57], v[56:57], s[90:91] op_sel_hi:[1,0]
	v_pk_mul_f32 v[54:55], v[54:55], s[90:91] op_sel_hi:[1,0]
	v_pk_fma_f32 v[42:43], v[72:73], v[42:43], v[50:51]
	v_pk_fma_f32 v[44:45], v[70:71], v[44:45], v[52:53]
	v_pk_fma_f32 v[46:47], v[82:83], v[46:47], v[54:55]
	v_pk_fma_f32 v[48:49], v[80:81], v[48:49], v[56:57]
	v_pk_fma_f32 v[40:41], v[76:77], v[40:41], v[44:45] op_sel_hi:[0,1,1]
	v_pk_fma_f32 v[38:39], v[76:77], v[38:39], v[42:43] op_sel_hi:[0,1,1]
	v_pk_fma_f32 v[42:43], v[76:77], v[64:65], v[48:49] op_sel_hi:[0,1,1]
	v_pk_fma_f32 v[44:45], v[76:77], v[62:63], v[46:47] op_sel_hi:[0,1,1]
	v_cvt_pk_f16_f32 v38, v38, v39
	v_cvt_pk_f16_f32 v39, v40, v41
	v_cvt_pk_f16_f32 v40, v44, v45
	v_cvt_pk_f16_f32 v41, v42, v43
	global_store_dwordx4 v[74:75], v[38:41], off offset:256 nt
	global_load_dwordx4 v[38:41], v[142:143], off
	s_nop 0
	global_load_dwordx4 v[42:45], v[142:143], off offset:16
	global_load_dwordx4 v[46:49], v[140:141], off
	global_load_dwordx4 v[50:53], v[140:141], off offset:16
	v_cvt_f32_i32_e32 v55, v27
	v_cvt_f32_i32_e32 v54, v26
	v_lshl_add_u64 v[26:27], s[10:11], 0, v[66:67]
	v_cvt_f32_i32_e32 v57, v29
	v_cvt_f32_i32_e32 v56, v28
	v_lshl_add_u64 v[62:63], v[26:27], 0, v[144:145]
	global_load_dwordx4 v[26:29], v[68:69], off offset:256
	s_waitcnt vmcnt(6)
	v_cvt_f32_f16_sdwa v65, v34 dst_sel:DWORD dst_unused:UNUSED_PAD src0_sel:WORD_1
	v_cvt_f32_f16_e32 v67, v34
	v_cvt_f32_f16_sdwa v68, v35 dst_sel:DWORD dst_unused:UNUSED_PAD src0_sel:WORD_1
	v_cvt_f32_f16_e32 v34, v35
	v_cvt_f32_f16_sdwa v71, v36 dst_sel:DWORD dst_unused:UNUSED_PAD src0_sel:WORD_1
	v_cvt_f32_f16_e32 v70, v36
	v_cvt_f32_f16_sdwa v69, v37 dst_sel:DWORD dst_unused:UNUSED_PAD src0_sel:WORD_1
	v_cvt_f32_f16_e32 v72, v37
	v_mul_f32_e32 v66, 0x3fb504f3, v103
	v_sub_f32_e32 v34, v34, v102
	v_sub_f32_e32 v35, v68, v102
	v_sub_f32_e32 v36, v67, v102
	v_sub_f32_e32 v37, v65, v102
	v_sub_f32_e32 v68, v72, v102
	v_sub_f32_e32 v69, v69, v102
	v_sub_f32_e32 v70, v70, v102
	v_sub_f32_e32 v71, v71, v102
	v_mul_f32_e32 v64, v151, v123
	s_waitcnt vmcnt(4)
	v_pk_mul_f32 v[40:41], v[66:67], v[40:41] op_sel_hi:[0,1]
	v_pk_mul_f32 v[38:39], v[66:67], v[38:39] op_sel_hi:[0,1]
	s_waitcnt vmcnt(3)
	v_pk_mul_f32 v[44:45], v[66:67], v[44:45] op_sel_hi:[0,1]
	v_pk_mul_f32 v[42:43], v[66:67], v[42:43] op_sel_hi:[0,1]
	s_waitcnt vmcnt(2)
	v_pk_mul_f32 v[48:49], v[48:49], s[90:91] op_sel_hi:[1,0]
	v_pk_mul_f32 v[46:47], v[46:47], s[90:91] op_sel_hi:[1,0]
	s_waitcnt vmcnt(1)
	v_pk_mul_f32 v[52:53], v[52:53], s[90:91] op_sel_hi:[1,0]
	v_pk_mul_f32 v[50:51], v[50:51], s[90:91] op_sel_hi:[1,0]
	v_pk_fma_f32 v[36:37], v[36:37], v[38:39], v[46:47]
	v_pk_fma_f32 v[34:35], v[34:35], v[40:41], v[48:49]
	v_pk_fma_f32 v[38:39], v[70:71], v[42:43], v[50:51]
	v_pk_fma_f32 v[40:41], v[68:69], v[44:45], v[52:53]
	v_pk_fma_f32 v[32:33], v[64:65], v[32:33], v[34:35] op_sel_hi:[0,1,1]
	v_pk_fma_f32 v[30:31], v[64:65], v[30:31], v[36:37] op_sel_hi:[0,1,1]
	v_pk_fma_f32 v[34:35], v[64:65], v[56:57], v[40:41] op_sel_hi:[0,1,1]
	v_pk_fma_f32 v[36:37], v[64:65], v[54:55], v[38:39] op_sel_hi:[0,1,1]
	v_cvt_pk_f16_f32 v30, v30, v31
	v_cvt_pk_f16_f32 v31, v32, v33
	v_cvt_pk_f16_f32 v32, v36, v37
	v_cvt_pk_f16_f32 v33, v34, v35
	global_store_dwordx4 v[62:63], v[30:33], off nt
	global_load_dwordx4 v[30:33], v[142:143], off offset:512
	s_nop 0
	global_load_dwordx4 v[34:37], v[142:143], off offset:528
	global_load_dwordx4 v[38:41], v[140:141], off offset:512
	global_load_dwordx4 v[42:45], v[140:141], off offset:528
	s_waitcnt vmcnt(5)
; __device__ __forceinline__ u32x4 pk8h(const f32x4 a, const f32x4 b) { u32x4 w; w.x = pkh(a[0], a[1]); w.y = pkh(a[2], a[3]); w.z = pkh(b[0], b[1]); w.w = pkh(b[2], b[3]); return w; }
; __device__ __forceinline__ f32x4 h4lo(const u32x4 w) { return (f32x4){hlo(w.x), hhi(w.x), hlo(w.y), hhi(w.y)}; }
; __device__ __forceinline__ f32x4 h4hi(const u32x4 w) { return (f32x4){hlo(w.z), hhi(w.z), hlo(w.w), hhi(w.w)}; }
;     __device__ __forceinline__ void operator()(const i32x4 (&acc)[2][2][4][2], const Unit& u, int wr, int wc, int fr, int fq) const {
;     ...
;             for (int m = 0; m < 4; ++m) { const int row = row0 + ai * HALF + m * 16; const bf16_t* yp = X + (size_t)row * 4096 + col0; y[m][0] = *(const u32x4*)yp; y[m][1] = *(const u32x4*)(yp + HALF);
;                 mean[m] = stats[2 * row]; rstd[m] = stats[2 * row + 1]; f[m] = rowinv[row] * wdq; }
; #pragma unroll
;             for (int m = 0; m < 4; ++m) { bf16_t* rowp = X + (size_t)(row0 + ai * HALF + m * 16) * 4096 + col0;
; #pragma unroll
;                 for (int bj = 0; bj < 2; ++bj) { const int c = col0 + bj * HALF; const float ra = rstd[m] * alpha;
;                     const f32x4 g0 = *(const f32x4*)(g + c) * ra, g1 = *(const f32x4*)(g + c + 4) * ra, b0 = *(const f32x4*)(b + c) * alpha, b1 = *(const f32x4*)(b + c + 4) * alpha;
;                     const i32x4 a0 = acc[ai][bj][m][0], a1 = acc[ai][bj][m][1];
;                     f32x4 q0, q1; q0.x = (float)a0.x; q0.y = (float)a0.y; q0.z = (float)a0.z; q0.w = (float)a0.w; q1.x = (float)a1.x; q1.y = (float)a1.y; q1.z = (float)a1.z; q1.w = (float)a1.w;
;                     *(u32x4*)(rowp + bj * HALF) = pk8h((h4lo(y[m][bj]) - mean[m]) * g0 + b0 + q0 * f[m], (h4hi(y[m][bj]) - mean[m]) * g1 + b1 + q1 * f[m]); } }
;             asm volatile("" ::: "memory");
;         }
	v_cvt_f32_f16_sdwa v46, v26 dst_sel:DWORD dst_unused:UNUSED_PAD src0_sel:WORD_1
	v_cvt_f32_f16_e32 v47, v26
	v_cvt_f32_f16_sdwa v48, v27 dst_sel:DWORD dst_unused:UNUSED_PAD src0_sel:WORD_1
	v_cvt_f32_f16_e32 v26, v27
	v_cvt_f32_f16_sdwa v49, v28 dst_sel:DWORD dst_unused:UNUSED_PAD src0_sel:WORD_1
	v_cvt_f32_f16_e32 v50, v28
	v_cvt_f32_f16_sdwa v51, v29 dst_sel:DWORD dst_unused:UNUSED_PAD src0_sel:WORD_1
	v_cvt_f32_f16_e32 v52, v29
	v_sub_f32_e32 v26, v26, v102
	v_sub_f32_e32 v27, v48, v102
	v_sub_f32_e32 v28, v47, v102
	v_sub_f32_e32 v29, v46, v102
	v_sub_f32_e32 v46, v52, v102
	v_sub_f32_e32 v47, v51, v102
	v_sub_f32_e32 v48, v50, v102
	v_sub_f32_e32 v49, v49, v102
	s_waitcnt vmcnt(3)
	v_pk_mul_f32 v[32:33], v[66:67], v[32:33] op_sel_hi:[0,1]
	v_pk_mul_f32 v[30:31], v[66:67], v[30:31] op_sel_hi:[0,1]
	s_waitcnt vmcnt(2)
	v_pk_mul_f32 v[36:37], v[66:67], v[36:37] op_sel_hi:[0,1]
	v_pk_mul_f32 v[34:35], v[66:67], v[34:35] op_sel_hi:[0,1]
	s_waitcnt vmcnt(1)
	v_pk_mul_f32 v[40:41], v[40:41], s[90:91] op_sel_hi:[1,0]
	v_pk_mul_f32 v[38:39], v[38:39], s[90:91] op_sel_hi:[1,0]
	s_waitcnt vmcnt(0)
	v_pk_mul_f32 v[44:45], v[44:45], s[90:91] op_sel_hi:[1,0]
	v_pk_mul_f32 v[42:43], v[42:43], s[90:91] op_sel_hi:[1,0]
	v_pk_fma_f32 v[28:29], v[28:29], v[30:31], v[38:39]
	v_pk_fma_f32 v[26:27], v[26:27], v[32:33], v[40:41]
	v_pk_fma_f32 v[30:31], v[48:49], v[34:35], v[42:43]
	v_pk_fma_f32 v[32:33], v[46:47], v[36:37], v[44:45]
	v_pk_fma_f32 v[24:25], v[64:65], v[24:25], v[26:27] op_sel_hi:[0,1,1]
	v_pk_fma_f32 v[22:23], v[64:65], v[22:23], v[28:29] op_sel_hi:[0,1,1]
	v_pk_fma_f32 v[26:27], v[64:65], v[20:21], v[32:33] op_sel_hi:[0,1,1]
	v_pk_fma_f32 v[20:21], v[64:65], v[18:19], v[30:31] op_sel_hi:[0,1,1]
	v_cvt_pk_f16_f32 v18, v22, v23
	v_cvt_pk_f16_f32 v19, v24, v25
	v_cvt_pk_f16_f32 v20, v20, v21
	v_cvt_pk_f16_f32 v21, v26, v27
	global_store_dwordx4 v[62:63], v[18:21], off offset:256 nt
	global_load_dwordx4 v[18:21], v[142:143], off
	s_nop 0
	global_load_dwordx4 v[22:25], v[142:143], off offset:16
	global_load_dwordx4 v[26:29], v[140:141], off
	global_load_dwordx4 v[30:33], v[140:141], off offset:16
	v_cvt_f32_f16_sdwa v37, v58 dst_sel:DWORD dst_unused:UNUSED_PAD src0_sel:WORD_1
	v_cvt_f32_f16_e32 v39, v58
	v_cvt_f32_f16_sdwa v41, v59 dst_sel:DWORD dst_unused:UNUSED_PAD src0_sel:WORD_1
	v_cvt_f32_f16_e32 v40, v59
	v_cvt_f32_f16_sdwa v47, v60 dst_sel:DWORD dst_unused:UNUSED_PAD src0_sel:WORD_1
	v_cvt_f32_f16_e32 v46, v60
	v_cvt_f32_f16_sdwa v45, v61 dst_sel:DWORD dst_unused:UNUSED_PAD src0_sel:WORD_1
	v_cvt_f32_f16_e32 v44, v61
	v_mul_f32_e32 v38, 0x3fb504f3, v105
	v_sub_f32_e32 v40, v40, v104
	v_sub_f32_e32 v41, v41, v104
	v_sub_f32_e32 v42, v39, v104
	v_sub_f32_e32 v43, v37, v104
	v_sub_f32_e32 v44, v44, v104
	v_sub_f32_e32 v45, v45, v104
	v_sub_f32_e32 v46, v46, v104
	v_sub_f32_e32 v47, v47, v104
	v_mul_f32_e32 v36, v151, v122
	v_lshl_add_u64 v[34:35], s[10:11], 0, v[98:99]
	v_lshl_add_u64 v[34:35], v[34:35], 0, v[144:145]
	s_waitcnt vmcnt(3)
	v_pk_mul_f32 v[20:21], v[38:39], v[20:21] op_sel_hi:[0,1]
	v_pk_mul_f32 v[18:19], v[38:39], v[18:19] op_sel_hi:[0,1]
	s_waitcnt vmcnt(2)
	v_pk_mul_f32 v[24:25], v[38:39], v[24:25] op_sel_hi:[0,1]
	v_pk_mul_f32 v[22:23], v[38:39], v[22:23] op_sel_hi:[0,1]
	s_waitcnt vmcnt(1)
	v_pk_mul_f32 v[28:29], v[28:29], s[90:91] op_sel_hi:[1,0]
	v_pk_mul_f32 v[26:27], v[26:27], s[90:91] op_sel_hi:[1,0]
	s_waitcnt vmcnt(0)
	v_pk_mul_f32 v[32:33], v[32:33], s[90:91] op_sel_hi:[1,0]
	v_pk_mul_f32 v[30:31], v[30:31], s[90:91] op_sel_hi:[1,0]
	v_pk_fma_f32 v[18:19], v[42:43], v[18:19], v[26:27]
	v_pk_fma_f32 v[20:21], v[40:41], v[20:21], v[28:29]
	v_pk_fma_f32 v[22:23], v[46:47], v[22:23], v[30:31]
	v_pk_fma_f32 v[24:25], v[44:45], v[24:25], v[32:33]
	v_pk_fma_f32 v[16:17], v[36:37], v[16:17], v[20:21] op_sel_hi:[0,1,1]
	v_pk_fma_f32 v[14:15], v[36:37], v[14:15], v[18:19] op_sel_hi:[0,1,1]
	v_pk_fma_f32 v[18:19], v[36:37], v[12:13], v[24:25] op_sel_hi:[0,1,1]
	v_pk_fma_f32 v[12:13], v[36:37], v[10:11], v[22:23] op_sel_hi:[0,1,1]
	v_cvt_pk_f16_f32 v10, v14, v15
	v_cvt_pk_f16_f32 v11, v16, v17
	v_cvt_pk_f16_f32 v12, v12, v13
	v_cvt_pk_f16_f32 v13, v18, v19
	global_store_dwordx4 v[34:35], v[10:13], off nt
	global_load_dwordx4 v[10:13], v[142:143], off offset:512
	s_nop 0
	global_load_dwordx4 v[14:17], v[142:143], off offset:528
	global_load_dwordx4 v[18:21], v[140:141], off offset:512
	global_load_dwordx4 v[22:25], v[140:141], off offset:528
	v_cvt_f32_f16_sdwa v29, v94 dst_sel:DWORD dst_unused:UNUSED_PAD src0_sel:WORD_1
	v_cvt_f32_f16_e32 v28, v94
	v_cvt_f32_f16_sdwa v27, v95 dst_sel:DWORD dst_unused:UNUSED_PAD src0_sel:WORD_1
	v_cvt_f32_f16_e32 v26, v95
	v_cvt_f32_f16_sdwa v33, v96 dst_sel:DWORD dst_unused:UNUSED_PAD src0_sel:WORD_1
	v_cvt_f32_f16_e32 v32, v96
	v_cvt_f32_f16_sdwa v31, v97 dst_sel:DWORD dst_unused:UNUSED_PAD src0_sel:WORD_1
	v_cvt_f32_f16_e32 v30, v97
	v_sub_f32_e32 v26, v26, v104
	v_sub_f32_e32 v27, v27, v104
	v_sub_f32_e32 v28, v28, v104
	v_sub_f32_e32 v29, v29, v104
	v_sub_f32_e32 v30, v30, v104
	v_sub_f32_e32 v31, v31, v104
	v_sub_f32_e32 v32, v32, v104
	v_sub_f32_e32 v33, v33, v104
	s_waitcnt vmcnt(3)
	v_pk_mul_f32 v[12:13], v[38:39], v[12:13] op_sel_hi:[0,1]
	v_pk_mul_f32 v[10:11], v[38:39], v[10:11] op_sel_hi:[0,1]
	s_waitcnt vmcnt(2)
	v_pk_mul_f32 v[16:17], v[38:39], v[16:17] op_sel_hi:[0,1]
	v_pk_mul_f32 v[14:15], v[38:39], v[14:15] op_sel_hi:[0,1]
	s_waitcnt vmcnt(1)
	v_pk_mul_f32 v[20:21], v[20:21], s[90:91] op_sel_hi:[1,0]
	v_pk_mul_f32 v[18:19], v[18:19], s[90:91] op_sel_hi:[1,0]
	s_waitcnt vmcnt(0)
	v_pk_mul_f32 v[24:25], v[24:25], s[90:91] op_sel_hi:[1,0]
	v_pk_mul_f32 v[22:23], v[22:23], s[90:91] op_sel_hi:[1,0]
	v_pk_fma_f32 v[10:11], v[28:29], v[10:11], v[18:19]
	v_pk_fma_f32 v[12:13], v[26:27], v[12:13], v[20:21]
	v_pk_fma_f32 v[14:15], v[32:33], v[14:15], v[22:23]
	v_pk_fma_f32 v[16:17], v[30:31], v[16:17], v[24:25]
	v_pk_fma_f32 v[8:9], v[36:37], v[8:9], v[12:13] op_sel_hi:[0,1,1]
	v_pk_fma_f32 v[6:7], v[36:37], v[6:7], v[10:11] op_sel_hi:[0,1,1]
	v_pk_fma_f32 v[10:11], v[36:37], v[4:5], v[16:17] op_sel_hi:[0,1,1]
	v_pk_fma_f32 v[4:5], v[36:37], v[2:3], v[14:15] op_sel_hi:[0,1,1]
	v_cvt_pk_f16_f32 v2, v6, v7
	v_cvt_pk_f16_f32 v3, v8, v9
	v_cvt_pk_f16_f32 v4, v4, v5
	v_cvt_pk_f16_f32 v5, v10, v11
	global_store_dwordx4 v[34:35], v[2:5], off offset:256 nt
	s_cbranch_vccnz .LBB0_1192
	s_andn2_b64 vcc, exec, s[8:9]
	s_cbranch_vccnz .LBB0_1191
	s_barrier
	s_branch .LBB0_1191
